# conv-pointwise and fnet projections fused into the group-norm unit (GPW/GFW GEMM tiles removed); S5 pass 2: chunk states requested ahead of the parameter loads, carry recurrence from registers
# speedup vs baseline: 1.5253x; 1.0090x over previous
.LBB0_152:
	s_andn2_b64 vcc, exec, s[6:7]
	s_movk_i32 s94, 0x1000
	s_cbranch_vccnz .LBB0_154
	s_movk_i32 s94, 0x608

.LBB0_383:
	s_bitcmp0_b32 s94, 9
	v_readlane_b32 s6, v247, 54
	s_cselect_b64 s[0:1], -1, 0
	v_readlane_b32 s7, v247, 55
	s_or_b64 s[0:1], s[6:7], s[0:1]
	v_readlane_b32 s82, v245, 32
	s_and_b64 vcc, exec, s[0:1]
	s_mov_b32 s25, 0x11f000
	s_mov_b32 s70, 0x8800
	s_mov_b32 s71, 0x78787879
	s_movk_i32 s72, 0x44
	s_mov_b32 s26, 0x15f000
	s_mov_b32 s27, 0x19f000
	s_mov_b32 s73, 0x3e000000
	s_mov_b32 s78, 0xff61b1e6
	s_mov_b32 s79, 0xdf00000
	v_readlane_b32 s83, v245, 33
	s_mov_b32 s60, 0x1df000
	s_cbranch_vccnz .LBB0_388
	v_readlane_b32 s0, v247, 56
	v_lshrrev_b32_e32 v156, 6, v143
	s_nop 0
	v_readfirstlane_b32 s1, v156
	s_lshr_b32 s0, s0, 6
	s_add_i32 s0, s0, s1
	s_mul_i32 s0, s0, 0x8800
	s_add_u32 s0, s0, 0x300000
	s_add_u32 s8, s4, s0
	s_addc_u32 s9, s5, 0
	v_lshlrev_b32_e32 v156, 3, v205
	global_load_dwordx2 v[18:19], v156, s[8:9] offset:0
	global_load_dwordx2 v[20:21], v156, s[8:9] offset:512
	global_load_dwordx2 v[22:23], v156, s[8:9] offset:1024
	global_load_dwordx2 v[24:25], v156, s[8:9] offset:1536
	global_load_dwordx2 v[26:27], v156, s[8:9] offset:2048
	global_load_dwordx2 v[28:29], v156, s[8:9] offset:2560
	global_load_dwordx2 v[30:31], v156, s[8:9] offset:3072
	global_load_dwordx2 v[32:33], v156, s[8:9] offset:3584
	s_add_u32 s8, s8, 0x1000
	s_addc_u32 s9, s9, 0
	global_load_dwordx2 v[34:35], v156, s[8:9] offset:0
	global_load_dwordx2 v[36:37], v156, s[8:9] offset:512
	global_load_dwordx2 v[38:39], v156, s[8:9] offset:1024
	global_load_dwordx2 v[40:41], v156, s[8:9] offset:1536
	global_load_dwordx2 v[42:43], v156, s[8:9] offset:2048
	global_load_dwordx2 v[44:45], v156, s[8:9] offset:2560
	global_load_dwordx2 v[46:47], v156, s[8:9] offset:3072
	global_load_dwordx2 v[48:49], v156, s[8:9] offset:3584
	s_add_u32 s8, s8, 0x1000
	s_addc_u32 s9, s9, 0
	global_load_dwordx2 v[50:51], v156, s[8:9] offset:0
	global_load_dwordx2 v[52:53], v156, s[8:9] offset:512
	global_load_dwordx2 v[54:55], v156, s[8:9] offset:1024
	global_load_dwordx2 v[56:57], v156, s[8:9] offset:1536
	global_load_dwordx2 v[58:59], v156, s[8:9] offset:2048
	global_load_dwordx2 v[60:61], v156, s[8:9] offset:2560
	global_load_dwordx2 v[62:63], v156, s[8:9] offset:3072
	global_load_dwordx2 v[64:65], v156, s[8:9] offset:3584
	s_add_u32 s8, s8, 0x1000
	s_addc_u32 s9, s9, 0
	global_load_dwordx2 v[66:67], v156, s[8:9] offset:0
	global_load_dwordx2 v[68:69], v156, s[8:9] offset:512
	global_load_dwordx2 v[70:71], v156, s[8:9] offset:1024
	global_load_dwordx2 v[72:73], v156, s[8:9] offset:1536
	global_load_dwordx2 v[74:75], v156, s[8:9] offset:2048
	global_load_dwordx2 v[76:77], v156, s[8:9] offset:2560
	global_load_dwordx2 v[78:79], v156, s[8:9] offset:3072
	global_load_dwordx2 v[80:81], v156, s[8:9] offset:3584
	s_add_u32 s8, s8, 0x1000
	s_addc_u32 s9, s9, 0
	global_load_dwordx2 v[82:83], v156, s[8:9] offset:0
	global_load_dwordx2 v[84:85], v156, s[8:9] offset:512
	global_load_dwordx2 v[86:87], v156, s[8:9] offset:1024
	global_load_dwordx2 v[88:89], v156, s[8:9] offset:1536
	global_load_dwordx2 v[90:91], v156, s[8:9] offset:2048
	global_load_dwordx2 v[92:93], v156, s[8:9] offset:2560
	global_load_dwordx2 v[94:95], v156, s[8:9] offset:3072
	global_load_dwordx2 v[96:97], v156, s[8:9] offset:3584
	s_add_u32 s8, s8, 0x1000
	s_addc_u32 s9, s9, 0
	global_load_dwordx2 v[98:99], v156, s[8:9] offset:0
	global_load_dwordx2 v[100:101], v156, s[8:9] offset:512
	global_load_dwordx2 v[102:103], v156, s[8:9] offset:1024
	global_load_dwordx2 v[104:105], v156, s[8:9] offset:1536
	global_load_dwordx2 v[106:107], v156, s[8:9] offset:2048
	global_load_dwordx2 v[108:109], v156, s[8:9] offset:2560
	global_load_dwordx2 v[110:111], v156, s[8:9] offset:3072
	global_load_dwordx2 v[112:113], v156, s[8:9] offset:3584
	s_add_u32 s8, s8, 0x1000
	s_addc_u32 s9, s9, 0
	global_load_dwordx2 v[114:115], v156, s[8:9] offset:0
	global_load_dwordx2 v[116:117], v156, s[8:9] offset:512
	global_load_dwordx2 v[118:119], v156, s[8:9] offset:1024
	global_load_dwordx2 v[120:121], v156, s[8:9] offset:1536
	global_load_dwordx2 v[122:123], v156, s[8:9] offset:2048
	global_load_dwordx2 v[124:125], v156, s[8:9] offset:2560
	global_load_dwordx2 v[126:127], v156, s[8:9] offset:3072
	global_load_dwordx2 v[128:129], v156, s[8:9] offset:3584
	s_add_u32 s8, s8, 0x1000
	s_addc_u32 s9, s9, 0
	global_load_dwordx2 v[130:131], v156, s[8:9] offset:0
	global_load_dwordx2 v[132:133], v156, s[8:9] offset:512
	global_load_dwordx2 v[134:135], v156, s[8:9] offset:1024
	global_load_dwordx2 v[138:139], v156, s[8:9] offset:1536
	v_readlane_b32 s0, v247, 56
	v_mov_b32_e32 v6, 0
	s_mov_b32 s6, 0
	v_add_u32_e32 v4, s0, v143
	v_lshrrev_b32_e32 v0, 6, v4
	v_readlane_b32 s0, v247, 28
	v_bfe_u32 v5, v4, 6, 4
	s_lshl_b32 s0, s0, 5
	v_and_b32_e32 v7, 16, v0
	v_or3_b32 v0, v7, s0, v5
	v_ashrrev_i32_e32 v1, 31, v0
	v_lshl_add_u64 v[2:3], v[0:1], 2, s[4:5]
	v_add_co_u32_e32 v2, vcc, 0x11f000, v2
	v_lshl_or_b32 v0, v0, 6, v205
	s_nop 0
	v_addc_co_u32_e32 v3, vcc, 0, v3, vcc
	global_load_dword v8, v[2:3], off offset:2592
	v_ashrrev_i32_e32 v1, 31, v0
	v_lshl_add_u64 v[0:1], v[0:1], 2, s[4:5]
	v_add_co_u32_e32 v2, vcc, 0x117000, v0
	s_nop 1
	v_addc_co_u32_e32 v3, vcc, 0, v1, vcc
	v_add_co_u32_e32 v0, vcc, 0x11b000, v0
	s_nop 1
	v_addc_co_u32_e32 v1, vcc, 0, v1, vcc
	global_load_dword v2, v[2:3], off offset:2592
	s_nop 0
	global_load_dword v3, v[0:1], off offset:2592
	v_ashrrev_i32_e32 v0, 11, v4
	v_lshlrev_b32_e32 v0, 5, v0
	v_or3_b32 v0, v0, v7, v5
	v_mov_b32_e32 v7, v6
	s_waitcnt vmcnt(0)
	v_mul_f32_e32 v1, 0x3fb8aa3b, v8
	v_exp_f32_e32 v4, v1
	v_mad_i64_i32 v[0:1], s[0:1], v0, s70, 0
	v_lshl_or_b32 v0, v205, 3, v0
	v_lshl_add_u64 v[0:1], s[4:5], 0, v[0:1]
	s_mov_b64 s[0:1], 0x740e00
	v_lshl_add_u64 v[0:1], v[0:1], 0, s[0:1]
	v_mul_f32_e32 v2, v2, v4
	v_mul_f32_e32 v3, v3, v4
	v_mul_f32_e32 v4, 0.15915494, v3
	v_rndne_f32_e32 v4, v4
	v_mul_f32_e32 v2, 0x3fb8aa3b, v2
	v_fma_f32 v3, v3, 0.15915494, -v4
	v_exp_f32_e32 v2, v2
	v_cos_f32_e32 v4, v3
	v_sin_f32_e32 v3, v3
	v_mul_f32_e32 v4, v2, v4
	v_mul_f32_e32 v2, v2, v3
	v_mul_f32_e32 v3, v2, v2
	v_mul_f32_e32 v2, v4, v2
	v_fma_f32 v3, v4, v4, -v3
	v_add_f32_e32 v2, v2, v2
	v_mul_f32_e32 v4, v2, v2
	v_mul_f32_e32 v2, v3, v2
	v_fma_f32 v3, v3, v3, -v4
	v_add_f32_e32 v2, v2, v2
	v_mul_f32_e32 v4, v2, v2
	v_mul_f32_e32 v2, v3, v2
	v_fma_f32 v3, v3, v3, -v4
	v_add_f32_e32 v2, v2, v2
	v_mul_f32_e32 v4, v2, v2
	v_mul_f32_e32 v2, v3, v2
	v_fma_f32 v3, v3, v3, -v4
	v_add_f32_e32 v2, v2, v2
	v_mul_f32_e32 v4, v2, v2
	v_mul_f32_e32 v2, v3, v2
	v_fma_f32 v3, v3, v3, -v4
	v_add_f32_e32 v2, v2, v2
	v_mul_f32_e32 v4, v2, v2
	v_mul_f32_e32 v5, v3, v2
	v_fma_f32 v2, v3, v3, -v4
	v_add_f32_e32 v4, v5, v5
	v_mov_b32_e32 v3, v2
	v_mov_b32_e32 v5, v4
	global_load_dwordx2 v[140:141], v156, s[8:9] offset:2048
	global_load_dwordx2 v[142:143], v156, s[8:9] offset:2560
	global_load_dwordx2 v[144:145], v156, s[8:9] offset:3072
	global_load_dwordx2 v[146:147], v156, s[8:9] offset:3584
	s_add_u32 s8, s8, 0x1000
	s_addc_u32 s9, s9, 0
	global_load_dwordx2 v[148:149], v156, s[8:9] offset:0
	global_load_dwordx2 v[150:151], v156, s[8:9] offset:512
	global_load_dwordx2 v[152:153], v156, s[8:9] offset:1024
	global_load_dwordx2 v[154:155], v156, s[8:9] offset:1536
	v_fma_f32 v159, v2, v6, v18
	v_fma_f32 v160, v2, v7, v19
	v_mov_b32_e32 v18, v6
	v_mov_b32_e32 v19, v7
	v_fma_f32 v157, -v4, v7, v159
	v_fma_f32 v158, v4, v6, v160
	v_fma_f32 v159, v2, v157, v20
	v_fma_f32 v160, v2, v158, v21
	v_mov_b32_e32 v20, v157
	v_mov_b32_e32 v21, v158
	v_fma_f32 v6, -v4, v158, v159
	v_fma_f32 v7, v4, v157, v160
	v_fma_f32 v159, v2, v6, v22
	v_fma_f32 v160, v2, v7, v23
	v_mov_b32_e32 v22, v6
	v_mov_b32_e32 v23, v7
	v_fma_f32 v157, -v4, v7, v159
	v_fma_f32 v158, v4, v6, v160
	v_fma_f32 v159, v2, v157, v24
	v_fma_f32 v160, v2, v158, v25
	v_mov_b32_e32 v24, v157
	v_mov_b32_e32 v25, v158
	v_fma_f32 v6, -v4, v158, v159
	v_fma_f32 v7, v4, v157, v160
	v_fma_f32 v159, v2, v6, v26
	v_fma_f32 v160, v2, v7, v27
	v_mov_b32_e32 v26, v6
	v_mov_b32_e32 v27, v7
	v_fma_f32 v157, -v4, v7, v159
	v_fma_f32 v158, v4, v6, v160
	v_fma_f32 v159, v2, v157, v28
	v_fma_f32 v160, v2, v158, v29
	v_mov_b32_e32 v28, v157
	v_mov_b32_e32 v29, v158
	v_fma_f32 v6, -v4, v158, v159
	v_fma_f32 v7, v4, v157, v160
	v_fma_f32 v159, v2, v6, v30
	v_fma_f32 v160, v2, v7, v31
	v_mov_b32_e32 v30, v6
	v_mov_b32_e32 v31, v7
	v_fma_f32 v157, -v4, v7, v159
	v_fma_f32 v158, v4, v6, v160
	v_fma_f32 v159, v2, v157, v32
	v_fma_f32 v160, v2, v158, v33
	v_mov_b32_e32 v32, v157
	v_mov_b32_e32 v33, v158
	v_fma_f32 v6, -v4, v158, v159
	v_fma_f32 v7, v4, v157, v160
	v_fma_f32 v159, v2, v6, v34
	v_fma_f32 v160, v2, v7, v35
	v_mov_b32_e32 v34, v6
	v_mov_b32_e32 v35, v7
	v_fma_f32 v157, -v4, v7, v159
	v_fma_f32 v158, v4, v6, v160
	v_fma_f32 v159, v2, v157, v36
	v_fma_f32 v160, v2, v158, v37
	v_mov_b32_e32 v36, v157
	v_mov_b32_e32 v37, v158
	v_fma_f32 v6, -v4, v158, v159
	v_fma_f32 v7, v4, v157, v160
	v_fma_f32 v159, v2, v6, v38
	v_fma_f32 v160, v2, v7, v39
	v_mov_b32_e32 v38, v6
	v_mov_b32_e32 v39, v7
	v_fma_f32 v157, -v4, v7, v159
	v_fma_f32 v158, v4, v6, v160
	v_fma_f32 v159, v2, v157, v40
	v_fma_f32 v160, v2, v158, v41
	v_mov_b32_e32 v40, v157
	v_mov_b32_e32 v41, v158
	v_fma_f32 v6, -v4, v158, v159
	v_fma_f32 v7, v4, v157, v160
	v_fma_f32 v159, v2, v6, v42
	v_fma_f32 v160, v2, v7, v43
	v_mov_b32_e32 v42, v6
	v_mov_b32_e32 v43, v7
	v_fma_f32 v157, -v4, v7, v159
	v_fma_f32 v158, v4, v6, v160
	v_fma_f32 v159, v2, v157, v44
	v_fma_f32 v160, v2, v158, v45
	v_mov_b32_e32 v44, v157
	v_mov_b32_e32 v45, v158
	v_fma_f32 v6, -v4, v158, v159
	v_fma_f32 v7, v4, v157, v160
	v_fma_f32 v159, v2, v6, v46
	v_fma_f32 v160, v2, v7, v47
	v_mov_b32_e32 v46, v6
	v_mov_b32_e32 v47, v7
	v_fma_f32 v157, -v4, v7, v159
	v_fma_f32 v158, v4, v6, v160
	v_fma_f32 v159, v2, v157, v48
	v_fma_f32 v160, v2, v158, v49
	v_mov_b32_e32 v48, v157
	v_mov_b32_e32 v49, v158
	v_fma_f32 v6, -v4, v158, v159
	v_fma_f32 v7, v4, v157, v160
	v_fma_f32 v159, v2, v6, v50
	v_fma_f32 v160, v2, v7, v51
	v_mov_b32_e32 v50, v6
	v_mov_b32_e32 v51, v7
	v_fma_f32 v157, -v4, v7, v159
	v_fma_f32 v158, v4, v6, v160
	v_fma_f32 v159, v2, v157, v52
	v_fma_f32 v160, v2, v158, v53
	v_mov_b32_e32 v52, v157
	v_mov_b32_e32 v53, v158
	v_fma_f32 v6, -v4, v158, v159
	v_fma_f32 v7, v4, v157, v160
	v_fma_f32 v159, v2, v6, v54
	v_fma_f32 v160, v2, v7, v55
	v_mov_b32_e32 v54, v6
	v_mov_b32_e32 v55, v7
	v_fma_f32 v157, -v4, v7, v159
	v_fma_f32 v158, v4, v6, v160
	v_fma_f32 v159, v2, v157, v56
	v_fma_f32 v160, v2, v158, v57
	v_mov_b32_e32 v56, v157
	v_mov_b32_e32 v57, v158
	v_fma_f32 v6, -v4, v158, v159
	v_fma_f32 v7, v4, v157, v160
	v_fma_f32 v159, v2, v6, v58
	v_fma_f32 v160, v2, v7, v59
	v_mov_b32_e32 v58, v6
	v_mov_b32_e32 v59, v7
	v_fma_f32 v157, -v4, v7, v159
	v_fma_f32 v158, v4, v6, v160
	v_fma_f32 v159, v2, v157, v60
	v_fma_f32 v160, v2, v158, v61
	v_mov_b32_e32 v60, v157
	v_mov_b32_e32 v61, v158
	v_fma_f32 v6, -v4, v158, v159
	v_fma_f32 v7, v4, v157, v160
	v_fma_f32 v159, v2, v6, v62
	v_fma_f32 v160, v2, v7, v63
	v_mov_b32_e32 v62, v6
	v_mov_b32_e32 v63, v7
	v_fma_f32 v157, -v4, v7, v159
	v_fma_f32 v158, v4, v6, v160
	v_fma_f32 v159, v2, v157, v64
	v_fma_f32 v160, v2, v158, v65
	v_mov_b32_e32 v64, v157
	v_mov_b32_e32 v65, v158
	v_fma_f32 v6, -v4, v158, v159
	v_fma_f32 v7, v4, v157, v160
	v_fma_f32 v159, v2, v6, v66
	v_fma_f32 v160, v2, v7, v67
	v_mov_b32_e32 v66, v6
	v_mov_b32_e32 v67, v7
	v_fma_f32 v157, -v4, v7, v159
	v_fma_f32 v158, v4, v6, v160
	v_fma_f32 v159, v2, v157, v68
	v_fma_f32 v160, v2, v158, v69
	v_mov_b32_e32 v68, v157
	v_mov_b32_e32 v69, v158
	v_fma_f32 v6, -v4, v158, v159
	v_fma_f32 v7, v4, v157, v160
	v_fma_f32 v159, v2, v6, v70
	v_fma_f32 v160, v2, v7, v71
	v_mov_b32_e32 v70, v6
	v_mov_b32_e32 v71, v7
	v_fma_f32 v157, -v4, v7, v159
	v_fma_f32 v158, v4, v6, v160
	v_fma_f32 v159, v2, v157, v72
	v_fma_f32 v160, v2, v158, v73
	v_mov_b32_e32 v72, v157
	v_mov_b32_e32 v73, v158
	v_fma_f32 v6, -v4, v158, v159
	v_fma_f32 v7, v4, v157, v160
	v_fma_f32 v159, v2, v6, v74
	v_fma_f32 v160, v2, v7, v75
	v_mov_b32_e32 v74, v6
	v_mov_b32_e32 v75, v7
	v_fma_f32 v157, -v4, v7, v159
	v_fma_f32 v158, v4, v6, v160
	v_fma_f32 v159, v2, v157, v76
	v_fma_f32 v160, v2, v158, v77
	v_mov_b32_e32 v76, v157
	v_mov_b32_e32 v77, v158
	v_fma_f32 v6, -v4, v158, v159
	v_fma_f32 v7, v4, v157, v160
	v_fma_f32 v159, v2, v6, v78
	v_fma_f32 v160, v2, v7, v79
	v_mov_b32_e32 v78, v6
	v_mov_b32_e32 v79, v7
	v_fma_f32 v157, -v4, v7, v159
	v_fma_f32 v158, v4, v6, v160
	v_fma_f32 v159, v2, v157, v80
	v_fma_f32 v160, v2, v158, v81
	v_mov_b32_e32 v80, v157
	v_mov_b32_e32 v81, v158
	v_fma_f32 v6, -v4, v158, v159
	v_fma_f32 v7, v4, v157, v160
	v_fma_f32 v159, v2, v6, v82
	v_fma_f32 v160, v2, v7, v83
	v_mov_b32_e32 v82, v6
	v_mov_b32_e32 v83, v7
	v_fma_f32 v157, -v4, v7, v159
	v_fma_f32 v158, v4, v6, v160
	v_fma_f32 v159, v2, v157, v84
	v_fma_f32 v160, v2, v158, v85
	v_mov_b32_e32 v84, v157
	v_mov_b32_e32 v85, v158
	v_fma_f32 v6, -v4, v158, v159
	v_fma_f32 v7, v4, v157, v160
	v_fma_f32 v159, v2, v6, v86
	v_fma_f32 v160, v2, v7, v87
	v_mov_b32_e32 v86, v6
	v_mov_b32_e32 v87, v7
	v_fma_f32 v157, -v4, v7, v159
	v_fma_f32 v158, v4, v6, v160
	v_fma_f32 v159, v2, v157, v88
	v_fma_f32 v160, v2, v158, v89
	v_mov_b32_e32 v88, v157
	v_mov_b32_e32 v89, v158
	v_fma_f32 v6, -v4, v158, v159
	v_fma_f32 v7, v4, v157, v160
	v_fma_f32 v159, v2, v6, v90
	v_fma_f32 v160, v2, v7, v91
	v_mov_b32_e32 v90, v6
	v_mov_b32_e32 v91, v7
	v_fma_f32 v157, -v4, v7, v159
	v_fma_f32 v158, v4, v6, v160
	v_fma_f32 v159, v2, v157, v92
	v_fma_f32 v160, v2, v158, v93
	v_mov_b32_e32 v92, v157
	v_mov_b32_e32 v93, v158
	v_fma_f32 v6, -v4, v158, v159
	v_fma_f32 v7, v4, v157, v160
	v_fma_f32 v159, v2, v6, v94
	v_fma_f32 v160, v2, v7, v95
	v_mov_b32_e32 v94, v6
	v_mov_b32_e32 v95, v7
	v_fma_f32 v157, -v4, v7, v159
	v_fma_f32 v158, v4, v6, v160
	v_fma_f32 v159, v2, v157, v96
	v_fma_f32 v160, v2, v158, v97
	v_mov_b32_e32 v96, v157
	v_mov_b32_e32 v97, v158
	v_fma_f32 v6, -v4, v158, v159
	v_fma_f32 v7, v4, v157, v160
	v_fma_f32 v159, v2, v6, v98
	v_fma_f32 v160, v2, v7, v99
	v_mov_b32_e32 v98, v6
	v_mov_b32_e32 v99, v7
	v_fma_f32 v157, -v4, v7, v159
	v_fma_f32 v158, v4, v6, v160
	v_fma_f32 v159, v2, v157, v100
	v_fma_f32 v160, v2, v158, v101
	v_mov_b32_e32 v100, v157
	v_mov_b32_e32 v101, v158
	v_fma_f32 v6, -v4, v158, v159
	v_fma_f32 v7, v4, v157, v160
	v_fma_f32 v159, v2, v6, v102
	v_fma_f32 v160, v2, v7, v103
	v_mov_b32_e32 v102, v6
	v_mov_b32_e32 v103, v7
	v_fma_f32 v157, -v4, v7, v159
	v_fma_f32 v158, v4, v6, v160
	v_fma_f32 v159, v2, v157, v104
	v_fma_f32 v160, v2, v158, v105
	v_mov_b32_e32 v104, v157
	v_mov_b32_e32 v105, v158
	v_fma_f32 v6, -v4, v158, v159
	v_fma_f32 v7, v4, v157, v160
	v_fma_f32 v159, v2, v6, v106
	v_fma_f32 v160, v2, v7, v107
	v_mov_b32_e32 v106, v6
	v_mov_b32_e32 v107, v7
	v_fma_f32 v157, -v4, v7, v159
	v_fma_f32 v158, v4, v6, v160
	v_fma_f32 v159, v2, v157, v108
	v_fma_f32 v160, v2, v158, v109
	v_mov_b32_e32 v108, v157
	v_mov_b32_e32 v109, v158
	v_fma_f32 v6, -v4, v158, v159
	v_fma_f32 v7, v4, v157, v160
	v_fma_f32 v159, v2, v6, v110
	v_fma_f32 v160, v2, v7, v111
	v_mov_b32_e32 v110, v6
	v_mov_b32_e32 v111, v7
	v_fma_f32 v157, -v4, v7, v159
	v_fma_f32 v158, v4, v6, v160
	v_fma_f32 v159, v2, v157, v112
	v_fma_f32 v160, v2, v158, v113
	v_mov_b32_e32 v112, v157
	v_mov_b32_e32 v113, v158
	v_fma_f32 v6, -v4, v158, v159
	v_fma_f32 v7, v4, v157, v160
	v_fma_f32 v159, v2, v6, v114
	v_fma_f32 v160, v2, v7, v115
	v_mov_b32_e32 v114, v6
	v_mov_b32_e32 v115, v7
	v_fma_f32 v157, -v4, v7, v159
	v_fma_f32 v158, v4, v6, v160
	v_fma_f32 v159, v2, v157, v116
	v_fma_f32 v160, v2, v158, v117
	v_mov_b32_e32 v116, v157
	v_mov_b32_e32 v117, v158
	v_fma_f32 v6, -v4, v158, v159
	v_fma_f32 v7, v4, v157, v160
	v_fma_f32 v159, v2, v6, v118
	v_fma_f32 v160, v2, v7, v119
	v_mov_b32_e32 v118, v6
	v_mov_b32_e32 v119, v7
	v_fma_f32 v157, -v4, v7, v159
	v_fma_f32 v158, v4, v6, v160
	v_fma_f32 v159, v2, v157, v120
	v_fma_f32 v160, v2, v158, v121
	v_mov_b32_e32 v120, v157
	v_mov_b32_e32 v121, v158
	v_fma_f32 v6, -v4, v158, v159
	v_fma_f32 v7, v4, v157, v160
	v_fma_f32 v159, v2, v6, v122
	v_fma_f32 v160, v2, v7, v123
	v_mov_b32_e32 v122, v6
	v_mov_b32_e32 v123, v7
	v_fma_f32 v157, -v4, v7, v159
	v_fma_f32 v158, v4, v6, v160
	v_fma_f32 v159, v2, v157, v124
	v_fma_f32 v160, v2, v158, v125
	v_mov_b32_e32 v124, v157
	v_mov_b32_e32 v125, v158
	v_fma_f32 v6, -v4, v158, v159
	v_fma_f32 v7, v4, v157, v160
	v_fma_f32 v159, v2, v6, v126
	v_fma_f32 v160, v2, v7, v127
	v_mov_b32_e32 v126, v6
	v_mov_b32_e32 v127, v7
	v_fma_f32 v157, -v4, v7, v159
	v_fma_f32 v158, v4, v6, v160
	v_fma_f32 v159, v2, v157, v128
	v_fma_f32 v160, v2, v158, v129
	v_mov_b32_e32 v128, v157
	v_mov_b32_e32 v129, v158
	v_fma_f32 v6, -v4, v158, v159
	v_fma_f32 v7, v4, v157, v160
	v_fma_f32 v159, v2, v6, v130
	v_fma_f32 v160, v2, v7, v131
	v_mov_b32_e32 v130, v6
	v_mov_b32_e32 v131, v7
	v_fma_f32 v157, -v4, v7, v159
	v_fma_f32 v158, v4, v6, v160
	v_fma_f32 v159, v2, v157, v132
	v_fma_f32 v160, v2, v158, v133
	v_mov_b32_e32 v132, v157
	v_mov_b32_e32 v133, v158
	v_fma_f32 v6, -v4, v158, v159
	v_fma_f32 v7, v4, v157, v160
	v_fma_f32 v159, v2, v6, v134
	v_fma_f32 v160, v2, v7, v135
	v_mov_b32_e32 v134, v6
	v_mov_b32_e32 v135, v7
	v_fma_f32 v157, -v4, v7, v159
	v_fma_f32 v158, v4, v6, v160
	v_fma_f32 v159, v2, v157, v138
	v_fma_f32 v160, v2, v158, v139
	v_mov_b32_e32 v138, v157
	v_mov_b32_e32 v139, v158
	v_fma_f32 v6, -v4, v158, v159
	v_fma_f32 v7, v4, v157, v160
	s_waitcnt vmcnt(7)
	v_fma_f32 v159, v2, v6, v140
	v_fma_f32 v160, v2, v7, v141
	v_mov_b32_e32 v140, v6
	v_mov_b32_e32 v141, v7
	v_fma_f32 v157, -v4, v7, v159
	v_fma_f32 v158, v4, v6, v160
	s_waitcnt vmcnt(6)
	v_fma_f32 v159, v2, v157, v142
	v_fma_f32 v160, v2, v158, v143
	v_mov_b32_e32 v142, v157
	v_mov_b32_e32 v143, v158
	v_fma_f32 v6, -v4, v158, v159
	v_fma_f32 v7, v4, v157, v160
	s_waitcnt vmcnt(5)
	v_fma_f32 v159, v2, v6, v144
	v_fma_f32 v160, v2, v7, v145
	v_mov_b32_e32 v144, v6
	v_mov_b32_e32 v145, v7
	v_fma_f32 v157, -v4, v7, v159
	v_fma_f32 v158, v4, v6, v160
	s_waitcnt vmcnt(4)
	v_fma_f32 v159, v2, v157, v146
	v_fma_f32 v160, v2, v158, v147
	v_mov_b32_e32 v146, v157
	v_mov_b32_e32 v147, v158
	v_fma_f32 v6, -v4, v158, v159
	v_fma_f32 v7, v4, v157, v160
	s_waitcnt vmcnt(3)
	v_fma_f32 v159, v2, v6, v148
	v_fma_f32 v160, v2, v7, v149
	v_mov_b32_e32 v148, v6
	v_mov_b32_e32 v149, v7
	v_fma_f32 v157, -v4, v7, v159
	v_fma_f32 v158, v4, v6, v160
	s_waitcnt vmcnt(2)
	v_fma_f32 v159, v2, v157, v150
	v_fma_f32 v160, v2, v158, v151
	v_mov_b32_e32 v150, v157
	v_mov_b32_e32 v151, v158
	v_fma_f32 v6, -v4, v158, v159
	v_fma_f32 v7, v4, v157, v160
	s_waitcnt vmcnt(1)
	v_fma_f32 v159, v2, v6, v152
	v_fma_f32 v160, v2, v7, v153
	v_mov_b32_e32 v152, v6
	v_mov_b32_e32 v153, v7
	v_fma_f32 v157, -v4, v7, v159
	v_fma_f32 v158, v4, v6, v160
	v_mov_b32_e32 v154, v157
	v_mov_b32_e32 v155, v158
	s_mov_b64 s[0:1], 0x1000
	global_store_dwordx2 v[0:1], v[18:19], off offset:-3584
	global_store_dwordx2 v[0:1], v[20:21], off offset:-3072
	global_store_dwordx2 v[0:1], v[22:23], off offset:-2560
	global_store_dwordx2 v[0:1], v[24:25], off offset:-2048
	global_store_dwordx2 v[0:1], v[26:27], off offset:-1536
	global_store_dwordx2 v[0:1], v[28:29], off offset:-1024
	global_store_dwordx2 v[0:1], v[30:31], off offset:-512
	global_store_dwordx2 v[0:1], v[32:33], off offset:0
	v_lshl_add_u64 v[0:1], v[0:1], 0, s[0:1]
	global_store_dwordx2 v[0:1], v[34:35], off offset:-3584
	global_store_dwordx2 v[0:1], v[36:37], off offset:-3072
	global_store_dwordx2 v[0:1], v[38:39], off offset:-2560
	global_store_dwordx2 v[0:1], v[40:41], off offset:-2048
	global_store_dwordx2 v[0:1], v[42:43], off offset:-1536
	global_store_dwordx2 v[0:1], v[44:45], off offset:-1024
	global_store_dwordx2 v[0:1], v[46:47], off offset:-512
	global_store_dwordx2 v[0:1], v[48:49], off offset:0
	v_lshl_add_u64 v[0:1], v[0:1], 0, s[0:1]
	global_store_dwordx2 v[0:1], v[50:51], off offset:-3584
	global_store_dwordx2 v[0:1], v[52:53], off offset:-3072
	global_store_dwordx2 v[0:1], v[54:55], off offset:-2560
	global_store_dwordx2 v[0:1], v[56:57], off offset:-2048
	global_store_dwordx2 v[0:1], v[58:59], off offset:-1536
	global_store_dwordx2 v[0:1], v[60:61], off offset:-1024
	global_store_dwordx2 v[0:1], v[62:63], off offset:-512
	global_store_dwordx2 v[0:1], v[64:65], off offset:0
	v_lshl_add_u64 v[0:1], v[0:1], 0, s[0:1]
	global_store_dwordx2 v[0:1], v[66:67], off offset:-3584
	global_store_dwordx2 v[0:1], v[68:69], off offset:-3072
	global_store_dwordx2 v[0:1], v[70:71], off offset:-2560
	global_store_dwordx2 v[0:1], v[72:73], off offset:-2048
	global_store_dwordx2 v[0:1], v[74:75], off offset:-1536
	global_store_dwordx2 v[0:1], v[76:77], off offset:-1024
	global_store_dwordx2 v[0:1], v[78:79], off offset:-512
	global_store_dwordx2 v[0:1], v[80:81], off offset:0
	v_lshl_add_u64 v[0:1], v[0:1], 0, s[0:1]
	global_store_dwordx2 v[0:1], v[82:83], off offset:-3584
	global_store_dwordx2 v[0:1], v[84:85], off offset:-3072
	global_store_dwordx2 v[0:1], v[86:87], off offset:-2560
	global_store_dwordx2 v[0:1], v[88:89], off offset:-2048
	global_store_dwordx2 v[0:1], v[90:91], off offset:-1536
	global_store_dwordx2 v[0:1], v[92:93], off offset:-1024
	global_store_dwordx2 v[0:1], v[94:95], off offset:-512
	global_store_dwordx2 v[0:1], v[96:97], off offset:0
	v_lshl_add_u64 v[0:1], v[0:1], 0, s[0:1]
	global_store_dwordx2 v[0:1], v[98:99], off offset:-3584
	global_store_dwordx2 v[0:1], v[100:101], off offset:-3072
	global_store_dwordx2 v[0:1], v[102:103], off offset:-2560
	global_store_dwordx2 v[0:1], v[104:105], off offset:-2048
	global_store_dwordx2 v[0:1], v[106:107], off offset:-1536
	global_store_dwordx2 v[0:1], v[108:109], off offset:-1024
	global_store_dwordx2 v[0:1], v[110:111], off offset:-512
	global_store_dwordx2 v[0:1], v[112:113], off offset:0
	v_lshl_add_u64 v[0:1], v[0:1], 0, s[0:1]
	global_store_dwordx2 v[0:1], v[114:115], off offset:-3584
	global_store_dwordx2 v[0:1], v[116:117], off offset:-3072
	global_store_dwordx2 v[0:1], v[118:119], off offset:-2560
	global_store_dwordx2 v[0:1], v[120:121], off offset:-2048
	global_store_dwordx2 v[0:1], v[122:123], off offset:-1536
	global_store_dwordx2 v[0:1], v[124:125], off offset:-1024
	global_store_dwordx2 v[0:1], v[126:127], off offset:-512
	global_store_dwordx2 v[0:1], v[128:129], off offset:0
	v_lshl_add_u64 v[0:1], v[0:1], 0, s[0:1]
	global_store_dwordx2 v[0:1], v[130:131], off offset:-3584
	global_store_dwordx2 v[0:1], v[132:133], off offset:-3072
	global_store_dwordx2 v[0:1], v[134:135], off offset:-2560
	global_store_dwordx2 v[0:1], v[138:139], off offset:-2048
	global_store_dwordx2 v[0:1], v[140:141], off offset:-1536
	global_store_dwordx2 v[0:1], v[142:143], off offset:-1024
	global_store_dwordx2 v[0:1], v[144:145], off offset:-512
	global_store_dwordx2 v[0:1], v[146:147], off offset:0
	v_lshl_add_u64 v[0:1], v[0:1], 0, s[0:1]
	global_store_dwordx2 v[0:1], v[148:149], off offset:-3584
	global_store_dwordx2 v[0:1], v[150:151], off offset:-3072
	global_store_dwordx2 v[0:1], v[152:153], off offset:-2560
	global_store_dwordx2 v[0:1], v[154:155], off offset:-2048

.Lrn_p1_end:
.LBB0_620:
	s_bitcmp0_b32 s94, 14
	s_cbranch_scc1 .LBB0_624
	v_and_b32_e32 v206, 15, v205
	v_lshrrev_b32_e32 v207, 4, v205
	v_lshlrev_b32_e32 v208, 3, v205
	v_lshlrev_b32_e32 v209, 4, v205
	v_lshrrev_b32_e32 v210, 6, v186
	s_nop 0
	v_readfirstlane_b32 s22, v210
	v_lshrrev_b32_e32 v135, 3, v205
	v_and_b32_e32 v132, 7, v205
	v_xor_b32_e32 v132, v132, v135
	v_lshlrev_b32_e32 v132, 4, v132
	v_lshl_add_u32 v132, v135, 9, v132
	s_lshl_b32 s23, s22, 13
	v_and_b32_e32 v135, 7, v206
	v_xor_b32_e32 v133, 0, v207
	v_xor_b32_e32 v133, v133, v135
	v_lshlrev_b32_e32 v133, 4, v133
	v_lshl_add_u32 v133, v206, 7, v133
	v_add_u32_e32 v128, 0x10000, v133
	v_add_u32_e32 v133, s23, v133
	v_xor_b32_e32 v134, 4, v207
	v_or_b32_e32 v134, 4, v207
	v_xor_b32_e32 v134, v134, v135
	v_lshlrev_b32_e32 v134, 4, v134
	v_lshl_add_u32 v134, v206, 7, v134
	v_add_u32_e32 v129, 0x10000, v134
	v_add_u32_e32 v134, s23, v134
	v_mul_u32_u24_e32 v212, 0x90, v206
	v_add_u32_e32 v212, 0x21000, v212
	v_lshl_add_u32 v211, v210, 2, v207
	v_lshl_add_u32 v211, v211, 2, v212
	v_lshlrev_b32_e32 v213, 11, v206
	v_lshl_add_u32 v213, v207, 3, v213
	s_lshl_b32 s0, s22, 6
	s_addk_i32 s0, 0x600
	v_add_u32_e32 v213, s0, v213
	s_mul_i32 s0, s24, 0x1600000
	s_add_u32 s0, s0, 0xfc0000
	s_lshl_b32 s1, s22, 14
	s_add_u32 s0, s0, s1
	s_add_u32 s8, s4, s0
	s_addc_u32 s9, s5, 0
	s_lshl_b32 s16, s69, 6
	s_addk_i32 s16, 0x400
	s_mov_b32 s17, 0
.Lgg_blk:
	s_lshl_b32 s0, s22, 3
	s_add_i32 s0, s0, s16
	s_mul_i32 s1, s0, 0x600
	s_add_u32 s1, s1, 0xdf00000
	s_add_u32 s10, s4, s1
	s_addc_u32 s11, s5, 0
	s_lshl_b32 s1, s0, 11
	s_add_u32 s1, s1, 0x3c00000
	s_add_u32 s12, s4, s1
	s_addc_u32 s13, s5, 0
	s_lshl_b32 s1, s16, 11
	s_add_u32 s1, s1, 0x3c00000
	s_add_u32 s14, s4, s1
	s_addc_u32 s15, s5, 0
	s_lshl_b32 s1, s16, 9
	s_add_u32 s1, s1, 0xc500000
	s_add_u32 s6, s4, s1
	s_addc_u32 s7, s5, 0
	s_lshl_b32 s0, s22, 12
	s_add_u32 s6, s6, s0
	s_addc_u32 s7, s7, 0
	s_lshl_b32 s18, s22, 10
	s_add_i32 s18, s18, 0x10000
	s_add_i32 m0, s18, 0x0
	s_nop 0
	global_load_lds_dwordx4 v132, s[6:7]
	s_add_u32 s6, s6, 0x80
	s_addc_u32 s7, s7, 0
	s_add_i32 m0, s18, 0x2000
	s_nop 0
	global_load_lds_dwordx4 v132, s[6:7]
	s_add_u32 s6, s6, 0x80
	s_addc_u32 s7, s7, 0
	s_add_i32 m0, s18, 0x4000
	s_nop 0
	global_load_lds_dwordx4 v132, s[6:7]
	s_add_u32 s6, s6, 0x80
	s_addc_u32 s7, s7, 0
	s_add_i32 m0, s18, 0x6000
	s_nop 0
	global_load_lds_dwordx4 v132, s[6:7]
	s_lshl_b32 s0, s22, 3
	s_add_i32 s0, s0, s16
	s_lshl_b32 s0, s0, 9
	s_lshl_b32 s1, s22, 10
	s_add_i32 s1, s1, 0x10000
	s_add_u32 s6, s0, 0xbc00000
	s_add_u32 s6, s4, s6
	s_addc_u32 s7, s5, 0
	s_add_i32 m0, s1, 0x8000
	s_nop 0
	global_load_lds_dwordx4 v132, s[6:7]
	s_add_u32 s6, s6, 0x80
	s_addc_u32 s7, s7, 0
	s_add_i32 m0, s1, 0xa000
	s_nop 0
	global_load_lds_dwordx4 v132, s[6:7]
	s_add_u32 s6, s6, 0x80
	s_addc_u32 s7, s7, 0
	s_add_i32 m0, s1, 0xc000
	s_nop 0
	global_load_lds_dwordx4 v132, s[6:7]
	s_add_u32 s6, s6, 0x80
	s_addc_u32 s7, s7, 0
	s_add_i32 m0, s1, 0xe000
	s_nop 0
	global_load_lds_dwordx4 v132, s[6:7]
	s_add_u32 s0, s8, 0x0
	s_addc_u32 s1, s9, 0
	s_add_i32 m0, s23, 0x0
	s_nop 0
	global_load_lds_dwordx4 v132, s[0:1]
	s_add_u32 s0, s8, 0x1000
	s_addc_u32 s1, s9, 0
	s_add_i32 m0, s23, 0x400
	s_nop 0
	global_load_lds_dwordx4 v132, s[0:1]
	s_add_u32 s0, s8, 0x2000
	s_addc_u32 s1, s9, 0
	s_add_i32 m0, s23, 0x800
	s_nop 0
	global_load_lds_dwordx4 v132, s[0:1]
	s_add_u32 s0, s8, 0x3000
	s_addc_u32 s1, s9, 0
	s_add_i32 m0, s23, 0xc00
	s_nop 0
	global_load_lds_dwordx4 v132, s[0:1]
	s_add_u32 s0, s8, 0x20000
	s_addc_u32 s1, s9, 0
	s_add_i32 m0, s23, 0x1000
	s_nop 0
	global_load_lds_dwordx4 v132, s[0:1]
	s_add_u32 s0, s8, 0x21000
	s_addc_u32 s1, s9, 0
	s_add_i32 m0, s23, 0x1400
	s_nop 0
	global_load_lds_dwordx4 v132, s[0:1]
	s_add_u32 s0, s8, 0x22000
	s_addc_u32 s1, s9, 0
	s_add_i32 m0, s23, 0x1800
	s_nop 0
	global_load_lds_dwordx4 v132, s[0:1]
	s_add_u32 s0, s8, 0x23000
	s_addc_u32 s1, s9, 0
	s_add_i32 m0, s23, 0x1c00
	s_nop 0
	global_load_lds_dwordx4 v132, s[0:1]
	s_waitcnt vmcnt(12)
	s_barrier
	ds_read_b128 v[138:141], v128 offset:0
	ds_read_b128 v[142:145], v128 offset:2048
	ds_read_b128 v[146:149], v128 offset:4096
	ds_read_b128 v[150:153], v128 offset:6144
	ds_read_b128 v[154:157], v129 offset:0
	ds_read_b128 v[158:161], v129 offset:2048
	ds_read_b128 v[162:165], v129 offset:4096
	ds_read_b128 v[166:169], v129 offset:6144
	s_waitcnt vmcnt(0)
	ds_read_b128 v[64:67], v133 offset:0
	ds_read_b128 v[72:75], v133 offset:2048
	ds_read_b128 v[80:83], v133 offset:4096
	ds_read_b128 v[88:91], v133 offset:6144
	ds_read_b128 v[68:71], v134 offset:0
	ds_read_b128 v[76:79], v134 offset:2048
	ds_read_b128 v[84:87], v134 offset:4096
	ds_read_b128 v[92:95], v134 offset:6144
	s_waitcnt lgkmcnt(0)
	s_add_u32 s0, s8, 0x80
	s_addc_u32 s1, s9, 0
	s_add_i32 m0, s23, 0x0
	s_nop 0
	global_load_lds_dwordx4 v132, s[0:1]
	s_add_u32 s0, s8, 0x1080
	s_addc_u32 s1, s9, 0
	s_add_i32 m0, s23, 0x400
	s_nop 0
	global_load_lds_dwordx4 v132, s[0:1]
	s_add_u32 s0, s8, 0x2080
	s_addc_u32 s1, s9, 0
	s_add_i32 m0, s23, 0x800
	s_nop 0
	global_load_lds_dwordx4 v132, s[0:1]
	s_add_u32 s0, s8, 0x3080
	s_addc_u32 s1, s9, 0
	s_add_i32 m0, s23, 0xc00
	s_nop 0
	global_load_lds_dwordx4 v132, s[0:1]
	s_add_u32 s0, s8, 0x20080
	s_addc_u32 s1, s9, 0
	s_add_i32 m0, s23, 0x1000
	s_nop 0
	global_load_lds_dwordx4 v132, s[0:1]
	s_add_u32 s0, s8, 0x21080
	s_addc_u32 s1, s9, 0
	s_add_i32 m0, s23, 0x1400
	s_nop 0
	global_load_lds_dwordx4 v132, s[0:1]
	s_add_u32 s0, s8, 0x22080
	s_addc_u32 s1, s9, 0
	s_add_i32 m0, s23, 0x1800
	s_nop 0
	global_load_lds_dwordx4 v132, s[0:1]
	s_add_u32 s0, s8, 0x23080
	s_addc_u32 s1, s9, 0
	s_add_i32 m0, s23, 0x1c00
	s_nop 0
	global_load_lds_dwordx4 v132, s[0:1]
	v_mfma_f32_16x16x32_bf16 v[0:3], v[64:67], v[138:141], 0
	v_mfma_f32_16x16x32_bf16 v[16:19], v[64:67], v[142:145], 0
	v_mfma_f32_16x16x32_bf16 v[32:35], v[64:67], v[146:149], 0
	v_mfma_f32_16x16x32_bf16 v[48:51], v[64:67], v[150:153], 0
	v_mfma_f32_16x16x32_bf16 v[4:7], v[72:75], v[138:141], 0
	v_mfma_f32_16x16x32_bf16 v[20:23], v[72:75], v[142:145], 0
	v_mfma_f32_16x16x32_bf16 v[36:39], v[72:75], v[146:149], 0
	v_mfma_f32_16x16x32_bf16 v[52:55], v[72:75], v[150:153], 0
	v_mfma_f32_16x16x32_bf16 v[8:11], v[80:83], v[138:141], 0
	v_mfma_f32_16x16x32_bf16 v[24:27], v[80:83], v[142:145], 0
	v_mfma_f32_16x16x32_bf16 v[40:43], v[80:83], v[146:149], 0
	v_mfma_f32_16x16x32_bf16 v[56:59], v[80:83], v[150:153], 0
	v_mfma_f32_16x16x32_bf16 v[12:15], v[88:91], v[138:141], 0
	v_mfma_f32_16x16x32_bf16 v[28:31], v[88:91], v[142:145], 0
	v_mfma_f32_16x16x32_bf16 v[44:47], v[88:91], v[146:149], 0
	v_mfma_f32_16x16x32_bf16 v[60:63], v[88:91], v[150:153], 0
	ds_read_b128 v[170:173], v128 offset:8192
	ds_read_b128 v[174:177], v128 offset:10240
	ds_read_b128 v[178:181], v128 offset:12288
	ds_read_b128 v[182:185], v128 offset:14336
	s_waitcnt vmcnt(0)
	ds_read_b128 v[96:99], v133 offset:0
	ds_read_b128 v[104:107], v133 offset:2048
	ds_read_b128 v[112:115], v133 offset:4096
	ds_read_b128 v[120:123], v133 offset:6144
	ds_read_b128 v[100:103], v134 offset:0
	ds_read_b128 v[108:111], v134 offset:2048
	ds_read_b128 v[116:119], v134 offset:4096
	ds_read_b128 v[124:127], v134 offset:6144
	v_mfma_f32_16x16x32_bf16 v[0:3], v[68:71], v[154:157], v[0:3]
	v_mfma_f32_16x16x32_bf16 v[16:19], v[68:71], v[158:161], v[16:19]
	v_mfma_f32_16x16x32_bf16 v[32:35], v[68:71], v[162:165], v[32:35]
	v_mfma_f32_16x16x32_bf16 v[48:51], v[68:71], v[166:169], v[48:51]
	v_mfma_f32_16x16x32_bf16 v[4:7], v[76:79], v[154:157], v[4:7]
	v_mfma_f32_16x16x32_bf16 v[20:23], v[76:79], v[158:161], v[20:23]
	v_mfma_f32_16x16x32_bf16 v[36:39], v[76:79], v[162:165], v[36:39]
	v_mfma_f32_16x16x32_bf16 v[52:55], v[76:79], v[166:169], v[52:55]
	v_mfma_f32_16x16x32_bf16 v[8:11], v[84:87], v[154:157], v[8:11]
	v_mfma_f32_16x16x32_bf16 v[24:27], v[84:87], v[158:161], v[24:27]
	v_mfma_f32_16x16x32_bf16 v[40:43], v[84:87], v[162:165], v[40:43]
	v_mfma_f32_16x16x32_bf16 v[56:59], v[84:87], v[166:169], v[56:59]
	v_mfma_f32_16x16x32_bf16 v[12:15], v[92:95], v[154:157], v[12:15]
	v_mfma_f32_16x16x32_bf16 v[28:31], v[92:95], v[158:161], v[28:31]
	v_mfma_f32_16x16x32_bf16 v[44:47], v[92:95], v[162:165], v[44:47]
	v_mfma_f32_16x16x32_bf16 v[60:63], v[92:95], v[166:169], v[60:63]
	ds_read_b128 v[138:141], v129 offset:8192
	ds_read_b128 v[142:145], v129 offset:10240
	ds_read_b128 v[146:149], v129 offset:12288
	ds_read_b128 v[150:153], v129 offset:14336
	s_waitcnt lgkmcnt(4)
	s_add_u32 s0, s8, 0x100
	s_addc_u32 s1, s9, 0
	s_add_i32 m0, s23, 0x0
	s_nop 0
	global_load_lds_dwordx4 v132, s[0:1]
	s_add_u32 s0, s8, 0x1100
	s_addc_u32 s1, s9, 0
	s_add_i32 m0, s23, 0x400
	s_nop 0
	global_load_lds_dwordx4 v132, s[0:1]
	s_add_u32 s0, s8, 0x2100
	s_addc_u32 s1, s9, 0
	s_add_i32 m0, s23, 0x800
	s_nop 0
	global_load_lds_dwordx4 v132, s[0:1]
	s_add_u32 s0, s8, 0x3100
	s_addc_u32 s1, s9, 0
	s_add_i32 m0, s23, 0xc00
	s_nop 0
	global_load_lds_dwordx4 v132, s[0:1]
	s_add_u32 s0, s8, 0x20100
	s_addc_u32 s1, s9, 0
	s_add_i32 m0, s23, 0x1000
	s_nop 0
	global_load_lds_dwordx4 v132, s[0:1]
	s_add_u32 s0, s8, 0x21100
	s_addc_u32 s1, s9, 0
	s_add_i32 m0, s23, 0x1400
	s_nop 0
	global_load_lds_dwordx4 v132, s[0:1]
	s_add_u32 s0, s8, 0x22100
	s_addc_u32 s1, s9, 0
	s_add_i32 m0, s23, 0x1800
	s_nop 0
	global_load_lds_dwordx4 v132, s[0:1]
	s_add_u32 s0, s8, 0x23100
	s_addc_u32 s1, s9, 0
	s_add_i32 m0, s23, 0x1c00
	s_nop 0
	global_load_lds_dwordx4 v132, s[0:1]
	v_mfma_f32_16x16x32_bf16 v[0:3], v[96:99], v[170:173], v[0:3]
	v_mfma_f32_16x16x32_bf16 v[16:19], v[96:99], v[174:177], v[16:19]
	v_mfma_f32_16x16x32_bf16 v[32:35], v[96:99], v[178:181], v[32:35]
	v_mfma_f32_16x16x32_bf16 v[48:51], v[96:99], v[182:185], v[48:51]
	v_mfma_f32_16x16x32_bf16 v[4:7], v[104:107], v[170:173], v[4:7]
	v_mfma_f32_16x16x32_bf16 v[20:23], v[104:107], v[174:177], v[20:23]
	v_mfma_f32_16x16x32_bf16 v[36:39], v[104:107], v[178:181], v[36:39]
	v_mfma_f32_16x16x32_bf16 v[52:55], v[104:107], v[182:185], v[52:55]
	v_mfma_f32_16x16x32_bf16 v[8:11], v[112:115], v[170:173], v[8:11]
	v_mfma_f32_16x16x32_bf16 v[24:27], v[112:115], v[174:177], v[24:27]
	v_mfma_f32_16x16x32_bf16 v[40:43], v[112:115], v[178:181], v[40:43]
	v_mfma_f32_16x16x32_bf16 v[56:59], v[112:115], v[182:185], v[56:59]
	v_mfma_f32_16x16x32_bf16 v[12:15], v[120:123], v[170:173], v[12:15]
	v_mfma_f32_16x16x32_bf16 v[28:31], v[120:123], v[174:177], v[28:31]
	v_mfma_f32_16x16x32_bf16 v[44:47], v[120:123], v[178:181], v[44:47]
	v_mfma_f32_16x16x32_bf16 v[60:63], v[120:123], v[182:185], v[60:63]
	ds_read_b128 v[154:157], v128 offset:16384
	ds_read_b128 v[158:161], v128 offset:18432
	ds_read_b128 v[162:165], v128 offset:20480
	ds_read_b128 v[166:169], v128 offset:22528
	s_waitcnt vmcnt(0)
	ds_read_b128 v[64:67], v133 offset:0
	ds_read_b128 v[72:75], v133 offset:2048
	ds_read_b128 v[80:83], v133 offset:4096
	ds_read_b128 v[88:91], v133 offset:6144
	ds_read_b128 v[68:71], v134 offset:0
	ds_read_b128 v[76:79], v134 offset:2048
	ds_read_b128 v[84:87], v134 offset:4096
	ds_read_b128 v[92:95], v134 offset:6144
	s_waitcnt lgkmcnt(12)
	v_mfma_f32_16x16x32_bf16 v[0:3], v[100:103], v[138:141], v[0:3]
	v_mfma_f32_16x16x32_bf16 v[16:19], v[100:103], v[142:145], v[16:19]
	v_mfma_f32_16x16x32_bf16 v[32:35], v[100:103], v[146:149], v[32:35]
	v_mfma_f32_16x16x32_bf16 v[48:51], v[100:103], v[150:153], v[48:51]
	v_mfma_f32_16x16x32_bf16 v[4:7], v[108:111], v[138:141], v[4:7]
	v_mfma_f32_16x16x32_bf16 v[20:23], v[108:111], v[142:145], v[20:23]
	v_mfma_f32_16x16x32_bf16 v[36:39], v[108:111], v[146:149], v[36:39]
	v_mfma_f32_16x16x32_bf16 v[52:55], v[108:111], v[150:153], v[52:55]
	v_mfma_f32_16x16x32_bf16 v[8:11], v[116:119], v[138:141], v[8:11]
	v_mfma_f32_16x16x32_bf16 v[24:27], v[116:119], v[142:145], v[24:27]
	v_mfma_f32_16x16x32_bf16 v[40:43], v[116:119], v[146:149], v[40:43]
	v_mfma_f32_16x16x32_bf16 v[56:59], v[116:119], v[150:153], v[56:59]
	v_mfma_f32_16x16x32_bf16 v[12:15], v[124:127], v[138:141], v[12:15]
	v_mfma_f32_16x16x32_bf16 v[28:31], v[124:127], v[142:145], v[28:31]
	v_mfma_f32_16x16x32_bf16 v[44:47], v[124:127], v[146:149], v[44:47]
	v_mfma_f32_16x16x32_bf16 v[60:63], v[124:127], v[150:153], v[60:63]
	ds_read_b128 v[170:173], v129 offset:16384
	ds_read_b128 v[174:177], v129 offset:18432
	ds_read_b128 v[178:181], v129 offset:20480
	ds_read_b128 v[182:185], v129 offset:22528
	s_waitcnt lgkmcnt(4)
	s_add_u32 s0, s8, 0x180
	s_addc_u32 s1, s9, 0
	s_add_i32 m0, s23, 0x0
	s_nop 0
	global_load_lds_dwordx4 v132, s[0:1]
	s_add_u32 s0, s8, 0x1180
	s_addc_u32 s1, s9, 0
	s_add_i32 m0, s23, 0x400
	s_nop 0
	global_load_lds_dwordx4 v132, s[0:1]
	s_add_u32 s0, s8, 0x2180
	s_addc_u32 s1, s9, 0
	s_add_i32 m0, s23, 0x800
	s_nop 0
	global_load_lds_dwordx4 v132, s[0:1]
	s_add_u32 s0, s8, 0x3180
	s_addc_u32 s1, s9, 0
	s_add_i32 m0, s23, 0xc00
	s_nop 0
	global_load_lds_dwordx4 v132, s[0:1]
	s_add_u32 s0, s8, 0x20180
	s_addc_u32 s1, s9, 0
	s_add_i32 m0, s23, 0x1000
	s_nop 0
	global_load_lds_dwordx4 v132, s[0:1]
	s_add_u32 s0, s8, 0x21180
	s_addc_u32 s1, s9, 0
	s_add_i32 m0, s23, 0x1400
	s_nop 0
	global_load_lds_dwordx4 v132, s[0:1]
	s_add_u32 s0, s8, 0x22180
	s_addc_u32 s1, s9, 0
	s_add_i32 m0, s23, 0x1800
	s_nop 0
	global_load_lds_dwordx4 v132, s[0:1]
	s_add_u32 s0, s8, 0x23180
	s_addc_u32 s1, s9, 0
	s_add_i32 m0, s23, 0x1c00
	s_nop 0
	global_load_lds_dwordx4 v132, s[0:1]
	v_mfma_f32_16x16x32_bf16 v[0:3], v[64:67], v[154:157], v[0:3]
	v_mfma_f32_16x16x32_bf16 v[16:19], v[64:67], v[158:161], v[16:19]
	v_mfma_f32_16x16x32_bf16 v[32:35], v[64:67], v[162:165], v[32:35]
	v_mfma_f32_16x16x32_bf16 v[48:51], v[64:67], v[166:169], v[48:51]
	v_mfma_f32_16x16x32_bf16 v[4:7], v[72:75], v[154:157], v[4:7]
	v_mfma_f32_16x16x32_bf16 v[20:23], v[72:75], v[158:161], v[20:23]
	v_mfma_f32_16x16x32_bf16 v[36:39], v[72:75], v[162:165], v[36:39]
	v_mfma_f32_16x16x32_bf16 v[52:55], v[72:75], v[166:169], v[52:55]
	v_mfma_f32_16x16x32_bf16 v[8:11], v[80:83], v[154:157], v[8:11]
	v_mfma_f32_16x16x32_bf16 v[24:27], v[80:83], v[158:161], v[24:27]
	v_mfma_f32_16x16x32_bf16 v[40:43], v[80:83], v[162:165], v[40:43]
	v_mfma_f32_16x16x32_bf16 v[56:59], v[80:83], v[166:169], v[56:59]
	v_mfma_f32_16x16x32_bf16 v[12:15], v[88:91], v[154:157], v[12:15]
	v_mfma_f32_16x16x32_bf16 v[28:31], v[88:91], v[158:161], v[28:31]
	v_mfma_f32_16x16x32_bf16 v[44:47], v[88:91], v[162:165], v[44:47]
	v_mfma_f32_16x16x32_bf16 v[60:63], v[88:91], v[166:169], v[60:63]
	ds_read_b128 v[138:141], v128 offset:24576
	ds_read_b128 v[142:145], v128 offset:26624
	ds_read_b128 v[146:149], v128 offset:28672
	ds_read_b128 v[150:153], v128 offset:30720
	s_waitcnt vmcnt(0)
	ds_read_b128 v[96:99], v133 offset:0
	ds_read_b128 v[104:107], v133 offset:2048
	ds_read_b128 v[112:115], v133 offset:4096
	ds_read_b128 v[120:123], v133 offset:6144
	ds_read_b128 v[100:103], v134 offset:0
	ds_read_b128 v[108:111], v134 offset:2048
	ds_read_b128 v[116:119], v134 offset:4096
	ds_read_b128 v[124:127], v134 offset:6144
	s_waitcnt lgkmcnt(12)
	v_mfma_f32_16x16x32_bf16 v[0:3], v[68:71], v[170:173], v[0:3]
	v_mfma_f32_16x16x32_bf16 v[16:19], v[68:71], v[174:177], v[16:19]
	v_mfma_f32_16x16x32_bf16 v[32:35], v[68:71], v[178:181], v[32:35]
	v_mfma_f32_16x16x32_bf16 v[48:51], v[68:71], v[182:185], v[48:51]
	v_mfma_f32_16x16x32_bf16 v[4:7], v[76:79], v[170:173], v[4:7]
	v_mfma_f32_16x16x32_bf16 v[20:23], v[76:79], v[174:177], v[20:23]
	v_mfma_f32_16x16x32_bf16 v[36:39], v[76:79], v[178:181], v[36:39]
	v_mfma_f32_16x16x32_bf16 v[52:55], v[76:79], v[182:185], v[52:55]
	v_mfma_f32_16x16x32_bf16 v[8:11], v[84:87], v[170:173], v[8:11]
	v_mfma_f32_16x16x32_bf16 v[24:27], v[84:87], v[174:177], v[24:27]
	v_mfma_f32_16x16x32_bf16 v[40:43], v[84:87], v[178:181], v[40:43]
	v_mfma_f32_16x16x32_bf16 v[56:59], v[84:87], v[182:185], v[56:59]
	v_mfma_f32_16x16x32_bf16 v[12:15], v[92:95], v[170:173], v[12:15]
	v_mfma_f32_16x16x32_bf16 v[28:31], v[92:95], v[174:177], v[28:31]
	v_mfma_f32_16x16x32_bf16 v[44:47], v[92:95], v[178:181], v[44:47]
	v_mfma_f32_16x16x32_bf16 v[60:63], v[92:95], v[182:185], v[60:63]
	ds_read_b128 v[154:157], v129 offset:24576
	ds_read_b128 v[158:161], v129 offset:26624
	ds_read_b128 v[162:165], v129 offset:28672
	ds_read_b128 v[166:169], v129 offset:30720
	s_waitcnt lgkmcnt(4)
	s_lshl_b32 s0, s24, 11
	s_add_u32 s0, s0, 0x220320
	s_lshl_b32 s1, s22, 7
	s_add_u32 s0, s0, s1
	s_add_u32 s20, s4, s0
	s_addc_u32 s21, s5, 0
	s_lshl_b32 s0, s24, 12
	s_add_u32 s0, s0, 0x221f20
	s_add_u32 s0, s0, s1
	s_add_u32 s18, s4, s0
	s_addc_u32 s19, s5, 0
	v_lshlrev_b32_e32 v214, 4, v207
	global_load_dwordx4 v[64:67], v214, s[20:21] offset:0
	global_load_dwordx4 v[72:75], v214, s[20:21] offset:1024
	global_load_dwordx4 v[80:83], v214, s[18:19] offset:0
	global_load_dwordx4 v[68:71], v214, s[20:21] offset:64
	global_load_dwordx4 v[76:79], v214, s[20:21] offset:1088
	global_load_dwordx4 v[84:87], v214, s[18:19] offset:64
	v_mfma_f32_16x16x32_bf16 v[0:3], v[96:99], v[138:141], v[0:3]
	v_mfma_f32_16x16x32_bf16 v[16:19], v[96:99], v[142:145], v[16:19]
	v_mfma_f32_16x16x32_bf16 v[32:35], v[96:99], v[146:149], v[32:35]
	v_mfma_f32_16x16x32_bf16 v[48:51], v[96:99], v[150:153], v[48:51]
	v_mfma_f32_16x16x32_bf16 v[4:7], v[104:107], v[138:141], v[4:7]
	v_mfma_f32_16x16x32_bf16 v[20:23], v[104:107], v[142:145], v[20:23]
	v_mfma_f32_16x16x32_bf16 v[36:39], v[104:107], v[146:149], v[36:39]
	v_mfma_f32_16x16x32_bf16 v[52:55], v[104:107], v[150:153], v[52:55]
	v_mfma_f32_16x16x32_bf16 v[8:11], v[112:115], v[138:141], v[8:11]
	v_mfma_f32_16x16x32_bf16 v[24:27], v[112:115], v[142:145], v[24:27]
	v_mfma_f32_16x16x32_bf16 v[40:43], v[112:115], v[146:149], v[40:43]
	v_mfma_f32_16x16x32_bf16 v[56:59], v[112:115], v[150:153], v[56:59]
	v_mfma_f32_16x16x32_bf16 v[12:15], v[120:123], v[138:141], v[12:15]
	v_mfma_f32_16x16x32_bf16 v[28:31], v[120:123], v[142:145], v[28:31]
	v_mfma_f32_16x16x32_bf16 v[44:47], v[120:123], v[146:149], v[44:47]
	v_mfma_f32_16x16x32_bf16 v[60:63], v[120:123], v[150:153], v[60:63]
	s_waitcnt lgkmcnt(0)
	v_mfma_f32_16x16x32_bf16 v[0:3], v[100:103], v[154:157], v[0:3]
	v_mfma_f32_16x16x32_bf16 v[16:19], v[100:103], v[158:161], v[16:19]
	v_mfma_f32_16x16x32_bf16 v[32:35], v[100:103], v[162:165], v[32:35]
	v_mfma_f32_16x16x32_bf16 v[48:51], v[100:103], v[166:169], v[48:51]
	v_mfma_f32_16x16x32_bf16 v[4:7], v[108:111], v[154:157], v[4:7]
	v_mfma_f32_16x16x32_bf16 v[20:23], v[108:111], v[158:161], v[20:23]
	v_mfma_f32_16x16x32_bf16 v[36:39], v[108:111], v[162:165], v[36:39]
	v_mfma_f32_16x16x32_bf16 v[52:55], v[108:111], v[166:169], v[52:55]
	v_mfma_f32_16x16x32_bf16 v[8:11], v[116:119], v[154:157], v[8:11]
	v_mfma_f32_16x16x32_bf16 v[24:27], v[116:119], v[158:161], v[24:27]
	v_mfma_f32_16x16x32_bf16 v[40:43], v[116:119], v[162:165], v[40:43]
	v_mfma_f32_16x16x32_bf16 v[56:59], v[116:119], v[166:169], v[56:59]
	v_mfma_f32_16x16x32_bf16 v[12:15], v[124:127], v[154:157], v[12:15]
	v_mfma_f32_16x16x32_bf16 v[28:31], v[124:127], v[158:161], v[28:31]
	v_mfma_f32_16x16x32_bf16 v[44:47], v[124:127], v[162:165], v[44:47]
	v_mfma_f32_16x16x32_bf16 v[60:63], v[124:127], v[166:169], v[60:63]
	s_mul_i32 s0, s24, 0x1600000
	s_lshl_b32 s1, s22, 14
	s_add_u32 s0, s0, s1
	s_add_u32 s1, s0, 0xf80000
	s_add_u32 s18, s4, s1
	s_addc_u32 s19, s5, 0
	s_add_u32 s1, s0, 0xfa0000
	s_add_u32 s20, s4, s1
	s_addc_u32 s21, s5, 0
	s_add_u32 s0, s18, 0x0
	s_addc_u32 s1, s19, 0
	s_add_i32 m0, s23, 0x0
	s_nop 0
	global_load_lds_dwordx4 v132, s[0:1]
	s_add_u32 s0, s18, 0x1000
	s_addc_u32 s1, s19, 0
	s_add_i32 m0, s23, 0x400
	s_nop 0
	global_load_lds_dwordx4 v132, s[0:1]
	s_add_u32 s0, s18, 0x2000
	s_addc_u32 s1, s19, 0
	s_add_i32 m0, s23, 0x800
	s_nop 0
	global_load_lds_dwordx4 v132, s[0:1]
	s_add_u32 s0, s18, 0x3000
	s_addc_u32 s1, s19, 0
	s_add_i32 m0, s23, 0xc00
	s_nop 0
	global_load_lds_dwordx4 v132, s[0:1]
	s_add_u32 s0, s20, 0x0
	s_addc_u32 s1, s21, 0
	s_add_i32 m0, s23, 0x1000
	s_nop 0
	global_load_lds_dwordx4 v132, s[0:1]
	s_add_u32 s0, s20, 0x1000
	s_addc_u32 s1, s21, 0
	s_add_i32 m0, s23, 0x1400
	s_nop 0
	global_load_lds_dwordx4 v132, s[0:1]
	s_add_u32 s0, s20, 0x2000
	s_addc_u32 s1, s21, 0
	s_add_i32 m0, s23, 0x1800
	s_nop 0
	global_load_lds_dwordx4 v132, s[0:1]
	s_add_u32 s0, s20, 0x3000
	s_addc_u32 s1, s21, 0
	s_add_i32 m0, s23, 0x1c00
	s_nop 0
	global_load_lds_dwordx4 v132, s[0:1]
	s_waitcnt vmcnt(8)
	s_nop 6
	v_mov_b32_e32 v94, 0
	v_mov_b32_e32 v95, 0
	v_mov_b32_e32 v215, 0
	v_mov_b32_e32 v216, 0
	v_add_f32_e32 v0, v0, v64
	v_add_f32_e32 v8, v8, v72
	v_bfe_u32 v88, v0, 16, 1
	v_bfe_u32 v89, v8, 16, 1
	v_add3_u32 v0, v0, v88, s77
	v_add3_u32 v8, v8, v89, s77
	v_and_b32_e32 v0, s35, v0
	v_and_b32_e32 v8, s35, v8
	v_mul_f32_e32 v8, 0xbfb8aa3b, v8
	v_exp_f32_e32 v8, v8
	s_nop 0
	v_add_f32_e32 v8, 1.0, v8
	v_div_scale_f32 v88, s[6:7], v8, v8, 1.0
	v_rcp_f32_e32 v89, v88
	s_nop 0
	v_fma_f32 v90, -v88, v89, 1.0
	v_fmac_f32_e32 v89, v90, v89
	v_div_scale_f32 v90, vcc, 1.0, v8, 1.0
	v_mul_f32_e32 v91, v90, v89
	v_fma_f32 v92, -v88, v91, v90
	v_fmac_f32_e32 v91, v92, v89
	v_fma_f32 v88, -v88, v91, v90
	v_div_fmas_f32 v88, v88, v89, v91
	v_div_fixup_f32 v8, v88, v8, 1.0
	v_mul_f32_e32 v0, v8, v0
	v_fmac_f32_e32 v94, v0, v0
	v_add_f32_e32 v1, v1, v65
	v_add_f32_e32 v9, v9, v73
	v_bfe_u32 v88, v1, 16, 1
	v_bfe_u32 v89, v9, 16, 1
	v_add3_u32 v1, v1, v88, s77
	v_add3_u32 v9, v9, v89, s77
	v_and_b32_e32 v1, s35, v1
	v_and_b32_e32 v9, s35, v9
	v_mul_f32_e32 v9, 0xbfb8aa3b, v9
	v_exp_f32_e32 v9, v9
	s_nop 0
	v_add_f32_e32 v9, 1.0, v9
	v_div_scale_f32 v88, s[6:7], v9, v9, 1.0
	v_rcp_f32_e32 v89, v88
	s_nop 0
	v_fma_f32 v90, -v88, v89, 1.0
	v_fmac_f32_e32 v89, v90, v89
	v_div_scale_f32 v90, vcc, 1.0, v9, 1.0
	v_mul_f32_e32 v91, v90, v89
	v_fma_f32 v92, -v88, v91, v90
	v_fmac_f32_e32 v91, v92, v89
	v_fma_f32 v88, -v88, v91, v90
	v_div_fmas_f32 v88, v88, v89, v91
	v_div_fixup_f32 v9, v88, v9, 1.0
	v_mul_f32_e32 v1, v9, v1
	v_fmac_f32_e32 v94, v1, v1
	v_add_f32_e32 v2, v2, v66
	v_add_f32_e32 v10, v10, v74
	v_bfe_u32 v88, v2, 16, 1
	v_bfe_u32 v89, v10, 16, 1
	v_add3_u32 v2, v2, v88, s77
	v_add3_u32 v10, v10, v89, s77
	v_and_b32_e32 v2, s35, v2
	v_and_b32_e32 v10, s35, v10
	v_mul_f32_e32 v10, 0xbfb8aa3b, v10
	v_exp_f32_e32 v10, v10
	s_nop 0
	v_add_f32_e32 v10, 1.0, v10
	v_div_scale_f32 v88, s[6:7], v10, v10, 1.0
	v_rcp_f32_e32 v89, v88
	s_nop 0
	v_fma_f32 v90, -v88, v89, 1.0
	v_fmac_f32_e32 v89, v90, v89
	v_div_scale_f32 v90, vcc, 1.0, v10, 1.0
	v_mul_f32_e32 v91, v90, v89
	v_fma_f32 v92, -v88, v91, v90
	v_fmac_f32_e32 v91, v92, v89
	v_fma_f32 v88, -v88, v91, v90
	v_div_fmas_f32 v88, v88, v89, v91
	v_div_fixup_f32 v10, v88, v10, 1.0
	v_mul_f32_e32 v2, v10, v2
	v_fmac_f32_e32 v94, v2, v2
	v_add_f32_e32 v3, v3, v67
	v_add_f32_e32 v11, v11, v75
	v_bfe_u32 v88, v3, 16, 1
	v_bfe_u32 v89, v11, 16, 1
	v_add3_u32 v3, v3, v88, s77
	v_add3_u32 v11, v11, v89, s77
	v_and_b32_e32 v3, s35, v3
	v_and_b32_e32 v11, s35, v11
	v_mul_f32_e32 v11, 0xbfb8aa3b, v11
	v_exp_f32_e32 v11, v11
	s_nop 0
	v_add_f32_e32 v11, 1.0, v11
	v_div_scale_f32 v88, s[6:7], v11, v11, 1.0
	v_rcp_f32_e32 v89, v88
	s_nop 0
	v_fma_f32 v90, -v88, v89, 1.0
	v_fmac_f32_e32 v89, v90, v89
	v_div_scale_f32 v90, vcc, 1.0, v11, 1.0
	v_mul_f32_e32 v91, v90, v89
	v_fma_f32 v92, -v88, v91, v90
	v_fmac_f32_e32 v91, v92, v89
	v_fma_f32 v88, -v88, v91, v90
	v_div_fmas_f32 v88, v88, v89, v91
	v_div_fixup_f32 v11, v88, v11, 1.0
	v_mul_f32_e32 v3, v11, v3
	v_fmac_f32_e32 v94, v3, v3
	v_add_f32_e32 v4, v4, v68
	v_add_f32_e32 v12, v12, v76
	v_bfe_u32 v88, v4, 16, 1
	v_bfe_u32 v89, v12, 16, 1
	v_add3_u32 v4, v4, v88, s77
	v_add3_u32 v12, v12, v89, s77
	v_and_b32_e32 v4, s35, v4
	v_and_b32_e32 v12, s35, v12
	v_mul_f32_e32 v12, 0xbfb8aa3b, v12
	v_exp_f32_e32 v12, v12
	s_nop 0
	v_add_f32_e32 v12, 1.0, v12
	v_div_scale_f32 v88, s[6:7], v12, v12, 1.0
	v_rcp_f32_e32 v89, v88
	s_nop 0
	v_fma_f32 v90, -v88, v89, 1.0
	v_fmac_f32_e32 v89, v90, v89
	v_div_scale_f32 v90, vcc, 1.0, v12, 1.0
	v_mul_f32_e32 v91, v90, v89
	v_fma_f32 v92, -v88, v91, v90
	v_fmac_f32_e32 v91, v92, v89
	v_fma_f32 v88, -v88, v91, v90
	v_div_fmas_f32 v88, v88, v89, v91
	v_div_fixup_f32 v12, v88, v12, 1.0
	v_mul_f32_e32 v4, v12, v4
	v_fmac_f32_e32 v94, v4, v4
	v_add_f32_e32 v5, v5, v69
	v_add_f32_e32 v13, v13, v77
	v_bfe_u32 v88, v5, 16, 1
	v_bfe_u32 v89, v13, 16, 1
	v_add3_u32 v5, v5, v88, s77
	v_add3_u32 v13, v13, v89, s77
	v_and_b32_e32 v5, s35, v5
	v_and_b32_e32 v13, s35, v13
	v_mul_f32_e32 v13, 0xbfb8aa3b, v13
	v_exp_f32_e32 v13, v13
	s_nop 0
	v_add_f32_e32 v13, 1.0, v13
	v_div_scale_f32 v88, s[6:7], v13, v13, 1.0
	v_rcp_f32_e32 v89, v88
	s_nop 0
	v_fma_f32 v90, -v88, v89, 1.0
	v_fmac_f32_e32 v89, v90, v89
	v_div_scale_f32 v90, vcc, 1.0, v13, 1.0
	v_mul_f32_e32 v91, v90, v89
	v_fma_f32 v92, -v88, v91, v90
	v_fmac_f32_e32 v91, v92, v89
	v_fma_f32 v88, -v88, v91, v90
	v_div_fmas_f32 v88, v88, v89, v91
	v_div_fixup_f32 v13, v88, v13, 1.0
	v_mul_f32_e32 v5, v13, v5
	v_fmac_f32_e32 v94, v5, v5
	v_add_f32_e32 v6, v6, v70
	v_add_f32_e32 v14, v14, v78
	v_bfe_u32 v88, v6, 16, 1
	v_bfe_u32 v89, v14, 16, 1
	v_add3_u32 v6, v6, v88, s77
	v_add3_u32 v14, v14, v89, s77
	v_and_b32_e32 v6, s35, v6
	v_and_b32_e32 v14, s35, v14
	v_mul_f32_e32 v14, 0xbfb8aa3b, v14
	v_exp_f32_e32 v14, v14
	s_nop 0
	v_add_f32_e32 v14, 1.0, v14
	v_div_scale_f32 v88, s[6:7], v14, v14, 1.0
	v_rcp_f32_e32 v89, v88
	s_nop 0
	v_fma_f32 v90, -v88, v89, 1.0
	v_fmac_f32_e32 v89, v90, v89
	v_div_scale_f32 v90, vcc, 1.0, v14, 1.0
	v_mul_f32_e32 v91, v90, v89
	v_fma_f32 v92, -v88, v91, v90
	v_fmac_f32_e32 v91, v92, v89
	v_fma_f32 v88, -v88, v91, v90
	v_div_fmas_f32 v88, v88, v89, v91
	v_div_fixup_f32 v14, v88, v14, 1.0
	v_mul_f32_e32 v6, v14, v6
	v_fmac_f32_e32 v94, v6, v6
	v_add_f32_e32 v7, v7, v71
	v_add_f32_e32 v15, v15, v79
	v_bfe_u32 v88, v7, 16, 1
	v_bfe_u32 v89, v15, 16, 1
	v_add3_u32 v7, v7, v88, s77
	v_add3_u32 v15, v15, v89, s77
	v_and_b32_e32 v7, s35, v7
	v_and_b32_e32 v15, s35, v15
	v_mul_f32_e32 v15, 0xbfb8aa3b, v15
	v_exp_f32_e32 v15, v15
	s_nop 0
	v_add_f32_e32 v15, 1.0, v15
	v_div_scale_f32 v88, s[6:7], v15, v15, 1.0
	v_rcp_f32_e32 v89, v88
	s_nop 0
	v_fma_f32 v90, -v88, v89, 1.0
	v_fmac_f32_e32 v89, v90, v89
	v_div_scale_f32 v90, vcc, 1.0, v15, 1.0
	v_mul_f32_e32 v91, v90, v89
	v_fma_f32 v92, -v88, v91, v90
	v_fmac_f32_e32 v91, v92, v89
	v_fma_f32 v88, -v88, v91, v90
	v_div_fmas_f32 v88, v88, v89, v91
	v_div_fixup_f32 v15, v88, v15, 1.0
	v_mul_f32_e32 v7, v15, v7
	v_fmac_f32_e32 v94, v7, v7
	v_add_f32_e32 v16, v16, v64
	v_add_f32_e32 v24, v24, v72
	v_bfe_u32 v88, v16, 16, 1
	v_bfe_u32 v89, v24, 16, 1
	v_add3_u32 v16, v16, v88, s77
	v_add3_u32 v24, v24, v89, s77
	v_and_b32_e32 v16, s35, v16
	v_and_b32_e32 v24, s35, v24
	v_mul_f32_e32 v24, 0xbfb8aa3b, v24
	v_exp_f32_e32 v24, v24
	s_nop 0
	v_add_f32_e32 v24, 1.0, v24
	v_div_scale_f32 v88, s[6:7], v24, v24, 1.0
	v_rcp_f32_e32 v89, v88
	s_nop 0
	v_fma_f32 v90, -v88, v89, 1.0
	v_fmac_f32_e32 v89, v90, v89
	v_div_scale_f32 v90, vcc, 1.0, v24, 1.0
	v_mul_f32_e32 v91, v90, v89
	v_fma_f32 v92, -v88, v91, v90
	v_fmac_f32_e32 v91, v92, v89
	v_fma_f32 v88, -v88, v91, v90
	v_div_fmas_f32 v88, v88, v89, v91
	v_div_fixup_f32 v24, v88, v24, 1.0
	v_mul_f32_e32 v16, v24, v16
	v_fmac_f32_e32 v95, v16, v16
	v_add_f32_e32 v17, v17, v65
	v_add_f32_e32 v25, v25, v73
	v_bfe_u32 v88, v17, 16, 1
	v_bfe_u32 v89, v25, 16, 1
	v_add3_u32 v17, v17, v88, s77
	v_add3_u32 v25, v25, v89, s77
	v_and_b32_e32 v17, s35, v17
	v_and_b32_e32 v25, s35, v25
	v_mul_f32_e32 v25, 0xbfb8aa3b, v25
	v_exp_f32_e32 v25, v25
	s_nop 0
	v_add_f32_e32 v25, 1.0, v25
	v_div_scale_f32 v88, s[6:7], v25, v25, 1.0
	v_rcp_f32_e32 v89, v88
	s_nop 0
	v_fma_f32 v90, -v88, v89, 1.0
	v_fmac_f32_e32 v89, v90, v89
	v_div_scale_f32 v90, vcc, 1.0, v25, 1.0
	v_mul_f32_e32 v91, v90, v89
	v_fma_f32 v92, -v88, v91, v90
	v_fmac_f32_e32 v91, v92, v89
	v_fma_f32 v88, -v88, v91, v90
	v_div_fmas_f32 v88, v88, v89, v91
	v_div_fixup_f32 v25, v88, v25, 1.0
	v_mul_f32_e32 v17, v25, v17
	v_fmac_f32_e32 v95, v17, v17
	v_add_f32_e32 v18, v18, v66
	v_add_f32_e32 v26, v26, v74
	v_bfe_u32 v88, v18, 16, 1
	v_bfe_u32 v89, v26, 16, 1
	v_add3_u32 v18, v18, v88, s77
	v_add3_u32 v26, v26, v89, s77
	v_and_b32_e32 v18, s35, v18
	v_and_b32_e32 v26, s35, v26
	v_mul_f32_e32 v26, 0xbfb8aa3b, v26
	v_exp_f32_e32 v26, v26
	s_nop 0
	v_add_f32_e32 v26, 1.0, v26
	v_div_scale_f32 v88, s[6:7], v26, v26, 1.0
	v_rcp_f32_e32 v89, v88
	s_nop 0
	v_fma_f32 v90, -v88, v89, 1.0
	v_fmac_f32_e32 v89, v90, v89
	v_div_scale_f32 v90, vcc, 1.0, v26, 1.0
	v_mul_f32_e32 v91, v90, v89
	v_fma_f32 v92, -v88, v91, v90
	v_fmac_f32_e32 v91, v92, v89
	v_fma_f32 v88, -v88, v91, v90
	v_div_fmas_f32 v88, v88, v89, v91
	v_div_fixup_f32 v26, v88, v26, 1.0
	v_mul_f32_e32 v18, v26, v18
	v_fmac_f32_e32 v95, v18, v18
	v_add_f32_e32 v19, v19, v67
	v_add_f32_e32 v27, v27, v75
	v_bfe_u32 v88, v19, 16, 1
	v_bfe_u32 v89, v27, 16, 1
	v_add3_u32 v19, v19, v88, s77
	v_add3_u32 v27, v27, v89, s77
	v_and_b32_e32 v19, s35, v19
	v_and_b32_e32 v27, s35, v27
	v_mul_f32_e32 v27, 0xbfb8aa3b, v27
	v_exp_f32_e32 v27, v27
	s_nop 0
	v_add_f32_e32 v27, 1.0, v27
	v_div_scale_f32 v88, s[6:7], v27, v27, 1.0
	v_rcp_f32_e32 v89, v88
	s_nop 0
	v_fma_f32 v90, -v88, v89, 1.0
	v_fmac_f32_e32 v89, v90, v89
	v_div_scale_f32 v90, vcc, 1.0, v27, 1.0
	v_mul_f32_e32 v91, v90, v89
	v_fma_f32 v92, -v88, v91, v90
	v_fmac_f32_e32 v91, v92, v89
	v_fma_f32 v88, -v88, v91, v90
	v_div_fmas_f32 v88, v88, v89, v91
	v_div_fixup_f32 v27, v88, v27, 1.0
	v_mul_f32_e32 v19, v27, v19
	v_fmac_f32_e32 v95, v19, v19
	v_add_f32_e32 v20, v20, v68
	v_add_f32_e32 v28, v28, v76
	v_bfe_u32 v88, v20, 16, 1
	v_bfe_u32 v89, v28, 16, 1
	v_add3_u32 v20, v20, v88, s77
	v_add3_u32 v28, v28, v89, s77
	v_and_b32_e32 v20, s35, v20
	v_and_b32_e32 v28, s35, v28
	v_mul_f32_e32 v28, 0xbfb8aa3b, v28
	v_exp_f32_e32 v28, v28
	s_nop 0
	v_add_f32_e32 v28, 1.0, v28
	v_div_scale_f32 v88, s[6:7], v28, v28, 1.0
	v_rcp_f32_e32 v89, v88
	s_nop 0
	v_fma_f32 v90, -v88, v89, 1.0
	v_fmac_f32_e32 v89, v90, v89
	v_div_scale_f32 v90, vcc, 1.0, v28, 1.0
	v_mul_f32_e32 v91, v90, v89
	v_fma_f32 v92, -v88, v91, v90
	v_fmac_f32_e32 v91, v92, v89
	v_fma_f32 v88, -v88, v91, v90
	v_div_fmas_f32 v88, v88, v89, v91
	v_div_fixup_f32 v28, v88, v28, 1.0
	v_mul_f32_e32 v20, v28, v20
	v_fmac_f32_e32 v95, v20, v20
	v_add_f32_e32 v21, v21, v69
	v_add_f32_e32 v29, v29, v77
	v_bfe_u32 v88, v21, 16, 1
	v_bfe_u32 v89, v29, 16, 1
	v_add3_u32 v21, v21, v88, s77
	v_add3_u32 v29, v29, v89, s77
	v_and_b32_e32 v21, s35, v21
	v_and_b32_e32 v29, s35, v29
	v_mul_f32_e32 v29, 0xbfb8aa3b, v29
	v_exp_f32_e32 v29, v29
	s_nop 0
	v_add_f32_e32 v29, 1.0, v29
	v_div_scale_f32 v88, s[6:7], v29, v29, 1.0
	v_rcp_f32_e32 v89, v88
	s_nop 0
	v_fma_f32 v90, -v88, v89, 1.0
	v_fmac_f32_e32 v89, v90, v89
	v_div_scale_f32 v90, vcc, 1.0, v29, 1.0
	v_mul_f32_e32 v91, v90, v89
	v_fma_f32 v92, -v88, v91, v90
	v_fmac_f32_e32 v91, v92, v89
	v_fma_f32 v88, -v88, v91, v90
	v_div_fmas_f32 v88, v88, v89, v91
	v_div_fixup_f32 v29, v88, v29, 1.0
	v_mul_f32_e32 v21, v29, v21
	v_fmac_f32_e32 v95, v21, v21
	v_add_f32_e32 v22, v22, v70
	v_add_f32_e32 v30, v30, v78
	v_bfe_u32 v88, v22, 16, 1
	v_bfe_u32 v89, v30, 16, 1
	v_add3_u32 v22, v22, v88, s77
	v_add3_u32 v30, v30, v89, s77
	v_and_b32_e32 v22, s35, v22
	v_and_b32_e32 v30, s35, v30
	v_mul_f32_e32 v30, 0xbfb8aa3b, v30
	v_exp_f32_e32 v30, v30
	s_nop 0
	v_add_f32_e32 v30, 1.0, v30
	v_div_scale_f32 v88, s[6:7], v30, v30, 1.0
	v_rcp_f32_e32 v89, v88
	s_nop 0
	v_fma_f32 v90, -v88, v89, 1.0
	v_fmac_f32_e32 v89, v90, v89
	v_div_scale_f32 v90, vcc, 1.0, v30, 1.0
	v_mul_f32_e32 v91, v90, v89
	v_fma_f32 v92, -v88, v91, v90
	v_fmac_f32_e32 v91, v92, v89
	v_fma_f32 v88, -v88, v91, v90
	v_div_fmas_f32 v88, v88, v89, v91
	v_div_fixup_f32 v30, v88, v30, 1.0
	v_mul_f32_e32 v22, v30, v22
	v_fmac_f32_e32 v95, v22, v22
	v_add_f32_e32 v23, v23, v71
	v_add_f32_e32 v31, v31, v79
	v_bfe_u32 v88, v23, 16, 1
	v_bfe_u32 v89, v31, 16, 1
	v_add3_u32 v23, v23, v88, s77
	v_add3_u32 v31, v31, v89, s77
	v_and_b32_e32 v23, s35, v23
	v_and_b32_e32 v31, s35, v31
	v_mul_f32_e32 v31, 0xbfb8aa3b, v31
	v_exp_f32_e32 v31, v31
	s_nop 0
	v_add_f32_e32 v31, 1.0, v31
	v_div_scale_f32 v88, s[6:7], v31, v31, 1.0
	v_rcp_f32_e32 v89, v88
	s_nop 0
	v_fma_f32 v90, -v88, v89, 1.0
	v_fmac_f32_e32 v89, v90, v89
	v_div_scale_f32 v90, vcc, 1.0, v31, 1.0
	v_mul_f32_e32 v91, v90, v89
	v_fma_f32 v92, -v88, v91, v90
	v_fmac_f32_e32 v91, v92, v89
	v_fma_f32 v88, -v88, v91, v90
	v_div_fmas_f32 v88, v88, v89, v91
	v_div_fixup_f32 v31, v88, v31, 1.0
	v_mul_f32_e32 v23, v31, v23
	v_fmac_f32_e32 v95, v23, v23
	v_add_f32_e32 v32, v32, v64
	v_add_f32_e32 v40, v40, v72
	v_bfe_u32 v88, v32, 16, 1
	v_bfe_u32 v89, v40, 16, 1
	v_add3_u32 v32, v32, v88, s77
	v_add3_u32 v40, v40, v89, s77
	v_and_b32_e32 v32, s35, v32
	v_and_b32_e32 v40, s35, v40
	v_mul_f32_e32 v40, 0xbfb8aa3b, v40
	v_exp_f32_e32 v40, v40
	s_nop 0
	v_add_f32_e32 v40, 1.0, v40
	v_div_scale_f32 v88, s[6:7], v40, v40, 1.0
	v_rcp_f32_e32 v89, v88
	s_nop 0
	v_fma_f32 v90, -v88, v89, 1.0
	v_fmac_f32_e32 v89, v90, v89
	v_div_scale_f32 v90, vcc, 1.0, v40, 1.0
	v_mul_f32_e32 v91, v90, v89
	v_fma_f32 v92, -v88, v91, v90
	v_fmac_f32_e32 v91, v92, v89
	v_fma_f32 v88, -v88, v91, v90
	v_div_fmas_f32 v88, v88, v89, v91
	v_div_fixup_f32 v40, v88, v40, 1.0
	v_mul_f32_e32 v32, v40, v32
	v_fmac_f32_e32 v215, v32, v32
	v_add_f32_e32 v33, v33, v65
	v_add_f32_e32 v41, v41, v73
	v_bfe_u32 v88, v33, 16, 1
	v_bfe_u32 v89, v41, 16, 1
	v_add3_u32 v33, v33, v88, s77
	v_add3_u32 v41, v41, v89, s77
	v_and_b32_e32 v33, s35, v33
	v_and_b32_e32 v41, s35, v41
	v_mul_f32_e32 v41, 0xbfb8aa3b, v41
	v_exp_f32_e32 v41, v41
	s_nop 0
	v_add_f32_e32 v41, 1.0, v41
	v_div_scale_f32 v88, s[6:7], v41, v41, 1.0
	v_rcp_f32_e32 v89, v88
	s_nop 0
	v_fma_f32 v90, -v88, v89, 1.0
	v_fmac_f32_e32 v89, v90, v89
	v_div_scale_f32 v90, vcc, 1.0, v41, 1.0
	v_mul_f32_e32 v91, v90, v89
	v_fma_f32 v92, -v88, v91, v90
	v_fmac_f32_e32 v91, v92, v89
	v_fma_f32 v88, -v88, v91, v90
	v_div_fmas_f32 v88, v88, v89, v91
	v_div_fixup_f32 v41, v88, v41, 1.0
	v_mul_f32_e32 v33, v41, v33
	v_fmac_f32_e32 v215, v33, v33
	v_add_f32_e32 v34, v34, v66
	v_add_f32_e32 v42, v42, v74
	v_bfe_u32 v88, v34, 16, 1
	v_bfe_u32 v89, v42, 16, 1
	v_add3_u32 v34, v34, v88, s77
	v_add3_u32 v42, v42, v89, s77
	v_and_b32_e32 v34, s35, v34
	v_and_b32_e32 v42, s35, v42
	v_mul_f32_e32 v42, 0xbfb8aa3b, v42
	v_exp_f32_e32 v42, v42
	s_nop 0
	v_add_f32_e32 v42, 1.0, v42
	v_div_scale_f32 v88, s[6:7], v42, v42, 1.0
	v_rcp_f32_e32 v89, v88
	s_nop 0
	v_fma_f32 v90, -v88, v89, 1.0
	v_fmac_f32_e32 v89, v90, v89
	v_div_scale_f32 v90, vcc, 1.0, v42, 1.0
	v_mul_f32_e32 v91, v90, v89
	v_fma_f32 v92, -v88, v91, v90
	v_fmac_f32_e32 v91, v92, v89
	v_fma_f32 v88, -v88, v91, v90
	v_div_fmas_f32 v88, v88, v89, v91
	v_div_fixup_f32 v42, v88, v42, 1.0
	v_mul_f32_e32 v34, v42, v34
	v_fmac_f32_e32 v215, v34, v34
	v_add_f32_e32 v35, v35, v67
	v_add_f32_e32 v43, v43, v75
	v_bfe_u32 v88, v35, 16, 1
	v_bfe_u32 v89, v43, 16, 1
	v_add3_u32 v35, v35, v88, s77
	v_add3_u32 v43, v43, v89, s77
	v_and_b32_e32 v35, s35, v35
	v_and_b32_e32 v43, s35, v43
	v_mul_f32_e32 v43, 0xbfb8aa3b, v43
	v_exp_f32_e32 v43, v43
	s_nop 0
	v_add_f32_e32 v43, 1.0, v43
	v_div_scale_f32 v88, s[6:7], v43, v43, 1.0
	v_rcp_f32_e32 v89, v88
	s_nop 0
	v_fma_f32 v90, -v88, v89, 1.0
	v_fmac_f32_e32 v89, v90, v89
	v_div_scale_f32 v90, vcc, 1.0, v43, 1.0
	v_mul_f32_e32 v91, v90, v89
	v_fma_f32 v92, -v88, v91, v90
	v_fmac_f32_e32 v91, v92, v89
	v_fma_f32 v88, -v88, v91, v90
	v_div_fmas_f32 v88, v88, v89, v91
	v_div_fixup_f32 v43, v88, v43, 1.0
	v_mul_f32_e32 v35, v43, v35
	v_fmac_f32_e32 v215, v35, v35
	v_add_f32_e32 v36, v36, v68
	v_add_f32_e32 v44, v44, v76
	v_bfe_u32 v88, v36, 16, 1
	v_bfe_u32 v89, v44, 16, 1
	v_add3_u32 v36, v36, v88, s77
	v_add3_u32 v44, v44, v89, s77
	v_and_b32_e32 v36, s35, v36
	v_and_b32_e32 v44, s35, v44
	v_mul_f32_e32 v44, 0xbfb8aa3b, v44
	v_exp_f32_e32 v44, v44
	s_nop 0
	v_add_f32_e32 v44, 1.0, v44
	v_div_scale_f32 v88, s[6:7], v44, v44, 1.0
	v_rcp_f32_e32 v89, v88
	s_nop 0
	v_fma_f32 v90, -v88, v89, 1.0
	v_fmac_f32_e32 v89, v90, v89
	v_div_scale_f32 v90, vcc, 1.0, v44, 1.0
	v_mul_f32_e32 v91, v90, v89
	v_fma_f32 v92, -v88, v91, v90
	v_fmac_f32_e32 v91, v92, v89
	v_fma_f32 v88, -v88, v91, v90
	v_div_fmas_f32 v88, v88, v89, v91
	v_div_fixup_f32 v44, v88, v44, 1.0
	v_mul_f32_e32 v36, v44, v36
	v_fmac_f32_e32 v215, v36, v36
	v_add_f32_e32 v37, v37, v69
	v_add_f32_e32 v45, v45, v77
	v_bfe_u32 v88, v37, 16, 1
	v_bfe_u32 v89, v45, 16, 1
	v_add3_u32 v37, v37, v88, s77
	v_add3_u32 v45, v45, v89, s77
	v_and_b32_e32 v37, s35, v37
	v_and_b32_e32 v45, s35, v45
	v_mul_f32_e32 v45, 0xbfb8aa3b, v45
	v_exp_f32_e32 v45, v45
	s_nop 0
	v_add_f32_e32 v45, 1.0, v45
	v_div_scale_f32 v88, s[6:7], v45, v45, 1.0
	v_rcp_f32_e32 v89, v88
	s_nop 0
	v_fma_f32 v90, -v88, v89, 1.0
	v_fmac_f32_e32 v89, v90, v89
	v_div_scale_f32 v90, vcc, 1.0, v45, 1.0
	v_mul_f32_e32 v91, v90, v89
	v_fma_f32 v92, -v88, v91, v90
	v_fmac_f32_e32 v91, v92, v89
	v_fma_f32 v88, -v88, v91, v90
	v_div_fmas_f32 v88, v88, v89, v91
	v_div_fixup_f32 v45, v88, v45, 1.0
	v_mul_f32_e32 v37, v45, v37
	v_fmac_f32_e32 v215, v37, v37
	v_add_f32_e32 v38, v38, v70
	v_add_f32_e32 v46, v46, v78
	v_bfe_u32 v88, v38, 16, 1
	v_bfe_u32 v89, v46, 16, 1
	v_add3_u32 v38, v38, v88, s77
	v_add3_u32 v46, v46, v89, s77
	v_and_b32_e32 v38, s35, v38
	v_and_b32_e32 v46, s35, v46
	v_mul_f32_e32 v46, 0xbfb8aa3b, v46
	v_exp_f32_e32 v46, v46
	s_nop 0
	v_add_f32_e32 v46, 1.0, v46
	v_div_scale_f32 v88, s[6:7], v46, v46, 1.0
	v_rcp_f32_e32 v89, v88
	s_nop 0
	v_fma_f32 v90, -v88, v89, 1.0
	v_fmac_f32_e32 v89, v90, v89
	v_div_scale_f32 v90, vcc, 1.0, v46, 1.0
	v_mul_f32_e32 v91, v90, v89
	v_fma_f32 v92, -v88, v91, v90
	v_fmac_f32_e32 v91, v92, v89
	v_fma_f32 v88, -v88, v91, v90
	v_div_fmas_f32 v88, v88, v89, v91
	v_div_fixup_f32 v46, v88, v46, 1.0
	v_mul_f32_e32 v38, v46, v38
	v_fmac_f32_e32 v215, v38, v38
	v_add_f32_e32 v39, v39, v71
	v_add_f32_e32 v47, v47, v79
	v_bfe_u32 v88, v39, 16, 1
	v_bfe_u32 v89, v47, 16, 1
	v_add3_u32 v39, v39, v88, s77
	v_add3_u32 v47, v47, v89, s77
	v_and_b32_e32 v39, s35, v39
	v_and_b32_e32 v47, s35, v47
	v_mul_f32_e32 v47, 0xbfb8aa3b, v47
	v_exp_f32_e32 v47, v47
	s_nop 0
	v_add_f32_e32 v47, 1.0, v47
	v_div_scale_f32 v88, s[6:7], v47, v47, 1.0
	v_rcp_f32_e32 v89, v88
	s_nop 0
	v_fma_f32 v90, -v88, v89, 1.0
	v_fmac_f32_e32 v89, v90, v89
	v_div_scale_f32 v90, vcc, 1.0, v47, 1.0
	v_mul_f32_e32 v91, v90, v89
	v_fma_f32 v92, -v88, v91, v90
	v_fmac_f32_e32 v91, v92, v89
	v_fma_f32 v88, -v88, v91, v90
	v_div_fmas_f32 v88, v88, v89, v91
	v_div_fixup_f32 v47, v88, v47, 1.0
	v_mul_f32_e32 v39, v47, v39
	v_fmac_f32_e32 v215, v39, v39
	v_add_f32_e32 v48, v48, v64
	v_add_f32_e32 v56, v56, v72
	v_bfe_u32 v88, v48, 16, 1
	v_bfe_u32 v89, v56, 16, 1
	v_add3_u32 v48, v48, v88, s77
	v_add3_u32 v56, v56, v89, s77
	v_and_b32_e32 v48, s35, v48
	v_and_b32_e32 v56, s35, v56
	v_mul_f32_e32 v56, 0xbfb8aa3b, v56
	v_exp_f32_e32 v56, v56
	s_nop 0
	v_add_f32_e32 v56, 1.0, v56
	v_div_scale_f32 v88, s[6:7], v56, v56, 1.0
	v_rcp_f32_e32 v89, v88
	s_nop 0
	v_fma_f32 v90, -v88, v89, 1.0
	v_fmac_f32_e32 v89, v90, v89
	v_div_scale_f32 v90, vcc, 1.0, v56, 1.0
	v_mul_f32_e32 v91, v90, v89
	v_fma_f32 v92, -v88, v91, v90
	v_fmac_f32_e32 v91, v92, v89
	v_fma_f32 v88, -v88, v91, v90
	v_div_fmas_f32 v88, v88, v89, v91
	v_div_fixup_f32 v56, v88, v56, 1.0
	v_mul_f32_e32 v48, v56, v48
	v_fmac_f32_e32 v216, v48, v48
	v_add_f32_e32 v49, v49, v65
	v_add_f32_e32 v57, v57, v73
	v_bfe_u32 v88, v49, 16, 1
	v_bfe_u32 v89, v57, 16, 1
	v_add3_u32 v49, v49, v88, s77
	v_add3_u32 v57, v57, v89, s77
	v_and_b32_e32 v49, s35, v49
	v_and_b32_e32 v57, s35, v57
	v_mul_f32_e32 v57, 0xbfb8aa3b, v57
	v_exp_f32_e32 v57, v57
	s_nop 0
	v_add_f32_e32 v57, 1.0, v57
	v_div_scale_f32 v88, s[6:7], v57, v57, 1.0
	v_rcp_f32_e32 v89, v88
	s_nop 0
	v_fma_f32 v90, -v88, v89, 1.0
	v_fmac_f32_e32 v89, v90, v89
	v_div_scale_f32 v90, vcc, 1.0, v57, 1.0
	v_mul_f32_e32 v91, v90, v89
	v_fma_f32 v92, -v88, v91, v90
	v_fmac_f32_e32 v91, v92, v89
	v_fma_f32 v88, -v88, v91, v90
	v_div_fmas_f32 v88, v88, v89, v91
	v_div_fixup_f32 v57, v88, v57, 1.0
	v_mul_f32_e32 v49, v57, v49
	v_fmac_f32_e32 v216, v49, v49
	v_add_f32_e32 v50, v50, v66
	v_add_f32_e32 v58, v58, v74
	v_bfe_u32 v88, v50, 16, 1
	v_bfe_u32 v89, v58, 16, 1
	v_add3_u32 v50, v50, v88, s77
	v_add3_u32 v58, v58, v89, s77
	v_and_b32_e32 v50, s35, v50
	v_and_b32_e32 v58, s35, v58
	v_mul_f32_e32 v58, 0xbfb8aa3b, v58
	v_exp_f32_e32 v58, v58
	s_nop 0
	v_add_f32_e32 v58, 1.0, v58
	v_div_scale_f32 v88, s[6:7], v58, v58, 1.0
	v_rcp_f32_e32 v89, v88
	s_nop 0
	v_fma_f32 v90, -v88, v89, 1.0
	v_fmac_f32_e32 v89, v90, v89
	v_div_scale_f32 v90, vcc, 1.0, v58, 1.0
	v_mul_f32_e32 v91, v90, v89
	v_fma_f32 v92, -v88, v91, v90
	v_fmac_f32_e32 v91, v92, v89
	v_fma_f32 v88, -v88, v91, v90
	v_div_fmas_f32 v88, v88, v89, v91
	v_div_fixup_f32 v58, v88, v58, 1.0
	v_mul_f32_e32 v50, v58, v50
	v_fmac_f32_e32 v216, v50, v50
	v_add_f32_e32 v51, v51, v67
	v_add_f32_e32 v59, v59, v75
	v_bfe_u32 v88, v51, 16, 1
	v_bfe_u32 v89, v59, 16, 1
	v_add3_u32 v51, v51, v88, s77
	v_add3_u32 v59, v59, v89, s77
	v_and_b32_e32 v51, s35, v51
	v_and_b32_e32 v59, s35, v59
	v_mul_f32_e32 v59, 0xbfb8aa3b, v59
	v_exp_f32_e32 v59, v59
	s_nop 0
	v_add_f32_e32 v59, 1.0, v59
	v_div_scale_f32 v88, s[6:7], v59, v59, 1.0
	v_rcp_f32_e32 v89, v88
	s_nop 0
	v_fma_f32 v90, -v88, v89, 1.0
	v_fmac_f32_e32 v89, v90, v89
	v_div_scale_f32 v90, vcc, 1.0, v59, 1.0
	v_mul_f32_e32 v91, v90, v89
	v_fma_f32 v92, -v88, v91, v90
	v_fmac_f32_e32 v91, v92, v89
	v_fma_f32 v88, -v88, v91, v90
	v_div_fmas_f32 v88, v88, v89, v91
	v_div_fixup_f32 v59, v88, v59, 1.0
	v_mul_f32_e32 v51, v59, v51
	v_fmac_f32_e32 v216, v51, v51
	v_add_f32_e32 v52, v52, v68
	v_add_f32_e32 v60, v60, v76
	v_bfe_u32 v88, v52, 16, 1
	v_bfe_u32 v89, v60, 16, 1
	v_add3_u32 v52, v52, v88, s77
	v_add3_u32 v60, v60, v89, s77
	v_and_b32_e32 v52, s35, v52
	v_and_b32_e32 v60, s35, v60
	v_mul_f32_e32 v60, 0xbfb8aa3b, v60
	v_exp_f32_e32 v60, v60
	s_nop 0
	v_add_f32_e32 v60, 1.0, v60
	v_div_scale_f32 v88, s[6:7], v60, v60, 1.0
	v_rcp_f32_e32 v89, v88
	s_nop 0
	v_fma_f32 v90, -v88, v89, 1.0
	v_fmac_f32_e32 v89, v90, v89
	v_div_scale_f32 v90, vcc, 1.0, v60, 1.0
	v_mul_f32_e32 v91, v90, v89
	v_fma_f32 v92, -v88, v91, v90
	v_fmac_f32_e32 v91, v92, v89
	v_fma_f32 v88, -v88, v91, v90
	v_div_fmas_f32 v88, v88, v89, v91
	v_div_fixup_f32 v60, v88, v60, 1.0
	v_mul_f32_e32 v52, v60, v52
	v_fmac_f32_e32 v216, v52, v52
	v_add_f32_e32 v53, v53, v69
	v_add_f32_e32 v61, v61, v77
	v_bfe_u32 v88, v53, 16, 1
	v_bfe_u32 v89, v61, 16, 1
	v_add3_u32 v53, v53, v88, s77
	v_add3_u32 v61, v61, v89, s77
	v_and_b32_e32 v53, s35, v53
	v_and_b32_e32 v61, s35, v61
	v_mul_f32_e32 v61, 0xbfb8aa3b, v61
	v_exp_f32_e32 v61, v61
	s_nop 0
	v_add_f32_e32 v61, 1.0, v61
	v_div_scale_f32 v88, s[6:7], v61, v61, 1.0
	v_rcp_f32_e32 v89, v88
	s_nop 0
	v_fma_f32 v90, -v88, v89, 1.0
	v_fmac_f32_e32 v89, v90, v89
	v_div_scale_f32 v90, vcc, 1.0, v61, 1.0
	v_mul_f32_e32 v91, v90, v89
	v_fma_f32 v92, -v88, v91, v90
	v_fmac_f32_e32 v91, v92, v89
	v_fma_f32 v88, -v88, v91, v90
	v_div_fmas_f32 v88, v88, v89, v91
	v_div_fixup_f32 v61, v88, v61, 1.0
	v_mul_f32_e32 v53, v61, v53
	v_fmac_f32_e32 v216, v53, v53
	v_add_f32_e32 v54, v54, v70
	v_add_f32_e32 v62, v62, v78
	v_bfe_u32 v88, v54, 16, 1
	v_bfe_u32 v89, v62, 16, 1
	v_add3_u32 v54, v54, v88, s77
	v_add3_u32 v62, v62, v89, s77
	v_and_b32_e32 v54, s35, v54
	v_and_b32_e32 v62, s35, v62
	v_mul_f32_e32 v62, 0xbfb8aa3b, v62
	v_exp_f32_e32 v62, v62
	s_nop 0
	v_add_f32_e32 v62, 1.0, v62
	v_div_scale_f32 v88, s[6:7], v62, v62, 1.0
	v_rcp_f32_e32 v89, v88
	s_nop 0
	v_fma_f32 v90, -v88, v89, 1.0
	v_fmac_f32_e32 v89, v90, v89
	v_div_scale_f32 v90, vcc, 1.0, v62, 1.0
	v_mul_f32_e32 v91, v90, v89
	v_fma_f32 v92, -v88, v91, v90
	v_fmac_f32_e32 v91, v92, v89
	v_fma_f32 v88, -v88, v91, v90
	v_div_fmas_f32 v88, v88, v89, v91
	v_div_fixup_f32 v62, v88, v62, 1.0
	v_mul_f32_e32 v54, v62, v54
	v_fmac_f32_e32 v216, v54, v54
	v_add_f32_e32 v55, v55, v71
	v_add_f32_e32 v63, v63, v79
	v_bfe_u32 v88, v55, 16, 1
	v_bfe_u32 v89, v63, 16, 1
	v_add3_u32 v55, v55, v88, s77
	v_add3_u32 v63, v63, v89, s77
	v_and_b32_e32 v55, s35, v55
	v_and_b32_e32 v63, s35, v63
	v_mul_f32_e32 v63, 0xbfb8aa3b, v63
	v_exp_f32_e32 v63, v63
	s_nop 0
	v_add_f32_e32 v63, 1.0, v63
	v_div_scale_f32 v88, s[6:7], v63, v63, 1.0
	v_rcp_f32_e32 v89, v88
	s_nop 0
	v_fma_f32 v90, -v88, v89, 1.0
	v_fmac_f32_e32 v89, v90, v89
	v_div_scale_f32 v90, vcc, 1.0, v63, 1.0
	v_mul_f32_e32 v91, v90, v89
	v_fma_f32 v92, -v88, v91, v90
	v_fmac_f32_e32 v91, v92, v89
	v_fma_f32 v88, -v88, v91, v90
	v_div_fmas_f32 v88, v88, v89, v91
	v_div_fixup_f32 v63, v88, v63, 1.0
	v_mul_f32_e32 v55, v63, v55
	v_fmac_f32_e32 v216, v55, v55
	ds_write_b32 v211, v94 offset:0
	ds_write_b32 v211, v95 offset:2304
	ds_write_b32 v211, v215 offset:4608
	ds_write_b32 v211, v216 offset:6912
	s_waitcnt lgkmcnt(0)
	s_barrier
	s_lshl_b32 s0, s22, 3
	s_add_i32 s0, s0, s16
	s_lshl_b32 s0, s0, 9
	s_lshl_b32 s1, s22, 10
	s_add_i32 s1, s1, 0x10000
	s_add_u32 s6, s0, 0xa300000
	s_add_u32 s6, s4, s6
	s_addc_u32 s7, s5, 0
	s_add_i32 m0, s1, 0x0
	s_nop 0
	global_load_lds_dwordx4 v132, s[6:7]
	s_add_u32 s6, s6, 0x80
	s_addc_u32 s7, s7, 0
	s_add_i32 m0, s1, 0x2000
	s_nop 0
	global_load_lds_dwordx4 v132, s[6:7]
	s_add_u32 s6, s6, 0x80
	s_addc_u32 s7, s7, 0
	s_add_i32 m0, s1, 0x4000
	s_nop 0
	global_load_lds_dwordx4 v132, s[6:7]
	s_add_u32 s6, s6, 0x80
	s_addc_u32 s7, s7, 0
	s_add_i32 m0, s1, 0x6000
	s_nop 0
	global_load_lds_dwordx4 v132, s[6:7]
	ds_read_b128 v[96:99], v212 offset:0
	ds_read_b128 v[100:103], v212 offset:16
	ds_read_b128 v[104:107], v212 offset:32
	ds_read_b128 v[108:111], v212 offset:48
	s_waitcnt lgkmcnt(0)
	v_add_f32_e32 v96, v96, v100
	v_add_f32_e32 v97, v97, v101
	v_add_f32_e32 v98, v98, v102
	v_add_f32_e32 v99, v99, v103
	v_add_f32_e32 v96, v96, v104
	v_add_f32_e32 v97, v97, v105
	v_add_f32_e32 v98, v98, v106
	v_add_f32_e32 v99, v99, v107
	v_add_f32_e32 v96, v96, v108
	v_add_f32_e32 v97, v97, v109
	v_add_f32_e32 v98, v98, v110
	v_add_f32_e32 v99, v99, v111
	v_add_f32_e32 v96, v96, v97
	v_add_f32_e32 v98, v98, v99
	v_add_f32_e32 v94, v96, v98
	ds_read_b128 v[96:99], v212 offset:64
	ds_read_b128 v[100:103], v212 offset:80
	ds_read_b128 v[104:107], v212 offset:96
	ds_read_b128 v[108:111], v212 offset:112
	s_waitcnt lgkmcnt(0)
	v_add_f32_e32 v96, v96, v100
	v_add_f32_e32 v97, v97, v101
	v_add_f32_e32 v98, v98, v102
	v_add_f32_e32 v99, v99, v103
	v_add_f32_e32 v96, v96, v104
	v_add_f32_e32 v97, v97, v105
	v_add_f32_e32 v98, v98, v106
	v_add_f32_e32 v99, v99, v107
	v_add_f32_e32 v96, v96, v108
	v_add_f32_e32 v97, v97, v109
	v_add_f32_e32 v98, v98, v110
	v_add_f32_e32 v99, v99, v111
	v_add_f32_e32 v96, v96, v97
	v_add_f32_e32 v98, v98, v99
	v_add_f32_e32 v96, v96, v98
	v_add_f32_e32 v94, v94, v96
	ds_read_b128 v[96:99], v212 offset:2304
	ds_read_b128 v[100:103], v212 offset:2320
	ds_read_b128 v[104:107], v212 offset:2336
	ds_read_b128 v[108:111], v212 offset:2352
	s_waitcnt lgkmcnt(0)
	v_add_f32_e32 v96, v96, v100
	v_add_f32_e32 v97, v97, v101
	v_add_f32_e32 v98, v98, v102
	v_add_f32_e32 v99, v99, v103
	v_add_f32_e32 v96, v96, v104
	v_add_f32_e32 v97, v97, v105
	v_add_f32_e32 v98, v98, v106
	v_add_f32_e32 v99, v99, v107
	v_add_f32_e32 v96, v96, v108
	v_add_f32_e32 v97, v97, v109
	v_add_f32_e32 v98, v98, v110
	v_add_f32_e32 v99, v99, v111
	v_add_f32_e32 v96, v96, v97
	v_add_f32_e32 v98, v98, v99
	v_add_f32_e32 v95, v96, v98
	ds_read_b128 v[96:99], v212 offset:2368
	ds_read_b128 v[100:103], v212 offset:2384
	ds_read_b128 v[104:107], v212 offset:2400
	ds_read_b128 v[108:111], v212 offset:2416
	s_waitcnt lgkmcnt(0)
	v_add_f32_e32 v96, v96, v100
	v_add_f32_e32 v97, v97, v101
	v_add_f32_e32 v98, v98, v102
	v_add_f32_e32 v99, v99, v103
	v_add_f32_e32 v96, v96, v104
	v_add_f32_e32 v97, v97, v105
	v_add_f32_e32 v98, v98, v106
	v_add_f32_e32 v99, v99, v107
	v_add_f32_e32 v96, v96, v108
	v_add_f32_e32 v97, v97, v109
	v_add_f32_e32 v98, v98, v110
	v_add_f32_e32 v99, v99, v111
	v_add_f32_e32 v96, v96, v97
	v_add_f32_e32 v98, v98, v99
	v_add_f32_e32 v96, v96, v98
	v_add_f32_e32 v95, v95, v96
	ds_read_b128 v[96:99], v212 offset:4608
	ds_read_b128 v[100:103], v212 offset:4624
	ds_read_b128 v[104:107], v212 offset:4640
	ds_read_b128 v[108:111], v212 offset:4656
	s_waitcnt lgkmcnt(0)
	v_add_f32_e32 v96, v96, v100
	v_add_f32_e32 v97, v97, v101
	v_add_f32_e32 v98, v98, v102
	v_add_f32_e32 v99, v99, v103
	v_add_f32_e32 v96, v96, v104
	v_add_f32_e32 v97, v97, v105
	v_add_f32_e32 v98, v98, v106
	v_add_f32_e32 v99, v99, v107
	v_add_f32_e32 v96, v96, v108
	v_add_f32_e32 v97, v97, v109
	v_add_f32_e32 v98, v98, v110
	v_add_f32_e32 v99, v99, v111
	v_add_f32_e32 v96, v96, v97
	v_add_f32_e32 v98, v98, v99
	v_add_f32_e32 v215, v96, v98
	ds_read_b128 v[96:99], v212 offset:4672
	ds_read_b128 v[100:103], v212 offset:4688
	ds_read_b128 v[104:107], v212 offset:4704
	ds_read_b128 v[108:111], v212 offset:4720
	s_waitcnt lgkmcnt(0)
	v_add_f32_e32 v96, v96, v100
	v_add_f32_e32 v97, v97, v101
	v_add_f32_e32 v98, v98, v102
	v_add_f32_e32 v99, v99, v103
	v_add_f32_e32 v96, v96, v104
	v_add_f32_e32 v97, v97, v105
	v_add_f32_e32 v98, v98, v106
	v_add_f32_e32 v99, v99, v107
	v_add_f32_e32 v96, v96, v108
	v_add_f32_e32 v97, v97, v109
	v_add_f32_e32 v98, v98, v110
	v_add_f32_e32 v99, v99, v111
	v_add_f32_e32 v96, v96, v97
	v_add_f32_e32 v98, v98, v99
	v_add_f32_e32 v96, v96, v98
	v_add_f32_e32 v215, v215, v96
	ds_read_b128 v[96:99], v212 offset:6912
	ds_read_b128 v[100:103], v212 offset:6928
	ds_read_b128 v[104:107], v212 offset:6944
	ds_read_b128 v[108:111], v212 offset:6960
	s_waitcnt lgkmcnt(0)
	v_add_f32_e32 v96, v96, v100
	v_add_f32_e32 v97, v97, v101
	v_add_f32_e32 v98, v98, v102
	v_add_f32_e32 v99, v99, v103
	v_add_f32_e32 v96, v96, v104
	v_add_f32_e32 v97, v97, v105
	v_add_f32_e32 v98, v98, v106
	v_add_f32_e32 v99, v99, v107
	v_add_f32_e32 v96, v96, v108
	v_add_f32_e32 v97, v97, v109
	v_add_f32_e32 v98, v98, v110
	v_add_f32_e32 v99, v99, v111
	v_add_f32_e32 v96, v96, v97
	v_add_f32_e32 v98, v98, v99
	v_add_f32_e32 v216, v96, v98
	ds_read_b128 v[96:99], v212 offset:6976
	ds_read_b128 v[100:103], v212 offset:6992
	ds_read_b128 v[104:107], v212 offset:7008
	ds_read_b128 v[108:111], v212 offset:7024
	s_waitcnt lgkmcnt(0)
	v_add_f32_e32 v96, v96, v100
	v_add_f32_e32 v97, v97, v101
	v_add_f32_e32 v98, v98, v102
	v_add_f32_e32 v99, v99, v103
	v_add_f32_e32 v96, v96, v104
	v_add_f32_e32 v97, v97, v105
	v_add_f32_e32 v98, v98, v106
	v_add_f32_e32 v99, v99, v107
	v_add_f32_e32 v96, v96, v108
	v_add_f32_e32 v97, v97, v109
	v_add_f32_e32 v98, v98, v110
	v_add_f32_e32 v99, v99, v111
	v_add_f32_e32 v96, v96, v97
	v_add_f32_e32 v98, v98, v99
	v_add_f32_e32 v96, v96, v98
	v_add_f32_e32 v216, v216, v96
	v_fmamk_f32 v94, v94, 0x3b800000, v197
	v_fmamk_f32 v95, v95, 0x3b800000, v197
	v_fmamk_f32 v215, v215, 0x3b800000, v197
	v_fmamk_f32 v216, v216, 0x3b800000, v197
	v_rsq_f32_e32 v94, v94
	v_rsq_f32_e32 v95, v95
	v_rsq_f32_e32 v215, v215
	v_rsq_f32_e32 v216, v216
	s_nop 0
	v_mul_f32_e32 v0, v94, v0
	v_mul_f32_e32 v1, v94, v1
	v_mul_f32_e32 v2, v94, v2
	v_mul_f32_e32 v3, v94, v3
	v_mul_f32_e32 v0, v80, v0
	v_mul_f32_e32 v1, v81, v1
	v_mul_f32_e32 v2, v82, v2
	v_mul_f32_e32 v3, v83, v3
	v_cvt_pk_bf16_f32 v0, v0, v1
	v_cvt_pk_bf16_f32 v1, v2, v3
	global_store_dwordx2 v213, v[0:1], s[14:15] offset:0
	v_mul_f32_e32 v4, v94, v4
	v_mul_f32_e32 v5, v94, v5
	v_mul_f32_e32 v6, v94, v6
	v_mul_f32_e32 v7, v94, v7
	v_mul_f32_e32 v4, v84, v4
	v_mul_f32_e32 v5, v85, v5
	v_mul_f32_e32 v6, v86, v6
	v_mul_f32_e32 v7, v87, v7
	v_cvt_pk_bf16_f32 v4, v4, v5
	v_cvt_pk_bf16_f32 v5, v6, v7
	global_store_dwordx2 v213, v[4:5], s[14:15] offset:32
	s_add_u32 s14, s14, 0x8000
	s_addc_u32 s15, s15, 0
	v_mul_f32_e32 v16, v95, v16
	v_mul_f32_e32 v17, v95, v17
	v_mul_f32_e32 v18, v95, v18
	v_mul_f32_e32 v19, v95, v19
	v_mul_f32_e32 v16, v80, v16
	v_mul_f32_e32 v17, v81, v17
	v_mul_f32_e32 v18, v82, v18
	v_mul_f32_e32 v19, v83, v19
	v_cvt_pk_bf16_f32 v16, v16, v17
	v_cvt_pk_bf16_f32 v17, v18, v19
	global_store_dwordx2 v213, v[16:17], s[14:15] offset:0
	v_mul_f32_e32 v20, v95, v20
	v_mul_f32_e32 v21, v95, v21
	v_mul_f32_e32 v22, v95, v22
	v_mul_f32_e32 v23, v95, v23
	v_mul_f32_e32 v20, v84, v20
	v_mul_f32_e32 v21, v85, v21
	v_mul_f32_e32 v22, v86, v22
	v_mul_f32_e32 v23, v87, v23
	v_cvt_pk_bf16_f32 v20, v20, v21
	v_cvt_pk_bf16_f32 v21, v22, v23
	global_store_dwordx2 v213, v[20:21], s[14:15] offset:32
	s_add_u32 s14, s14, 0x8000
	s_addc_u32 s15, s15, 0
	v_mul_f32_e32 v32, v215, v32
	v_mul_f32_e32 v33, v215, v33
	v_mul_f32_e32 v34, v215, v34
	v_mul_f32_e32 v35, v215, v35
	v_mul_f32_e32 v32, v80, v32
	v_mul_f32_e32 v33, v81, v33
	v_mul_f32_e32 v34, v82, v34
	v_mul_f32_e32 v35, v83, v35
	v_cvt_pk_bf16_f32 v32, v32, v33
	v_cvt_pk_bf16_f32 v33, v34, v35
	global_store_dwordx2 v213, v[32:33], s[14:15] offset:0
	v_mul_f32_e32 v36, v215, v36
	v_mul_f32_e32 v37, v215, v37
	v_mul_f32_e32 v38, v215, v38
	v_mul_f32_e32 v39, v215, v39
	v_mul_f32_e32 v36, v84, v36
	v_mul_f32_e32 v37, v85, v37
	v_mul_f32_e32 v38, v86, v38
	v_mul_f32_e32 v39, v87, v39
	v_cvt_pk_bf16_f32 v36, v36, v37
	v_cvt_pk_bf16_f32 v37, v38, v39
	global_store_dwordx2 v213, v[36:37], s[14:15] offset:32
	s_add_u32 s14, s14, 0x8000
	s_addc_u32 s15, s15, 0
	v_mul_f32_e32 v48, v216, v48
	v_mul_f32_e32 v49, v216, v49
	v_mul_f32_e32 v50, v216, v50
	v_mul_f32_e32 v51, v216, v51
	v_mul_f32_e32 v48, v80, v48
	v_mul_f32_e32 v49, v81, v49
	v_mul_f32_e32 v50, v82, v50
	v_mul_f32_e32 v51, v83, v51
	v_cvt_pk_bf16_f32 v48, v48, v49
	v_cvt_pk_bf16_f32 v49, v50, v51
	global_store_dwordx2 v213, v[48:49], s[14:15] offset:0
	v_mul_f32_e32 v52, v216, v52
	v_mul_f32_e32 v53, v216, v53
	v_mul_f32_e32 v54, v216, v54
	v_mul_f32_e32 v55, v216, v55
	v_mul_f32_e32 v52, v84, v52
	v_mul_f32_e32 v53, v85, v53
	v_mul_f32_e32 v54, v86, v54
	v_mul_f32_e32 v55, v87, v55
	v_cvt_pk_bf16_f32 v52, v52, v53
	v_cvt_pk_bf16_f32 v53, v54, v55
	global_store_dwordx2 v213, v[52:53], s[14:15] offset:32
	s_waitcnt vmcnt(8)
	s_barrier
	ds_read_b128 v[96:99], v128 offset:0
	ds_read_b128 v[100:103], v128 offset:2048
	ds_read_b128 v[104:107], v128 offset:4096
	ds_read_b128 v[108:111], v128 offset:6144
	ds_read_b128 v[112:115], v128 offset:32768
	ds_read_b128 v[116:119], v128 offset:34816
	ds_read_b128 v[120:123], v128 offset:36864
	ds_read_b128 v[124:127], v128 offset:38912
	ds_read_b128 v[138:141], v129 offset:0
	ds_read_b128 v[142:145], v129 offset:2048
	ds_read_b128 v[146:149], v129 offset:4096
	ds_read_b128 v[150:153], v129 offset:6144
	ds_read_b128 v[154:157], v129 offset:32768
	ds_read_b128 v[158:161], v129 offset:34816
	ds_read_b128 v[162:165], v129 offset:36864
	ds_read_b128 v[166:169], v129 offset:38912
	ds_read_b128 v[64:67], v133 offset:0
	ds_read_b128 v[72:75], v133 offset:2048
	ds_read_b128 v[80:83], v133 offset:4096
	ds_read_b128 v[88:91], v133 offset:6144
	ds_read_b128 v[68:71], v134 offset:0
	ds_read_b128 v[76:79], v134 offset:2048
	ds_read_b128 v[84:87], v134 offset:4096
	ds_read_b128 v[92:95], v134 offset:6144
	s_waitcnt lgkmcnt(0)
	s_add_u32 s0, s18, 0x80
	s_addc_u32 s1, s19, 0
	s_add_i32 m0, s23, 0x0
	s_nop 0
	global_load_lds_dwordx4 v132, s[0:1]
	s_add_u32 s0, s18, 0x1080
	s_addc_u32 s1, s19, 0
	s_add_i32 m0, s23, 0x400
	s_nop 0
	global_load_lds_dwordx4 v132, s[0:1]
	s_add_u32 s0, s18, 0x2080
	s_addc_u32 s1, s19, 0
	s_add_i32 m0, s23, 0x800
	s_nop 0
	global_load_lds_dwordx4 v132, s[0:1]
	s_add_u32 s0, s18, 0x3080
	s_addc_u32 s1, s19, 0
	s_add_i32 m0, s23, 0xc00
	s_nop 0
	global_load_lds_dwordx4 v132, s[0:1]
	s_add_u32 s0, s20, 0x80
	s_addc_u32 s1, s21, 0
	s_add_i32 m0, s23, 0x1000
	s_nop 0
	global_load_lds_dwordx4 v132, s[0:1]
	s_add_u32 s0, s20, 0x1080
	s_addc_u32 s1, s21, 0
	s_add_i32 m0, s23, 0x1400
	s_nop 0
	global_load_lds_dwordx4 v132, s[0:1]
	s_add_u32 s0, s20, 0x2080
	s_addc_u32 s1, s21, 0
	s_add_i32 m0, s23, 0x1800
	s_nop 0
	global_load_lds_dwordx4 v132, s[0:1]
	s_add_u32 s0, s20, 0x3080
	s_addc_u32 s1, s21, 0
	s_add_i32 m0, s23, 0x1c00
	s_nop 0
	global_load_lds_dwordx4 v132, s[0:1]
	v_mfma_f32_16x16x32_bf16 v[0:3], v[64:67], v[96:99], 0
	v_mfma_f32_16x16x32_bf16 v[16:19], v[64:67], v[100:103], 0
	v_mfma_f32_16x16x32_bf16 v[32:35], v[64:67], v[104:107], 0
	v_mfma_f32_16x16x32_bf16 v[48:51], v[64:67], v[108:111], 0
	v_mfma_f32_16x16x32_bf16 v[4:7], v[72:75], v[96:99], 0
	v_mfma_f32_16x16x32_bf16 v[20:23], v[72:75], v[100:103], 0
	v_mfma_f32_16x16x32_bf16 v[36:39], v[72:75], v[104:107], 0
	v_mfma_f32_16x16x32_bf16 v[52:55], v[72:75], v[108:111], 0
	v_mfma_f32_16x16x32_bf16 v[8:11], v[80:83], v[112:115], 0
	v_mfma_f32_16x16x32_bf16 v[24:27], v[80:83], v[116:119], 0
	v_mfma_f32_16x16x32_bf16 v[40:43], v[80:83], v[120:123], 0
	v_mfma_f32_16x16x32_bf16 v[56:59], v[80:83], v[124:127], 0
	v_mfma_f32_16x16x32_bf16 v[12:15], v[88:91], v[112:115], 0
	v_mfma_f32_16x16x32_bf16 v[28:31], v[88:91], v[116:119], 0
	v_mfma_f32_16x16x32_bf16 v[44:47], v[88:91], v[120:123], 0
	v_mfma_f32_16x16x32_bf16 v[60:63], v[88:91], v[124:127], 0
	ds_read_b128 v[96:99], v128 offset:8192
	ds_read_b128 v[100:103], v128 offset:10240
	ds_read_b128 v[104:107], v128 offset:12288
	ds_read_b128 v[108:111], v128 offset:14336
	ds_read_b128 v[112:115], v128 offset:40960
	ds_read_b128 v[116:119], v128 offset:43008
	ds_read_b128 v[120:123], v128 offset:45056
	ds_read_b128 v[124:127], v128 offset:47104
	v_mfma_f32_16x16x32_bf16 v[0:3], v[68:71], v[138:141], v[0:3]
	v_mfma_f32_16x16x32_bf16 v[16:19], v[68:71], v[142:145], v[16:19]
	v_mfma_f32_16x16x32_bf16 v[32:35], v[68:71], v[146:149], v[32:35]
	v_mfma_f32_16x16x32_bf16 v[48:51], v[68:71], v[150:153], v[48:51]
	v_mfma_f32_16x16x32_bf16 v[4:7], v[76:79], v[138:141], v[4:7]
	v_mfma_f32_16x16x32_bf16 v[20:23], v[76:79], v[142:145], v[20:23]
	v_mfma_f32_16x16x32_bf16 v[36:39], v[76:79], v[146:149], v[36:39]
	v_mfma_f32_16x16x32_bf16 v[52:55], v[76:79], v[150:153], v[52:55]
	v_mfma_f32_16x16x32_bf16 v[8:11], v[84:87], v[154:157], v[8:11]
	v_mfma_f32_16x16x32_bf16 v[24:27], v[84:87], v[158:161], v[24:27]
	v_mfma_f32_16x16x32_bf16 v[40:43], v[84:87], v[162:165], v[40:43]
	v_mfma_f32_16x16x32_bf16 v[56:59], v[84:87], v[166:169], v[56:59]
	v_mfma_f32_16x16x32_bf16 v[12:15], v[92:95], v[154:157], v[12:15]
	v_mfma_f32_16x16x32_bf16 v[28:31], v[92:95], v[158:161], v[28:31]
	v_mfma_f32_16x16x32_bf16 v[44:47], v[92:95], v[162:165], v[44:47]
	v_mfma_f32_16x16x32_bf16 v[60:63], v[92:95], v[166:169], v[60:63]
	ds_read_b128 v[138:141], v129 offset:8192
	ds_read_b128 v[142:145], v129 offset:10240
	ds_read_b128 v[146:149], v129 offset:12288
	ds_read_b128 v[150:153], v129 offset:14336
	ds_read_b128 v[154:157], v129 offset:40960
	ds_read_b128 v[158:161], v129 offset:43008
	ds_read_b128 v[162:165], v129 offset:45056
	ds_read_b128 v[166:169], v129 offset:47104
	s_waitcnt vmcnt(0)
	ds_read_b128 v[64:67], v133 offset:0
	ds_read_b128 v[72:75], v133 offset:2048
	ds_read_b128 v[80:83], v133 offset:4096
	ds_read_b128 v[88:91], v133 offset:6144
	ds_read_b128 v[68:71], v134 offset:0
	ds_read_b128 v[76:79], v134 offset:2048
	ds_read_b128 v[84:87], v134 offset:4096
	ds_read_b128 v[92:95], v134 offset:6144
	s_waitcnt lgkmcnt(0)
	s_add_u32 s0, s18, 0x100
	s_addc_u32 s1, s19, 0
	s_add_i32 m0, s23, 0x0
	s_nop 0
	global_load_lds_dwordx4 v132, s[0:1]
	s_add_u32 s0, s18, 0x1100
	s_addc_u32 s1, s19, 0
	s_add_i32 m0, s23, 0x400
	s_nop 0
	global_load_lds_dwordx4 v132, s[0:1]
	s_add_u32 s0, s18, 0x2100
	s_addc_u32 s1, s19, 0
	s_add_i32 m0, s23, 0x800
	s_nop 0
	global_load_lds_dwordx4 v132, s[0:1]
	s_add_u32 s0, s18, 0x3100
	s_addc_u32 s1, s19, 0
	s_add_i32 m0, s23, 0xc00
	s_nop 0
	global_load_lds_dwordx4 v132, s[0:1]
	s_add_u32 s0, s20, 0x100
	s_addc_u32 s1, s21, 0
	s_add_i32 m0, s23, 0x1000
	s_nop 0
	global_load_lds_dwordx4 v132, s[0:1]
	s_add_u32 s0, s20, 0x1100
	s_addc_u32 s1, s21, 0
	s_add_i32 m0, s23, 0x1400
	s_nop 0
	global_load_lds_dwordx4 v132, s[0:1]
	s_add_u32 s0, s20, 0x2100
	s_addc_u32 s1, s21, 0
	s_add_i32 m0, s23, 0x1800
	s_nop 0
	global_load_lds_dwordx4 v132, s[0:1]
	s_add_u32 s0, s20, 0x3100
	s_addc_u32 s1, s21, 0
	s_add_i32 m0, s23, 0x1c00
	s_nop 0
	global_load_lds_dwordx4 v132, s[0:1]
	v_mfma_f32_16x16x32_bf16 v[0:3], v[64:67], v[96:99], v[0:3]
	v_mfma_f32_16x16x32_bf16 v[16:19], v[64:67], v[100:103], v[16:19]
	v_mfma_f32_16x16x32_bf16 v[32:35], v[64:67], v[104:107], v[32:35]
	v_mfma_f32_16x16x32_bf16 v[48:51], v[64:67], v[108:111], v[48:51]
	v_mfma_f32_16x16x32_bf16 v[4:7], v[72:75], v[96:99], v[4:7]
	v_mfma_f32_16x16x32_bf16 v[20:23], v[72:75], v[100:103], v[20:23]
	v_mfma_f32_16x16x32_bf16 v[36:39], v[72:75], v[104:107], v[36:39]
	v_mfma_f32_16x16x32_bf16 v[52:55], v[72:75], v[108:111], v[52:55]
	v_mfma_f32_16x16x32_bf16 v[8:11], v[80:83], v[112:115], v[8:11]
	v_mfma_f32_16x16x32_bf16 v[24:27], v[80:83], v[116:119], v[24:27]
	v_mfma_f32_16x16x32_bf16 v[40:43], v[80:83], v[120:123], v[40:43]
	v_mfma_f32_16x16x32_bf16 v[56:59], v[80:83], v[124:127], v[56:59]
	v_mfma_f32_16x16x32_bf16 v[12:15], v[88:91], v[112:115], v[12:15]
	v_mfma_f32_16x16x32_bf16 v[28:31], v[88:91], v[116:119], v[28:31]
	v_mfma_f32_16x16x32_bf16 v[44:47], v[88:91], v[120:123], v[44:47]
	v_mfma_f32_16x16x32_bf16 v[60:63], v[88:91], v[124:127], v[60:63]
	ds_read_b128 v[96:99], v128 offset:16384
	ds_read_b128 v[100:103], v128 offset:18432
	ds_read_b128 v[104:107], v128 offset:20480
	ds_read_b128 v[108:111], v128 offset:22528
	ds_read_b128 v[112:115], v128 offset:49152
	ds_read_b128 v[116:119], v128 offset:51200
	ds_read_b128 v[120:123], v128 offset:53248
	ds_read_b128 v[124:127], v128 offset:55296
	v_mfma_f32_16x16x32_bf16 v[0:3], v[68:71], v[138:141], v[0:3]
	v_mfma_f32_16x16x32_bf16 v[16:19], v[68:71], v[142:145], v[16:19]
	v_mfma_f32_16x16x32_bf16 v[32:35], v[68:71], v[146:149], v[32:35]
	v_mfma_f32_16x16x32_bf16 v[48:51], v[68:71], v[150:153], v[48:51]
	v_mfma_f32_16x16x32_bf16 v[4:7], v[76:79], v[138:141], v[4:7]
	v_mfma_f32_16x16x32_bf16 v[20:23], v[76:79], v[142:145], v[20:23]
	v_mfma_f32_16x16x32_bf16 v[36:39], v[76:79], v[146:149], v[36:39]
	v_mfma_f32_16x16x32_bf16 v[52:55], v[76:79], v[150:153], v[52:55]
	v_mfma_f32_16x16x32_bf16 v[8:11], v[84:87], v[154:157], v[8:11]
	v_mfma_f32_16x16x32_bf16 v[24:27], v[84:87], v[158:161], v[24:27]
	v_mfma_f32_16x16x32_bf16 v[40:43], v[84:87], v[162:165], v[40:43]
	v_mfma_f32_16x16x32_bf16 v[56:59], v[84:87], v[166:169], v[56:59]
	v_mfma_f32_16x16x32_bf16 v[12:15], v[92:95], v[154:157], v[12:15]
	v_mfma_f32_16x16x32_bf16 v[28:31], v[92:95], v[158:161], v[28:31]
	v_mfma_f32_16x16x32_bf16 v[44:47], v[92:95], v[162:165], v[44:47]
	v_mfma_f32_16x16x32_bf16 v[60:63], v[92:95], v[166:169], v[60:63]
	ds_read_b128 v[138:141], v129 offset:16384
	ds_read_b128 v[142:145], v129 offset:18432
	ds_read_b128 v[146:149], v129 offset:20480
	ds_read_b128 v[150:153], v129 offset:22528
	ds_read_b128 v[154:157], v129 offset:49152
	ds_read_b128 v[158:161], v129 offset:51200
	ds_read_b128 v[162:165], v129 offset:53248
	ds_read_b128 v[166:169], v129 offset:55296
	s_waitcnt vmcnt(0)
	ds_read_b128 v[64:67], v133 offset:0
	ds_read_b128 v[72:75], v133 offset:2048
	ds_read_b128 v[80:83], v133 offset:4096
	ds_read_b128 v[88:91], v133 offset:6144
	ds_read_b128 v[68:71], v134 offset:0
	ds_read_b128 v[76:79], v134 offset:2048
	ds_read_b128 v[84:87], v134 offset:4096
	ds_read_b128 v[92:95], v134 offset:6144
	s_waitcnt lgkmcnt(0)
	s_add_u32 s0, s18, 0x180
	s_addc_u32 s1, s19, 0
	s_add_i32 m0, s23, 0x0
	s_nop 0
	global_load_lds_dwordx4 v132, s[0:1]
	s_add_u32 s0, s18, 0x1180
	s_addc_u32 s1, s19, 0
	s_add_i32 m0, s23, 0x400
	s_nop 0
	global_load_lds_dwordx4 v132, s[0:1]
	s_add_u32 s0, s18, 0x2180
	s_addc_u32 s1, s19, 0
	s_add_i32 m0, s23, 0x800
	s_nop 0
	global_load_lds_dwordx4 v132, s[0:1]
	s_add_u32 s0, s18, 0x3180
	s_addc_u32 s1, s19, 0
	s_add_i32 m0, s23, 0xc00
	s_nop 0
	global_load_lds_dwordx4 v132, s[0:1]
	s_add_u32 s0, s20, 0x180
	s_addc_u32 s1, s21, 0
	s_add_i32 m0, s23, 0x1000
	s_nop 0
	global_load_lds_dwordx4 v132, s[0:1]
	s_add_u32 s0, s20, 0x1180
	s_addc_u32 s1, s21, 0
	s_add_i32 m0, s23, 0x1400
	s_nop 0
	global_load_lds_dwordx4 v132, s[0:1]
	s_add_u32 s0, s20, 0x2180
	s_addc_u32 s1, s21, 0
	s_add_i32 m0, s23, 0x1800
	s_nop 0
	global_load_lds_dwordx4 v132, s[0:1]
	s_add_u32 s0, s20, 0x3180
	s_addc_u32 s1, s21, 0
	s_add_i32 m0, s23, 0x1c00
	s_nop 0
	global_load_lds_dwordx4 v132, s[0:1]
	v_mfma_f32_16x16x32_bf16 v[0:3], v[64:67], v[96:99], v[0:3]
	v_mfma_f32_16x16x32_bf16 v[16:19], v[64:67], v[100:103], v[16:19]
	v_mfma_f32_16x16x32_bf16 v[32:35], v[64:67], v[104:107], v[32:35]
	v_mfma_f32_16x16x32_bf16 v[48:51], v[64:67], v[108:111], v[48:51]
	v_mfma_f32_16x16x32_bf16 v[4:7], v[72:75], v[96:99], v[4:7]
	v_mfma_f32_16x16x32_bf16 v[20:23], v[72:75], v[100:103], v[20:23]
	v_mfma_f32_16x16x32_bf16 v[36:39], v[72:75], v[104:107], v[36:39]
	v_mfma_f32_16x16x32_bf16 v[52:55], v[72:75], v[108:111], v[52:55]
	v_mfma_f32_16x16x32_bf16 v[8:11], v[80:83], v[112:115], v[8:11]
	v_mfma_f32_16x16x32_bf16 v[24:27], v[80:83], v[116:119], v[24:27]
	v_mfma_f32_16x16x32_bf16 v[40:43], v[80:83], v[120:123], v[40:43]
	v_mfma_f32_16x16x32_bf16 v[56:59], v[80:83], v[124:127], v[56:59]
	v_mfma_f32_16x16x32_bf16 v[12:15], v[88:91], v[112:115], v[12:15]
	v_mfma_f32_16x16x32_bf16 v[28:31], v[88:91], v[116:119], v[28:31]
	v_mfma_f32_16x16x32_bf16 v[44:47], v[88:91], v[120:123], v[44:47]
	v_mfma_f32_16x16x32_bf16 v[60:63], v[88:91], v[124:127], v[60:63]
	ds_read_b128 v[96:99], v128 offset:24576
	ds_read_b128 v[100:103], v128 offset:26624
	ds_read_b128 v[104:107], v128 offset:28672
	ds_read_b128 v[108:111], v128 offset:30720
	ds_read_b128 v[112:115], v128 offset:57344
	ds_read_b128 v[116:119], v128 offset:59392
	ds_read_b128 v[120:123], v128 offset:61440
	ds_read_b128 v[124:127], v128 offset:63488
	v_mfma_f32_16x16x32_bf16 v[0:3], v[68:71], v[138:141], v[0:3]
	v_mfma_f32_16x16x32_bf16 v[16:19], v[68:71], v[142:145], v[16:19]
	v_mfma_f32_16x16x32_bf16 v[32:35], v[68:71], v[146:149], v[32:35]
	v_mfma_f32_16x16x32_bf16 v[48:51], v[68:71], v[150:153], v[48:51]
	v_mfma_f32_16x16x32_bf16 v[4:7], v[76:79], v[138:141], v[4:7]
	v_mfma_f32_16x16x32_bf16 v[20:23], v[76:79], v[142:145], v[20:23]
	v_mfma_f32_16x16x32_bf16 v[36:39], v[76:79], v[146:149], v[36:39]
	v_mfma_f32_16x16x32_bf16 v[52:55], v[76:79], v[150:153], v[52:55]
	v_mfma_f32_16x16x32_bf16 v[8:11], v[84:87], v[154:157], v[8:11]
	v_mfma_f32_16x16x32_bf16 v[24:27], v[84:87], v[158:161], v[24:27]
	v_mfma_f32_16x16x32_bf16 v[40:43], v[84:87], v[162:165], v[40:43]
	v_mfma_f32_16x16x32_bf16 v[56:59], v[84:87], v[166:169], v[56:59]
	v_mfma_f32_16x16x32_bf16 v[12:15], v[92:95], v[154:157], v[12:15]
	v_mfma_f32_16x16x32_bf16 v[28:31], v[92:95], v[158:161], v[28:31]
	v_mfma_f32_16x16x32_bf16 v[44:47], v[92:95], v[162:165], v[44:47]
	v_mfma_f32_16x16x32_bf16 v[60:63], v[92:95], v[166:169], v[60:63]
	ds_read_b128 v[138:141], v129 offset:24576
	ds_read_b128 v[142:145], v129 offset:26624
	ds_read_b128 v[146:149], v129 offset:28672
	ds_read_b128 v[150:153], v129 offset:30720
	ds_read_b128 v[154:157], v129 offset:57344
	ds_read_b128 v[158:161], v129 offset:59392
	ds_read_b128 v[162:165], v129 offset:61440
	ds_read_b128 v[166:169], v129 offset:63488
	s_waitcnt vmcnt(0)
	ds_read_b128 v[64:67], v133 offset:0
	ds_read_b128 v[72:75], v133 offset:2048
	ds_read_b128 v[80:83], v133 offset:4096
	ds_read_b128 v[88:91], v133 offset:6144
	ds_read_b128 v[68:71], v134 offset:0
	ds_read_b128 v[76:79], v134 offset:2048
	ds_read_b128 v[84:87], v134 offset:4096
	ds_read_b128 v[92:95], v134 offset:6144
	s_waitcnt lgkmcnt(0)
	v_mfma_f32_16x16x32_bf16 v[0:3], v[64:67], v[96:99], v[0:3]
	v_mfma_f32_16x16x32_bf16 v[16:19], v[64:67], v[100:103], v[16:19]
	v_mfma_f32_16x16x32_bf16 v[32:35], v[64:67], v[104:107], v[32:35]
	v_mfma_f32_16x16x32_bf16 v[48:51], v[64:67], v[108:111], v[48:51]
	v_mfma_f32_16x16x32_bf16 v[4:7], v[72:75], v[96:99], v[4:7]
	v_mfma_f32_16x16x32_bf16 v[20:23], v[72:75], v[100:103], v[20:23]
	v_mfma_f32_16x16x32_bf16 v[36:39], v[72:75], v[104:107], v[36:39]
	v_mfma_f32_16x16x32_bf16 v[52:55], v[72:75], v[108:111], v[52:55]
	v_mfma_f32_16x16x32_bf16 v[8:11], v[80:83], v[112:115], v[8:11]
	v_mfma_f32_16x16x32_bf16 v[24:27], v[80:83], v[116:119], v[24:27]
	v_mfma_f32_16x16x32_bf16 v[40:43], v[80:83], v[120:123], v[40:43]
	v_mfma_f32_16x16x32_bf16 v[56:59], v[80:83], v[124:127], v[56:59]
	v_mfma_f32_16x16x32_bf16 v[12:15], v[88:91], v[112:115], v[12:15]
	v_mfma_f32_16x16x32_bf16 v[28:31], v[88:91], v[116:119], v[28:31]
	v_mfma_f32_16x16x32_bf16 v[44:47], v[88:91], v[120:123], v[44:47]
	v_mfma_f32_16x16x32_bf16 v[60:63], v[88:91], v[124:127], v[60:63]
	v_lshlrev_b32_e32 v214, 4, v207
	s_lshl_b32 s1, s22, 7
	s_lshl_b32 s0, s24, 10
	s_add_u32 s0, s0, 0x113000
	s_add_u32 s0, s0, s1
	s_add_u32 s6, s4, s0
	s_addc_u32 s7, s5, 0
	global_load_dwordx4 v[96:99], v214, s[6:7] offset:0
	global_load_dwordx4 v[100:103], v214, s[6:7] offset:64
	s_lshl_b32 s0, s24, 10
	s_add_u32 s0, s0, 0x113800
	s_add_u32 s0, s0, s1
	s_add_u32 s6, s4, s0
	s_addc_u32 s7, s5, 0
	global_load_dwordx4 v[104:107], v214, s[6:7] offset:0
	global_load_dwordx4 v[108:111], v214, s[6:7] offset:64
	s_lshl_b32 s0, s24, 12
	s_add_u32 s0, s0, 0x221320
	s_add_u32 s0, s0, s1
	s_add_u32 s6, s4, s0
	s_addc_u32 s7, s5, 0
	global_load_dwordx4 v[112:115], v214, s[6:7] offset:0
	global_load_dwordx4 v[116:119], v214, s[6:7] offset:64
	s_lshl_b32 s0, s24, 12
	s_add_u32 s0, s0, 0x221720
	s_add_u32 s0, s0, s1
	s_add_u32 s6, s4, s0
	s_addc_u32 s7, s5, 0
	global_load_dwordx4 v[120:123], v214, s[6:7] offset:0
	global_load_dwordx4 v[124:127], v214, s[6:7] offset:64
	v_mfma_f32_16x16x32_bf16 v[0:3], v[68:71], v[138:141], v[0:3]
	v_mfma_f32_16x16x32_bf16 v[16:19], v[68:71], v[142:145], v[16:19]
	v_mfma_f32_16x16x32_bf16 v[32:35], v[68:71], v[146:149], v[32:35]
	v_mfma_f32_16x16x32_bf16 v[48:51], v[68:71], v[150:153], v[48:51]
	v_mfma_f32_16x16x32_bf16 v[4:7], v[76:79], v[138:141], v[4:7]
	v_mfma_f32_16x16x32_bf16 v[20:23], v[76:79], v[142:145], v[20:23]
	v_mfma_f32_16x16x32_bf16 v[36:39], v[76:79], v[146:149], v[36:39]
	v_mfma_f32_16x16x32_bf16 v[52:55], v[76:79], v[150:153], v[52:55]
	v_mfma_f32_16x16x32_bf16 v[8:11], v[84:87], v[154:157], v[8:11]
	v_mfma_f32_16x16x32_bf16 v[24:27], v[84:87], v[158:161], v[24:27]
	v_mfma_f32_16x16x32_bf16 v[40:43], v[84:87], v[162:165], v[40:43]
	v_mfma_f32_16x16x32_bf16 v[56:59], v[84:87], v[166:169], v[56:59]
	v_mfma_f32_16x16x32_bf16 v[12:15], v[92:95], v[154:157], v[12:15]
	v_mfma_f32_16x16x32_bf16 v[28:31], v[92:95], v[158:161], v[28:31]
	v_mfma_f32_16x16x32_bf16 v[44:47], v[92:95], v[162:165], v[44:47]
	v_mfma_f32_16x16x32_bf16 v[60:63], v[92:95], v[166:169], v[60:63]
	s_lshl_b32 s0, s24, 12
	s_add_u32 s0, s0, 0x221b20
	s_add_u32 s6, s4, s0
	s_addc_u32 s7, s5, 0
	global_load_dwordx4 v[64:67], v209, s[6:7]
	global_load_dwordx2 v[170:171], v208, s[10:11] offset:1024
	s_add_u32 s10, s10, 0x600
	s_addc_u32 s11, s11, 0
	global_load_dwordx2 v[172:173], v208, s[10:11] offset:1024
	s_add_u32 s10, s10, 0x600
	s_addc_u32 s11, s11, 0
	global_load_dwordx2 v[174:175], v208, s[10:11] offset:1024
	s_add_u32 s10, s10, 0x600
	s_addc_u32 s11, s11, 0
	global_load_dwordx2 v[176:177], v208, s[10:11] offset:1024
	s_add_u32 s10, s10, 0x600
	s_addc_u32 s11, s11, 0
	global_load_dwordx2 v[178:179], v208, s[10:11] offset:1024
	s_add_u32 s10, s10, 0x600
	s_addc_u32 s11, s11, 0
	global_load_dwordx2 v[180:181], v208, s[10:11] offset:1024
	s_add_u32 s10, s10, 0x600
	s_addc_u32 s11, s11, 0
	global_load_dwordx2 v[182:183], v208, s[10:11] offset:1024
	s_add_u32 s10, s10, 0x600
	s_addc_u32 s11, s11, 0
	global_load_dwordx2 v[184:185], v208, s[10:11] offset:1024
	v_xor_b32_e32 v215, 16, v205
	v_lshlrev_b32_e32 v215, 2, v215
	v_xor_b32_e32 v216, 32, v205
	v_lshlrev_b32_e32 v216, 2, v216
	v_lshlrev_b32_e32 v83, 5, v206
	v_add_u32_e32 v83, 0x20000, v83
	v_lshl_add_u32 v82, v210, 2, v83
	s_waitcnt vmcnt(9)
	s_nop 6
	v_mov_b32_e32 v74, 0
	v_mov_b32_e32 v75, 0
	v_mov_b32_e32 v76, 0
	v_mov_b32_e32 v77, 0
	v_mov_b32_e32 v78, 0
	v_mov_b32_e32 v79, 0
	v_mov_b32_e32 v80, 0
	v_mov_b32_e32 v81, 0
	v_add_f32_e32 v0, v0, v96
	v_bfe_u32 v68, v0, 16, 1
	v_add3_u32 v0, v0, v68, s77
	v_and_b32_e32 v0, s35, v0
	v_fmac_f32_e32 v74, v0, v0
	v_add_f32_e32 v1, v1, v97
	v_bfe_u32 v68, v1, 16, 1
	v_add3_u32 v1, v1, v68, s77
	v_and_b32_e32 v1, s35, v1
	v_fmac_f32_e32 v74, v1, v1
	v_add_f32_e32 v2, v2, v98
	v_bfe_u32 v68, v2, 16, 1
	v_add3_u32 v2, v2, v68, s77
	v_and_b32_e32 v2, s35, v2
	v_fmac_f32_e32 v74, v2, v2
	v_add_f32_e32 v3, v3, v99
	v_bfe_u32 v68, v3, 16, 1
	v_add3_u32 v3, v3, v68, s77
	v_and_b32_e32 v3, s35, v3
	v_fmac_f32_e32 v74, v3, v3
	v_add_f32_e32 v4, v4, v100
	v_bfe_u32 v68, v4, 16, 1
	v_add3_u32 v4, v4, v68, s77
	v_and_b32_e32 v4, s35, v4
	v_fmac_f32_e32 v74, v4, v4
	v_add_f32_e32 v5, v5, v101
	v_bfe_u32 v68, v5, 16, 1
	v_add3_u32 v5, v5, v68, s77
	v_and_b32_e32 v5, s35, v5
	v_fmac_f32_e32 v74, v5, v5
	v_add_f32_e32 v6, v6, v102
	v_bfe_u32 v68, v6, 16, 1
	v_add3_u32 v6, v6, v68, s77
	v_and_b32_e32 v6, s35, v6
	v_fmac_f32_e32 v74, v6, v6
	v_add_f32_e32 v7, v7, v103
	v_bfe_u32 v68, v7, 16, 1
	v_add3_u32 v7, v7, v68, s77
	v_and_b32_e32 v7, s35, v7
	v_fmac_f32_e32 v74, v7, v7
	v_add_f32_e32 v8, v8, v104
	v_bfe_u32 v68, v8, 16, 1
	v_add3_u32 v8, v8, v68, s77
	v_and_b32_e32 v8, s35, v8
	v_fmac_f32_e32 v78, v8, v8
	v_add_f32_e32 v9, v9, v105
	v_bfe_u32 v68, v9, 16, 1
	v_add3_u32 v9, v9, v68, s77
	v_and_b32_e32 v9, s35, v9
	v_fmac_f32_e32 v78, v9, v9
	v_add_f32_e32 v10, v10, v106
	v_bfe_u32 v68, v10, 16, 1
	v_add3_u32 v10, v10, v68, s77
	v_and_b32_e32 v10, s35, v10
	v_fmac_f32_e32 v78, v10, v10
	v_add_f32_e32 v11, v11, v107
	v_bfe_u32 v68, v11, 16, 1
	v_add3_u32 v11, v11, v68, s77
	v_and_b32_e32 v11, s35, v11
	v_fmac_f32_e32 v78, v11, v11
	v_add_f32_e32 v12, v12, v108
	v_bfe_u32 v68, v12, 16, 1
	v_add3_u32 v12, v12, v68, s77
	v_and_b32_e32 v12, s35, v12
	v_fmac_f32_e32 v78, v12, v12
	v_add_f32_e32 v13, v13, v109
	v_bfe_u32 v68, v13, 16, 1
	v_add3_u32 v13, v13, v68, s77
	v_and_b32_e32 v13, s35, v13
	v_fmac_f32_e32 v78, v13, v13
	v_add_f32_e32 v14, v14, v110
	v_bfe_u32 v68, v14, 16, 1
	v_add3_u32 v14, v14, v68, s77
	v_and_b32_e32 v14, s35, v14
	v_fmac_f32_e32 v78, v14, v14
	v_add_f32_e32 v15, v15, v111
	v_bfe_u32 v68, v15, 16, 1
	v_add3_u32 v15, v15, v68, s77
	v_and_b32_e32 v15, s35, v15
	v_fmac_f32_e32 v78, v15, v15
	v_add_f32_e32 v16, v16, v96
	v_bfe_u32 v68, v16, 16, 1
	v_add3_u32 v16, v16, v68, s77
	v_and_b32_e32 v16, s35, v16
	v_fmac_f32_e32 v75, v16, v16
	v_add_f32_e32 v17, v17, v97
	v_bfe_u32 v68, v17, 16, 1
	v_add3_u32 v17, v17, v68, s77
	v_and_b32_e32 v17, s35, v17
	v_fmac_f32_e32 v75, v17, v17
	v_add_f32_e32 v18, v18, v98
	v_bfe_u32 v68, v18, 16, 1
	v_add3_u32 v18, v18, v68, s77
	v_and_b32_e32 v18, s35, v18
	v_fmac_f32_e32 v75, v18, v18
	v_add_f32_e32 v19, v19, v99
	v_bfe_u32 v68, v19, 16, 1
	v_add3_u32 v19, v19, v68, s77
	v_and_b32_e32 v19, s35, v19
	v_fmac_f32_e32 v75, v19, v19
	v_add_f32_e32 v20, v20, v100
	v_bfe_u32 v68, v20, 16, 1
	v_add3_u32 v20, v20, v68, s77
	v_and_b32_e32 v20, s35, v20
	v_fmac_f32_e32 v75, v20, v20
	v_add_f32_e32 v21, v21, v101
	v_bfe_u32 v68, v21, 16, 1
	v_add3_u32 v21, v21, v68, s77
	v_and_b32_e32 v21, s35, v21
	v_fmac_f32_e32 v75, v21, v21
	v_add_f32_e32 v22, v22, v102
	v_bfe_u32 v68, v22, 16, 1
	v_add3_u32 v22, v22, v68, s77
	v_and_b32_e32 v22, s35, v22
	v_fmac_f32_e32 v75, v22, v22
	v_add_f32_e32 v23, v23, v103
	v_bfe_u32 v68, v23, 16, 1
	v_add3_u32 v23, v23, v68, s77
	v_and_b32_e32 v23, s35, v23
	v_fmac_f32_e32 v75, v23, v23
	v_add_f32_e32 v24, v24, v104
	v_bfe_u32 v68, v24, 16, 1
	v_add3_u32 v24, v24, v68, s77
	v_and_b32_e32 v24, s35, v24
	v_fmac_f32_e32 v79, v24, v24
	v_add_f32_e32 v25, v25, v105
	v_bfe_u32 v68, v25, 16, 1
	v_add3_u32 v25, v25, v68, s77
	v_and_b32_e32 v25, s35, v25
	v_fmac_f32_e32 v79, v25, v25
	v_add_f32_e32 v26, v26, v106
	v_bfe_u32 v68, v26, 16, 1
	v_add3_u32 v26, v26, v68, s77
	v_and_b32_e32 v26, s35, v26
	v_fmac_f32_e32 v79, v26, v26
	v_add_f32_e32 v27, v27, v107
	v_bfe_u32 v68, v27, 16, 1
	v_add3_u32 v27, v27, v68, s77
	v_and_b32_e32 v27, s35, v27
	v_fmac_f32_e32 v79, v27, v27
	v_add_f32_e32 v28, v28, v108
	v_bfe_u32 v68, v28, 16, 1
	v_add3_u32 v28, v28, v68, s77
	v_and_b32_e32 v28, s35, v28
	v_fmac_f32_e32 v79, v28, v28
	v_add_f32_e32 v29, v29, v109
	v_bfe_u32 v68, v29, 16, 1
	v_add3_u32 v29, v29, v68, s77
	v_and_b32_e32 v29, s35, v29
	v_fmac_f32_e32 v79, v29, v29
	v_add_f32_e32 v30, v30, v110
	v_bfe_u32 v68, v30, 16, 1
	v_add3_u32 v30, v30, v68, s77
	v_and_b32_e32 v30, s35, v30
	v_fmac_f32_e32 v79, v30, v30
	v_add_f32_e32 v31, v31, v111
	v_bfe_u32 v68, v31, 16, 1
	v_add3_u32 v31, v31, v68, s77
	v_and_b32_e32 v31, s35, v31
	v_fmac_f32_e32 v79, v31, v31
	v_add_f32_e32 v32, v32, v96
	v_bfe_u32 v68, v32, 16, 1
	v_add3_u32 v32, v32, v68, s77
	v_and_b32_e32 v32, s35, v32
	v_fmac_f32_e32 v76, v32, v32
	v_add_f32_e32 v33, v33, v97
	v_bfe_u32 v68, v33, 16, 1
	v_add3_u32 v33, v33, v68, s77
	v_and_b32_e32 v33, s35, v33
	v_fmac_f32_e32 v76, v33, v33
	v_add_f32_e32 v34, v34, v98
	v_bfe_u32 v68, v34, 16, 1
	v_add3_u32 v34, v34, v68, s77
	v_and_b32_e32 v34, s35, v34
	v_fmac_f32_e32 v76, v34, v34
	v_add_f32_e32 v35, v35, v99
	v_bfe_u32 v68, v35, 16, 1
	v_add3_u32 v35, v35, v68, s77
	v_and_b32_e32 v35, s35, v35
	v_fmac_f32_e32 v76, v35, v35
	v_add_f32_e32 v36, v36, v100
	v_bfe_u32 v68, v36, 16, 1
	v_add3_u32 v36, v36, v68, s77
	v_and_b32_e32 v36, s35, v36
	v_fmac_f32_e32 v76, v36, v36
	v_add_f32_e32 v37, v37, v101
	v_bfe_u32 v68, v37, 16, 1
	v_add3_u32 v37, v37, v68, s77
	v_and_b32_e32 v37, s35, v37
	v_fmac_f32_e32 v76, v37, v37
	v_add_f32_e32 v38, v38, v102
	v_bfe_u32 v68, v38, 16, 1
	v_add3_u32 v38, v38, v68, s77
	v_and_b32_e32 v38, s35, v38
	v_fmac_f32_e32 v76, v38, v38
	v_add_f32_e32 v39, v39, v103
	v_bfe_u32 v68, v39, 16, 1
	v_add3_u32 v39, v39, v68, s77
	v_and_b32_e32 v39, s35, v39
	v_fmac_f32_e32 v76, v39, v39
	v_add_f32_e32 v40, v40, v104
	v_bfe_u32 v68, v40, 16, 1
	v_add3_u32 v40, v40, v68, s77
	v_and_b32_e32 v40, s35, v40
	v_fmac_f32_e32 v80, v40, v40
	v_add_f32_e32 v41, v41, v105
	v_bfe_u32 v68, v41, 16, 1
	v_add3_u32 v41, v41, v68, s77
	v_and_b32_e32 v41, s35, v41
	v_fmac_f32_e32 v80, v41, v41
	v_add_f32_e32 v42, v42, v106
	v_bfe_u32 v68, v42, 16, 1
	v_add3_u32 v42, v42, v68, s77
	v_and_b32_e32 v42, s35, v42
	v_fmac_f32_e32 v80, v42, v42
	v_add_f32_e32 v43, v43, v107
	v_bfe_u32 v68, v43, 16, 1
	v_add3_u32 v43, v43, v68, s77
	v_and_b32_e32 v43, s35, v43
	v_fmac_f32_e32 v80, v43, v43
	v_add_f32_e32 v44, v44, v108
	v_bfe_u32 v68, v44, 16, 1
	v_add3_u32 v44, v44, v68, s77
	v_and_b32_e32 v44, s35, v44
	v_fmac_f32_e32 v80, v44, v44
	v_add_f32_e32 v45, v45, v109
	v_bfe_u32 v68, v45, 16, 1
	v_add3_u32 v45, v45, v68, s77
	v_and_b32_e32 v45, s35, v45
	v_fmac_f32_e32 v80, v45, v45
	v_add_f32_e32 v46, v46, v110
	v_bfe_u32 v68, v46, 16, 1
	v_add3_u32 v46, v46, v68, s77
	v_and_b32_e32 v46, s35, v46
	v_fmac_f32_e32 v80, v46, v46
	v_add_f32_e32 v47, v47, v111
	v_bfe_u32 v68, v47, 16, 1
	v_add3_u32 v47, v47, v68, s77
	v_and_b32_e32 v47, s35, v47
	v_fmac_f32_e32 v80, v47, v47
	v_add_f32_e32 v48, v48, v96
	v_bfe_u32 v68, v48, 16, 1
	v_add3_u32 v48, v48, v68, s77
	v_and_b32_e32 v48, s35, v48
	v_fmac_f32_e32 v77, v48, v48
	v_add_f32_e32 v49, v49, v97
	v_bfe_u32 v68, v49, 16, 1
	v_add3_u32 v49, v49, v68, s77
	v_and_b32_e32 v49, s35, v49
	v_fmac_f32_e32 v77, v49, v49
	v_add_f32_e32 v50, v50, v98
	v_bfe_u32 v68, v50, 16, 1
	v_add3_u32 v50, v50, v68, s77
	v_and_b32_e32 v50, s35, v50
	v_fmac_f32_e32 v77, v50, v50
	v_add_f32_e32 v51, v51, v99
	v_bfe_u32 v68, v51, 16, 1
	v_add3_u32 v51, v51, v68, s77
	v_and_b32_e32 v51, s35, v51
	v_fmac_f32_e32 v77, v51, v51
	v_add_f32_e32 v52, v52, v100
	v_bfe_u32 v68, v52, 16, 1
	v_add3_u32 v52, v52, v68, s77
	v_and_b32_e32 v52, s35, v52
	v_fmac_f32_e32 v77, v52, v52
	v_add_f32_e32 v53, v53, v101
	v_bfe_u32 v68, v53, 16, 1
	v_add3_u32 v53, v53, v68, s77
	v_and_b32_e32 v53, s35, v53
	v_fmac_f32_e32 v77, v53, v53
	v_add_f32_e32 v54, v54, v102
	v_bfe_u32 v68, v54, 16, 1
	v_add3_u32 v54, v54, v68, s77
	v_and_b32_e32 v54, s35, v54
	v_fmac_f32_e32 v77, v54, v54
	v_add_f32_e32 v55, v55, v103
	v_bfe_u32 v68, v55, 16, 1
	v_add3_u32 v55, v55, v68, s77
	v_and_b32_e32 v55, s35, v55
	v_fmac_f32_e32 v77, v55, v55
	v_add_f32_e32 v56, v56, v104
	v_bfe_u32 v68, v56, 16, 1
	v_add3_u32 v56, v56, v68, s77
	v_and_b32_e32 v56, s35, v56
	v_fmac_f32_e32 v81, v56, v56
	v_add_f32_e32 v57, v57, v105
	v_bfe_u32 v68, v57, 16, 1
	v_add3_u32 v57, v57, v68, s77
	v_and_b32_e32 v57, s35, v57
	v_fmac_f32_e32 v81, v57, v57
	v_add_f32_e32 v58, v58, v106
	v_bfe_u32 v68, v58, 16, 1
	v_add3_u32 v58, v58, v68, s77
	v_and_b32_e32 v58, s35, v58
	v_fmac_f32_e32 v81, v58, v58
	v_add_f32_e32 v59, v59, v107
	v_bfe_u32 v68, v59, 16, 1
	v_add3_u32 v59, v59, v68, s77
	v_and_b32_e32 v59, s35, v59
	v_fmac_f32_e32 v81, v59, v59
	v_add_f32_e32 v60, v60, v108
	v_bfe_u32 v68, v60, 16, 1
	v_add3_u32 v60, v60, v68, s77
	v_and_b32_e32 v60, s35, v60
	v_fmac_f32_e32 v81, v60, v60
	v_add_f32_e32 v61, v61, v109
	v_bfe_u32 v68, v61, 16, 1
	v_add3_u32 v61, v61, v68, s77
	v_and_b32_e32 v61, s35, v61
	v_fmac_f32_e32 v81, v61, v61
	v_add_f32_e32 v62, v62, v110
	v_bfe_u32 v68, v62, 16, 1
	v_add3_u32 v62, v62, v68, s77
	v_and_b32_e32 v62, s35, v62
	v_fmac_f32_e32 v81, v62, v62
	v_add_f32_e32 v63, v63, v111
	v_bfe_u32 v68, v63, 16, 1
	v_add3_u32 v63, v63, v68, s77
	v_and_b32_e32 v63, s35, v63
	v_fmac_f32_e32 v81, v63, v63
	ds_bpermute_b32 v86, v215, v74
	ds_bpermute_b32 v87, v215, v75
	ds_bpermute_b32 v88, v215, v76
	ds_bpermute_b32 v89, v215, v77
	ds_bpermute_b32 v90, v215, v78
	ds_bpermute_b32 v91, v215, v79
	ds_bpermute_b32 v92, v215, v80
	ds_bpermute_b32 v93, v215, v81
	s_waitcnt lgkmcnt(0)
	v_add_f32_e32 v74, v74, v86
	v_add_f32_e32 v75, v75, v87
	v_add_f32_e32 v76, v76, v88
	v_add_f32_e32 v77, v77, v89
	v_add_f32_e32 v78, v78, v90
	v_add_f32_e32 v79, v79, v91
	v_add_f32_e32 v80, v80, v92
	v_add_f32_e32 v81, v81, v93
	ds_bpermute_b32 v86, v216, v74
	ds_bpermute_b32 v87, v216, v75
	ds_bpermute_b32 v88, v216, v76
	ds_bpermute_b32 v89, v216, v77
	ds_bpermute_b32 v90, v216, v78
	ds_bpermute_b32 v91, v216, v79
	ds_bpermute_b32 v92, v216, v80
	ds_bpermute_b32 v93, v216, v81
	s_waitcnt lgkmcnt(0)
	v_add_f32_e32 v74, v74, v86
	v_add_f32_e32 v75, v75, v87
	v_add_f32_e32 v76, v76, v88
	v_add_f32_e32 v77, v77, v89
	v_add_f32_e32 v78, v78, v90
	v_add_f32_e32 v79, v79, v91
	v_add_f32_e32 v80, v80, v92
	v_add_f32_e32 v81, v81, v93
	ds_write_b32 v82, v74 offset:0
	ds_write_b32 v82, v75 offset:512
	ds_write_b32 v82, v76 offset:1024
	ds_write_b32 v82, v77 offset:1536
	ds_write_b32 v82, v78 offset:2048
	ds_write_b32 v82, v79 offset:2560
	ds_write_b32 v82, v80 offset:3072
	ds_write_b32 v82, v81 offset:3584
	s_waitcnt lgkmcnt(0)
	s_barrier
	ds_read_b128 v[86:89], v83 offset:0
	ds_read_b128 v[90:93], v83 offset:16
	s_waitcnt lgkmcnt(0)
	v_add_f32_e32 v86, v86, v90
	v_add_f32_e32 v87, v87, v91
	v_add_f32_e32 v88, v88, v92
	v_add_f32_e32 v89, v89, v93
	v_add_f32_e32 v86, v86, v87
	v_add_f32_e32 v88, v88, v89
	v_add_f32_e32 v74, v86, v88
	ds_read_b128 v[86:89], v83 offset:512
	ds_read_b128 v[90:93], v83 offset:528
	s_waitcnt lgkmcnt(0)
	v_add_f32_e32 v86, v86, v90
	v_add_f32_e32 v87, v87, v91
	v_add_f32_e32 v88, v88, v92
	v_add_f32_e32 v89, v89, v93
	v_add_f32_e32 v86, v86, v87
	v_add_f32_e32 v88, v88, v89
	v_add_f32_e32 v75, v86, v88
	ds_read_b128 v[86:89], v83 offset:1024
	ds_read_b128 v[90:93], v83 offset:1040
	s_waitcnt lgkmcnt(0)
	v_add_f32_e32 v86, v86, v90
	v_add_f32_e32 v87, v87, v91
	v_add_f32_e32 v88, v88, v92
	v_add_f32_e32 v89, v89, v93
	v_add_f32_e32 v86, v86, v87
	v_add_f32_e32 v88, v88, v89
	v_add_f32_e32 v76, v86, v88
	ds_read_b128 v[86:89], v83 offset:1536
	ds_read_b128 v[90:93], v83 offset:1552
	s_waitcnt lgkmcnt(0)
	v_add_f32_e32 v86, v86, v90
	v_add_f32_e32 v87, v87, v91
	v_add_f32_e32 v88, v88, v92
	v_add_f32_e32 v89, v89, v93
	v_add_f32_e32 v86, v86, v87
	v_add_f32_e32 v88, v88, v89
	v_add_f32_e32 v77, v86, v88
	ds_read_b128 v[86:89], v83 offset:2048
	ds_read_b128 v[90:93], v83 offset:2064
	s_waitcnt lgkmcnt(0)
	v_add_f32_e32 v86, v86, v90
	v_add_f32_e32 v87, v87, v91
	v_add_f32_e32 v88, v88, v92
	v_add_f32_e32 v89, v89, v93
	v_add_f32_e32 v86, v86, v87
	v_add_f32_e32 v88, v88, v89
	v_add_f32_e32 v78, v86, v88
	ds_read_b128 v[86:89], v83 offset:2560
	ds_read_b128 v[90:93], v83 offset:2576
	s_waitcnt lgkmcnt(0)
	v_add_f32_e32 v86, v86, v90
	v_add_f32_e32 v87, v87, v91
	v_add_f32_e32 v88, v88, v92
	v_add_f32_e32 v89, v89, v93
	v_add_f32_e32 v86, v86, v87
	v_add_f32_e32 v88, v88, v89
	v_add_f32_e32 v79, v86, v88
	ds_read_b128 v[86:89], v83 offset:3072
	ds_read_b128 v[90:93], v83 offset:3088
	s_waitcnt lgkmcnt(0)
	v_add_f32_e32 v86, v86, v90
	v_add_f32_e32 v87, v87, v91
	v_add_f32_e32 v88, v88, v92
	v_add_f32_e32 v89, v89, v93
	v_add_f32_e32 v86, v86, v87
	v_add_f32_e32 v88, v88, v89
	v_add_f32_e32 v80, v86, v88
	ds_read_b128 v[86:89], v83 offset:3584
	ds_read_b128 v[90:93], v83 offset:3600
	s_waitcnt lgkmcnt(0)
	v_add_f32_e32 v86, v86, v90
	v_add_f32_e32 v87, v87, v91
	v_add_f32_e32 v88, v88, v92
	v_add_f32_e32 v89, v89, v93
	v_add_f32_e32 v86, v86, v87
	v_add_f32_e32 v88, v88, v89
	v_add_f32_e32 v81, v86, v88
	v_fmamk_f32 v74, v74, 0x3b800000, v197
	v_fmamk_f32 v75, v75, 0x3b800000, v197
	v_fmamk_f32 v76, v76, 0x3b800000, v197
	v_fmamk_f32 v77, v77, 0x3b800000, v197
	v_fmamk_f32 v78, v78, 0x3b800000, v197
	v_fmamk_f32 v79, v79, 0x3b800000, v197
	v_fmamk_f32 v80, v80, 0x3b800000, v197
	v_fmamk_f32 v81, v81, 0x3b800000, v197
	v_rsq_f32_e32 v74, v74
	v_rsq_f32_e32 v75, v75
	v_rsq_f32_e32 v76, v76
	v_rsq_f32_e32 v77, v77
	v_rsq_f32_e32 v78, v78
	v_rsq_f32_e32 v79, v79
	v_rsq_f32_e32 v80, v80
	v_rsq_f32_e32 v81, v81
	s_nop 0
	s_lshl_b32 s1, s16, 11
	s_add_u32 s1, s1, 0x3c00000
	s_add_u32 s14, s4, s1
	s_addc_u32 s15, s5, 0
	v_mul_f32_e32 v0, v74, v0
	v_mul_f32_e32 v1, v74, v1
	v_mul_f32_e32 v2, v74, v2
	v_mul_f32_e32 v3, v74, v3
	v_mul_f32_e32 v0, v112, v0
	v_mul_f32_e32 v1, v113, v1
	v_mul_f32_e32 v2, v114, v2
	v_mul_f32_e32 v3, v115, v3
	v_cvt_pk_bf16_f32 v0, v0, v1
	v_cvt_pk_bf16_f32 v1, v2, v3
	global_store_dwordx2 v213, v[0:1], s[14:15] offset:-1536
	v_mul_f32_e32 v4, v74, v4
	v_mul_f32_e32 v5, v74, v5
	v_mul_f32_e32 v6, v74, v6
	v_mul_f32_e32 v7, v74, v7
	v_mul_f32_e32 v4, v116, v4
	v_mul_f32_e32 v5, v117, v5
	v_mul_f32_e32 v6, v118, v6
	v_mul_f32_e32 v7, v119, v7
	v_cvt_pk_bf16_f32 v4, v4, v5
	v_cvt_pk_bf16_f32 v5, v6, v7
	global_store_dwordx2 v213, v[4:5], s[14:15] offset:-1504
	v_mul_f32_e32 v8, v78, v8
	v_mul_f32_e32 v9, v78, v9
	v_mul_f32_e32 v10, v78, v10
	v_mul_f32_e32 v11, v78, v11
	v_mul_f32_e32 v8, v120, v8
	v_mul_f32_e32 v9, v121, v9
	v_mul_f32_e32 v10, v122, v10
	v_mul_f32_e32 v11, v123, v11
	v_cvt_pk_bf16_f32 v8, v8, v9
	v_cvt_pk_bf16_f32 v9, v10, v11
	global_store_dwordx2 v213, v[8:9], s[14:15] offset:-1024
	v_mul_f32_e32 v12, v78, v12
	v_mul_f32_e32 v13, v78, v13
	v_mul_f32_e32 v14, v78, v14
	v_mul_f32_e32 v15, v78, v15
	v_mul_f32_e32 v12, v124, v12
	v_mul_f32_e32 v13, v125, v13
	v_mul_f32_e32 v14, v126, v14
	v_mul_f32_e32 v15, v127, v15
	v_cvt_pk_bf16_f32 v12, v12, v13
	v_cvt_pk_bf16_f32 v13, v14, v15
	global_store_dwordx2 v213, v[12:13], s[14:15] offset:-992
	s_add_u32 s14, s14, 0x8000
	s_addc_u32 s15, s15, 0
	v_mul_f32_e32 v16, v75, v16
	v_mul_f32_e32 v17, v75, v17
	v_mul_f32_e32 v18, v75, v18
	v_mul_f32_e32 v19, v75, v19
	v_mul_f32_e32 v16, v112, v16
	v_mul_f32_e32 v17, v113, v17
	v_mul_f32_e32 v18, v114, v18
	v_mul_f32_e32 v19, v115, v19
	v_cvt_pk_bf16_f32 v16, v16, v17
	v_cvt_pk_bf16_f32 v17, v18, v19
	global_store_dwordx2 v213, v[16:17], s[14:15] offset:-1536
	v_mul_f32_e32 v20, v75, v20
	v_mul_f32_e32 v21, v75, v21
	v_mul_f32_e32 v22, v75, v22
	v_mul_f32_e32 v23, v75, v23
	v_mul_f32_e32 v20, v116, v20
	v_mul_f32_e32 v21, v117, v21
	v_mul_f32_e32 v22, v118, v22
	v_mul_f32_e32 v23, v119, v23
	v_cvt_pk_bf16_f32 v20, v20, v21
	v_cvt_pk_bf16_f32 v21, v22, v23
	global_store_dwordx2 v213, v[20:21], s[14:15] offset:-1504
	v_mul_f32_e32 v24, v79, v24
	v_mul_f32_e32 v25, v79, v25
	v_mul_f32_e32 v26, v79, v26
	v_mul_f32_e32 v27, v79, v27
	v_mul_f32_e32 v24, v120, v24
	v_mul_f32_e32 v25, v121, v25
	v_mul_f32_e32 v26, v122, v26
	v_mul_f32_e32 v27, v123, v27
	v_cvt_pk_bf16_f32 v24, v24, v25
	v_cvt_pk_bf16_f32 v25, v26, v27
	global_store_dwordx2 v213, v[24:25], s[14:15] offset:-1024
	v_mul_f32_e32 v28, v79, v28
	v_mul_f32_e32 v29, v79, v29
	v_mul_f32_e32 v30, v79, v30
	v_mul_f32_e32 v31, v79, v31
	v_mul_f32_e32 v28, v124, v28
	v_mul_f32_e32 v29, v125, v29
	v_mul_f32_e32 v30, v126, v30
	v_mul_f32_e32 v31, v127, v31
	v_cvt_pk_bf16_f32 v28, v28, v29
	v_cvt_pk_bf16_f32 v29, v30, v31
	global_store_dwordx2 v213, v[28:29], s[14:15] offset:-992
	s_add_u32 s14, s14, 0x8000
	s_addc_u32 s15, s15, 0
	v_mul_f32_e32 v32, v76, v32
	v_mul_f32_e32 v33, v76, v33
	v_mul_f32_e32 v34, v76, v34
	v_mul_f32_e32 v35, v76, v35
	v_mul_f32_e32 v32, v112, v32
	v_mul_f32_e32 v33, v113, v33
	v_mul_f32_e32 v34, v114, v34
	v_mul_f32_e32 v35, v115, v35
	v_cvt_pk_bf16_f32 v32, v32, v33
	v_cvt_pk_bf16_f32 v33, v34, v35
	global_store_dwordx2 v213, v[32:33], s[14:15] offset:-1536
	v_mul_f32_e32 v36, v76, v36
	v_mul_f32_e32 v37, v76, v37
	v_mul_f32_e32 v38, v76, v38
	v_mul_f32_e32 v39, v76, v39
	v_mul_f32_e32 v36, v116, v36
	v_mul_f32_e32 v37, v117, v37
	v_mul_f32_e32 v38, v118, v38
	v_mul_f32_e32 v39, v119, v39
	v_cvt_pk_bf16_f32 v36, v36, v37
	v_cvt_pk_bf16_f32 v37, v38, v39
	global_store_dwordx2 v213, v[36:37], s[14:15] offset:-1504
	v_mul_f32_e32 v40, v80, v40
	v_mul_f32_e32 v41, v80, v41
	v_mul_f32_e32 v42, v80, v42
	v_mul_f32_e32 v43, v80, v43
	v_mul_f32_e32 v40, v120, v40
	v_mul_f32_e32 v41, v121, v41
	v_mul_f32_e32 v42, v122, v42
	v_mul_f32_e32 v43, v123, v43
	v_cvt_pk_bf16_f32 v40, v40, v41
	v_cvt_pk_bf16_f32 v41, v42, v43
	global_store_dwordx2 v213, v[40:41], s[14:15] offset:-1024
	v_mul_f32_e32 v44, v80, v44
	v_mul_f32_e32 v45, v80, v45
	v_mul_f32_e32 v46, v80, v46
	v_mul_f32_e32 v47, v80, v47
	v_mul_f32_e32 v44, v124, v44
	v_mul_f32_e32 v45, v125, v45
	v_mul_f32_e32 v46, v126, v46
	v_mul_f32_e32 v47, v127, v47
	v_cvt_pk_bf16_f32 v44, v44, v45
	v_cvt_pk_bf16_f32 v45, v46, v47
	global_store_dwordx2 v213, v[44:45], s[14:15] offset:-992
	s_add_u32 s14, s14, 0x8000
	s_addc_u32 s15, s15, 0
	v_mul_f32_e32 v48, v77, v48
	v_mul_f32_e32 v49, v77, v49
	v_mul_f32_e32 v50, v77, v50
	v_mul_f32_e32 v51, v77, v51
	v_mul_f32_e32 v48, v112, v48
	v_mul_f32_e32 v49, v113, v49
	v_mul_f32_e32 v50, v114, v50
	v_mul_f32_e32 v51, v115, v51
	v_cvt_pk_bf16_f32 v48, v48, v49
	v_cvt_pk_bf16_f32 v49, v50, v51
	global_store_dwordx2 v213, v[48:49], s[14:15] offset:-1536
	v_mul_f32_e32 v52, v77, v52
	v_mul_f32_e32 v53, v77, v53
	v_mul_f32_e32 v54, v77, v54
	v_mul_f32_e32 v55, v77, v55
	v_mul_f32_e32 v52, v116, v52
	v_mul_f32_e32 v53, v117, v53
	v_mul_f32_e32 v54, v118, v54
	v_mul_f32_e32 v55, v119, v55
	v_cvt_pk_bf16_f32 v52, v52, v53
	v_cvt_pk_bf16_f32 v53, v54, v55
	global_store_dwordx2 v213, v[52:53], s[14:15] offset:-1504
	v_mul_f32_e32 v56, v81, v56
	v_mul_f32_e32 v57, v81, v57
	v_mul_f32_e32 v58, v81, v58
	v_mul_f32_e32 v59, v81, v59
	v_mul_f32_e32 v56, v120, v56
	v_mul_f32_e32 v57, v121, v57
	v_mul_f32_e32 v58, v122, v58
	v_mul_f32_e32 v59, v123, v59
	v_cvt_pk_bf16_f32 v56, v56, v57
	v_cvt_pk_bf16_f32 v57, v58, v59
	global_store_dwordx2 v213, v[56:57], s[14:15] offset:-1024
	v_mul_f32_e32 v60, v81, v60
	v_mul_f32_e32 v61, v81, v61
	v_mul_f32_e32 v62, v81, v62
	v_mul_f32_e32 v63, v81, v63
	v_mul_f32_e32 v60, v124, v60
	v_mul_f32_e32 v61, v125, v61
	v_mul_f32_e32 v62, v126, v62
	v_mul_f32_e32 v63, v127, v63
	v_cvt_pk_bf16_f32 v60, v60, v61
	v_cvt_pk_bf16_f32 v61, v62, v63
	global_store_dwordx2 v213, v[60:61], s[14:15] offset:-992
	s_waitcnt vmcnt(23)
	v_lshlrev_b32_e32 v68, 16, v170
	v_and_b32_e32 v69, 0xffff0000, v170
	v_lshlrev_b32_e32 v70, 16, v171
	v_and_b32_e32 v71, 0xffff0000, v171
	v_pk_mul_f32 v[76:77], v[68:69], v[68:69]
	v_pk_fma_f32 v[76:77], v[70:71], v[70:71], v[76:77]
	v_add_f32_e32 v72, v76, v77
	s_nop 1
	v_add_f32_dpp v72, v72, v72 row_ror:8 row_mask:0xf bank_mask:0xf
	s_nop 1
	v_add_f32_dpp v72, v72, v72 row_ror:4 row_mask:0xf bank_mask:0xf
	s_nop 1
	v_add_f32_dpp v72, v72, v72 row_ror:2 row_mask:0xf bank_mask:0xf
	s_nop 1
	v_add_f32_dpp v72, v72, v72 row_ror:1 row_mask:0xf bank_mask:0xf
	s_nop 1
	s_nop 0
	v_readlane_b32 s0, v72, 0
	v_readlane_b32 s1, v72, 16
	v_readlane_b32 s6, v72, 32
	v_readlane_b32 s7, v72, 48
	s_nop 1
	v_mov_b32_e32 v74, s0
	v_add_f32_e32 v74, s1, v74
	v_add_f32_e32 v74, s6, v74
	v_add_f32_e32 v74, s7, v74
	v_fmamk_f32 v74, v74, 0x3b800000, v197
	v_rsq_f32_e32 v74, v74
	s_nop 0
	v_pk_mul_f32 v[68:69], v[74:75], v[68:69] op_sel_hi:[0,1]
	v_pk_mul_f32 v[70:71], v[74:75], v[70:71] op_sel_hi:[0,1]
	v_pk_mul_f32 v[68:69], v[64:65], v[68:69]
	v_pk_mul_f32 v[70:71], v[66:67], v[70:71]
	v_cvt_pk_bf16_f32 v170, v68, v69
	v_cvt_pk_bf16_f32 v171, v70, v71
	global_store_dwordx2 v208, v[170:171], s[12:13] offset:1024
	s_add_u32 s12, s12, 0x800
	s_addc_u32 s13, s13, 0
	s_waitcnt vmcnt(23)
	v_lshlrev_b32_e32 v68, 16, v172
	v_and_b32_e32 v69, 0xffff0000, v172
	v_lshlrev_b32_e32 v70, 16, v173
	v_and_b32_e32 v71, 0xffff0000, v173
	v_pk_mul_f32 v[76:77], v[68:69], v[68:69]
	v_pk_fma_f32 v[76:77], v[70:71], v[70:71], v[76:77]
	v_add_f32_e32 v72, v76, v77
	s_nop 1
	v_add_f32_dpp v72, v72, v72 row_ror:8 row_mask:0xf bank_mask:0xf
	s_nop 1
	v_add_f32_dpp v72, v72, v72 row_ror:4 row_mask:0xf bank_mask:0xf
	s_nop 1
	v_add_f32_dpp v72, v72, v72 row_ror:2 row_mask:0xf bank_mask:0xf
	s_nop 1
	v_add_f32_dpp v72, v72, v72 row_ror:1 row_mask:0xf bank_mask:0xf
	s_nop 1
	s_nop 0
	v_readlane_b32 s0, v72, 0
	v_readlane_b32 s1, v72, 16
	v_readlane_b32 s6, v72, 32
	v_readlane_b32 s7, v72, 48
	s_nop 1
	v_mov_b32_e32 v74, s0
	v_add_f32_e32 v74, s1, v74
	v_add_f32_e32 v74, s6, v74
	v_add_f32_e32 v74, s7, v74
	v_fmamk_f32 v74, v74, 0x3b800000, v197
	v_rsq_f32_e32 v74, v74
	s_nop 0
	v_pk_mul_f32 v[68:69], v[74:75], v[68:69] op_sel_hi:[0,1]
	v_pk_mul_f32 v[70:71], v[74:75], v[70:71] op_sel_hi:[0,1]
	v_pk_mul_f32 v[68:69], v[64:65], v[68:69]
	v_pk_mul_f32 v[70:71], v[66:67], v[70:71]
	v_cvt_pk_bf16_f32 v172, v68, v69
	v_cvt_pk_bf16_f32 v173, v70, v71
	global_store_dwordx2 v208, v[172:173], s[12:13] offset:1024
	s_add_u32 s12, s12, 0x800
	s_addc_u32 s13, s13, 0
	s_waitcnt vmcnt(23)
	v_lshlrev_b32_e32 v68, 16, v174
	v_and_b32_e32 v69, 0xffff0000, v174
	v_lshlrev_b32_e32 v70, 16, v175
	v_and_b32_e32 v71, 0xffff0000, v175
	v_pk_mul_f32 v[76:77], v[68:69], v[68:69]
	v_pk_fma_f32 v[76:77], v[70:71], v[70:71], v[76:77]
	v_add_f32_e32 v72, v76, v77
	s_nop 1
	v_add_f32_dpp v72, v72, v72 row_ror:8 row_mask:0xf bank_mask:0xf
	s_nop 1
	v_add_f32_dpp v72, v72, v72 row_ror:4 row_mask:0xf bank_mask:0xf
	s_nop 1
	v_add_f32_dpp v72, v72, v72 row_ror:2 row_mask:0xf bank_mask:0xf
	s_nop 1
	v_add_f32_dpp v72, v72, v72 row_ror:1 row_mask:0xf bank_mask:0xf
	s_nop 1
	s_nop 0
	v_readlane_b32 s0, v72, 0
	v_readlane_b32 s1, v72, 16
	v_readlane_b32 s6, v72, 32
	v_readlane_b32 s7, v72, 48
	s_nop 1
	v_mov_b32_e32 v74, s0
	v_add_f32_e32 v74, s1, v74
	v_add_f32_e32 v74, s6, v74
	v_add_f32_e32 v74, s7, v74
	v_fmamk_f32 v74, v74, 0x3b800000, v197
	v_rsq_f32_e32 v74, v74
	s_nop 0
	v_pk_mul_f32 v[68:69], v[74:75], v[68:69] op_sel_hi:[0,1]
	v_pk_mul_f32 v[70:71], v[74:75], v[70:71] op_sel_hi:[0,1]
	v_pk_mul_f32 v[68:69], v[64:65], v[68:69]
	v_pk_mul_f32 v[70:71], v[66:67], v[70:71]
	v_cvt_pk_bf16_f32 v174, v68, v69
	v_cvt_pk_bf16_f32 v175, v70, v71
	global_store_dwordx2 v208, v[174:175], s[12:13] offset:1024
	s_add_u32 s12, s12, 0x800
	s_addc_u32 s13, s13, 0
	s_waitcnt vmcnt(23)
	v_lshlrev_b32_e32 v68, 16, v176
	v_and_b32_e32 v69, 0xffff0000, v176
	v_lshlrev_b32_e32 v70, 16, v177
	v_and_b32_e32 v71, 0xffff0000, v177
	v_pk_mul_f32 v[76:77], v[68:69], v[68:69]
	v_pk_fma_f32 v[76:77], v[70:71], v[70:71], v[76:77]
	v_add_f32_e32 v72, v76, v77
	s_nop 1
	v_add_f32_dpp v72, v72, v72 row_ror:8 row_mask:0xf bank_mask:0xf
	s_nop 1
	v_add_f32_dpp v72, v72, v72 row_ror:4 row_mask:0xf bank_mask:0xf
	s_nop 1
	v_add_f32_dpp v72, v72, v72 row_ror:2 row_mask:0xf bank_mask:0xf
	s_nop 1
	v_add_f32_dpp v72, v72, v72 row_ror:1 row_mask:0xf bank_mask:0xf
	s_nop 1
	s_nop 0
	v_readlane_b32 s0, v72, 0
	v_readlane_b32 s1, v72, 16
	v_readlane_b32 s6, v72, 32
	v_readlane_b32 s7, v72, 48
	s_nop 1
	v_mov_b32_e32 v74, s0
	v_add_f32_e32 v74, s1, v74
	v_add_f32_e32 v74, s6, v74
	v_add_f32_e32 v74, s7, v74
	v_fmamk_f32 v74, v74, 0x3b800000, v197
	v_rsq_f32_e32 v74, v74
	s_nop 0
	v_pk_mul_f32 v[68:69], v[74:75], v[68:69] op_sel_hi:[0,1]
	v_pk_mul_f32 v[70:71], v[74:75], v[70:71] op_sel_hi:[0,1]
	v_pk_mul_f32 v[68:69], v[64:65], v[68:69]
	v_pk_mul_f32 v[70:71], v[66:67], v[70:71]
	v_cvt_pk_bf16_f32 v176, v68, v69
	v_cvt_pk_bf16_f32 v177, v70, v71
	global_store_dwordx2 v208, v[176:177], s[12:13] offset:1024
	s_add_u32 s12, s12, 0x800
	s_addc_u32 s13, s13, 0
	s_waitcnt vmcnt(23)
	v_lshlrev_b32_e32 v68, 16, v178
	v_and_b32_e32 v69, 0xffff0000, v178
	v_lshlrev_b32_e32 v70, 16, v179
	v_and_b32_e32 v71, 0xffff0000, v179
	v_pk_mul_f32 v[76:77], v[68:69], v[68:69]
	v_pk_fma_f32 v[76:77], v[70:71], v[70:71], v[76:77]
	v_add_f32_e32 v72, v76, v77
	s_nop 1
	v_add_f32_dpp v72, v72, v72 row_ror:8 row_mask:0xf bank_mask:0xf
	s_nop 1
	v_add_f32_dpp v72, v72, v72 row_ror:4 row_mask:0xf bank_mask:0xf
	s_nop 1
	v_add_f32_dpp v72, v72, v72 row_ror:2 row_mask:0xf bank_mask:0xf
	s_nop 1
	v_add_f32_dpp v72, v72, v72 row_ror:1 row_mask:0xf bank_mask:0xf
	s_nop 1
	s_nop 0
	v_readlane_b32 s0, v72, 0
	v_readlane_b32 s1, v72, 16
	v_readlane_b32 s6, v72, 32
	v_readlane_b32 s7, v72, 48
	s_nop 1
	v_mov_b32_e32 v74, s0
	v_add_f32_e32 v74, s1, v74
	v_add_f32_e32 v74, s6, v74
	v_add_f32_e32 v74, s7, v74
	v_fmamk_f32 v74, v74, 0x3b800000, v197
	v_rsq_f32_e32 v74, v74
	s_nop 0
	v_pk_mul_f32 v[68:69], v[74:75], v[68:69] op_sel_hi:[0,1]
	v_pk_mul_f32 v[70:71], v[74:75], v[70:71] op_sel_hi:[0,1]
	v_pk_mul_f32 v[68:69], v[64:65], v[68:69]
	v_pk_mul_f32 v[70:71], v[66:67], v[70:71]
	v_cvt_pk_bf16_f32 v178, v68, v69
	v_cvt_pk_bf16_f32 v179, v70, v71
	global_store_dwordx2 v208, v[178:179], s[12:13] offset:1024
	s_add_u32 s12, s12, 0x800
	s_addc_u32 s13, s13, 0
	s_waitcnt vmcnt(23)
	v_lshlrev_b32_e32 v68, 16, v180
	v_and_b32_e32 v69, 0xffff0000, v180
	v_lshlrev_b32_e32 v70, 16, v181
	v_and_b32_e32 v71, 0xffff0000, v181
	v_pk_mul_f32 v[76:77], v[68:69], v[68:69]
	v_pk_fma_f32 v[76:77], v[70:71], v[70:71], v[76:77]
	v_add_f32_e32 v72, v76, v77
	s_nop 1
	v_add_f32_dpp v72, v72, v72 row_ror:8 row_mask:0xf bank_mask:0xf
	s_nop 1
	v_add_f32_dpp v72, v72, v72 row_ror:4 row_mask:0xf bank_mask:0xf
	s_nop 1
	v_add_f32_dpp v72, v72, v72 row_ror:2 row_mask:0xf bank_mask:0xf
	s_nop 1
	v_add_f32_dpp v72, v72, v72 row_ror:1 row_mask:0xf bank_mask:0xf
	s_nop 1
	s_nop 0
	v_readlane_b32 s0, v72, 0
	v_readlane_b32 s1, v72, 16
	v_readlane_b32 s6, v72, 32
	v_readlane_b32 s7, v72, 48
	s_nop 1
	v_mov_b32_e32 v74, s0
	v_add_f32_e32 v74, s1, v74
	v_add_f32_e32 v74, s6, v74
	v_add_f32_e32 v74, s7, v74
	v_fmamk_f32 v74, v74, 0x3b800000, v197
	v_rsq_f32_e32 v74, v74
	s_nop 0
	v_pk_mul_f32 v[68:69], v[74:75], v[68:69] op_sel_hi:[0,1]
	v_pk_mul_f32 v[70:71], v[74:75], v[70:71] op_sel_hi:[0,1]
	v_pk_mul_f32 v[68:69], v[64:65], v[68:69]
	v_pk_mul_f32 v[70:71], v[66:67], v[70:71]
	v_cvt_pk_bf16_f32 v180, v68, v69
	v_cvt_pk_bf16_f32 v181, v70, v71
	global_store_dwordx2 v208, v[180:181], s[12:13] offset:1024
	s_add_u32 s12, s12, 0x800
	s_addc_u32 s13, s13, 0
	s_waitcnt vmcnt(23)
	v_lshlrev_b32_e32 v68, 16, v182
	v_and_b32_e32 v69, 0xffff0000, v182
	v_lshlrev_b32_e32 v70, 16, v183
	v_and_b32_e32 v71, 0xffff0000, v183
	v_pk_mul_f32 v[76:77], v[68:69], v[68:69]
	v_pk_fma_f32 v[76:77], v[70:71], v[70:71], v[76:77]
	v_add_f32_e32 v72, v76, v77
	s_nop 1
	v_add_f32_dpp v72, v72, v72 row_ror:8 row_mask:0xf bank_mask:0xf
	s_nop 1
	v_add_f32_dpp v72, v72, v72 row_ror:4 row_mask:0xf bank_mask:0xf
	s_nop 1
	v_add_f32_dpp v72, v72, v72 row_ror:2 row_mask:0xf bank_mask:0xf
	s_nop 1
	v_add_f32_dpp v72, v72, v72 row_ror:1 row_mask:0xf bank_mask:0xf
	s_nop 1
	s_nop 0
	v_readlane_b32 s0, v72, 0
	v_readlane_b32 s1, v72, 16
	v_readlane_b32 s6, v72, 32
	v_readlane_b32 s7, v72, 48
	s_nop 1
	v_mov_b32_e32 v74, s0
	v_add_f32_e32 v74, s1, v74
	v_add_f32_e32 v74, s6, v74
	v_add_f32_e32 v74, s7, v74
	v_fmamk_f32 v74, v74, 0x3b800000, v197
	v_rsq_f32_e32 v74, v74
	s_nop 0
	v_pk_mul_f32 v[68:69], v[74:75], v[68:69] op_sel_hi:[0,1]
	v_pk_mul_f32 v[70:71], v[74:75], v[70:71] op_sel_hi:[0,1]
	v_pk_mul_f32 v[68:69], v[64:65], v[68:69]
	v_pk_mul_f32 v[70:71], v[66:67], v[70:71]
	v_cvt_pk_bf16_f32 v182, v68, v69
	v_cvt_pk_bf16_f32 v183, v70, v71
	global_store_dwordx2 v208, v[182:183], s[12:13] offset:1024
	s_add_u32 s12, s12, 0x800
	s_addc_u32 s13, s13, 0
	s_waitcnt vmcnt(23)
	v_lshlrev_b32_e32 v68, 16, v184
	v_and_b32_e32 v69, 0xffff0000, v184
	v_lshlrev_b32_e32 v70, 16, v185
	v_and_b32_e32 v71, 0xffff0000, v185
	v_pk_mul_f32 v[76:77], v[68:69], v[68:69]
	v_pk_fma_f32 v[76:77], v[70:71], v[70:71], v[76:77]
	v_add_f32_e32 v72, v76, v77
	s_nop 1
	v_add_f32_dpp v72, v72, v72 row_ror:8 row_mask:0xf bank_mask:0xf
	s_nop 1
	v_add_f32_dpp v72, v72, v72 row_ror:4 row_mask:0xf bank_mask:0xf
	s_nop 1
	v_add_f32_dpp v72, v72, v72 row_ror:2 row_mask:0xf bank_mask:0xf
	s_nop 1
	v_add_f32_dpp v72, v72, v72 row_ror:1 row_mask:0xf bank_mask:0xf
	s_nop 1
	s_nop 0
	v_readlane_b32 s0, v72, 0
	v_readlane_b32 s1, v72, 16
	v_readlane_b32 s6, v72, 32
	v_readlane_b32 s7, v72, 48
	s_nop 1
	v_mov_b32_e32 v74, s0
	v_add_f32_e32 v74, s1, v74
	v_add_f32_e32 v74, s6, v74
	v_add_f32_e32 v74, s7, v74
	v_fmamk_f32 v74, v74, 0x3b800000, v197
	v_rsq_f32_e32 v74, v74
	s_nop 0
	v_pk_mul_f32 v[68:69], v[74:75], v[68:69] op_sel_hi:[0,1]
	v_pk_mul_f32 v[70:71], v[74:75], v[70:71] op_sel_hi:[0,1]
	v_pk_mul_f32 v[68:69], v[64:65], v[68:69]
	v_pk_mul_f32 v[70:71], v[66:67], v[70:71]
	v_cvt_pk_bf16_f32 v184, v68, v69
	v_cvt_pk_bf16_f32 v185, v70, v71
	global_store_dwordx2 v208, v[184:185], s[12:13] offset:1024
	s_cmp_eq_u32 s17, 0
	s_cselect_b32 s0, 1, 0
	s_cmp_eq_u32 s27, 0
	s_cselect_b32 s0, s0, 0
	s_cmp_lt_u32 s69, 16
	s_cselect_b32 s0, s0, 0
	s_cmp_eq_u32 s0, 1
	s_cbranch_scc0 .Lgg_end
	s_mov_b32 s17, 1
	s_lshl_b32 s16, s69, 6
	s_barrier
	s_branch .Lgg_blk
